# gather_v: each ring slot is reloaded right after it is consumed (constant vmcnt(32)) instead of four slots per batch
# speedup vs baseline: 1.0057x; 1.0057x over previous
.Lgv0_chunk:
	s_movk_i32 s100, 0xc0
	s_lshl_b32 s16, s92, 14
	s_add_u32 s12, s26, 0xd800000
	s_addc_u32 s13, s27, 0
	s_lshl_b32 s15, s101, 9
	s_add_u32 s12, s12, s15
	s_addc_u32 s13, s13, 0
	s_lshl_b32 s18, s92, 11
	global_load_dword v64, v196, s[12:13]
	global_load_dword v65, v196, s[12:13] offset:256
	s_add_u32 s12, s12, s18
	s_addc_u32 s13, s13, 0
	global_load_dword v66, v196, s[12:13]
	global_load_dword v67, v196, s[12:13] offset:256
	s_add_u32 s12, s12, s18
	s_addc_u32 s13, s13, 0
	global_load_dword v68, v196, s[12:13]
	global_load_dword v69, v196, s[12:13] offset:256
	s_add_u32 s12, s12, s18
	s_addc_u32 s13, s13, 0
	global_load_dword v70, v196, s[12:13]
	global_load_dword v71, v196, s[12:13] offset:256
	s_add_u32 s12, s12, s18
	s_addc_u32 s13, s13, 0
	global_load_dword v72, v196, s[12:13]
	global_load_dword v73, v196, s[12:13] offset:256
	s_add_u32 s12, s12, s18
	s_addc_u32 s13, s13, 0
	global_load_dword v74, v196, s[12:13]
	global_load_dword v75, v196, s[12:13] offset:256
	s_add_u32 s12, s12, s18
	s_addc_u32 s13, s13, 0
	global_load_dword v76, v196, s[12:13]
	global_load_dword v77, v196, s[12:13] offset:256
	s_add_u32 s12, s12, s18
	s_addc_u32 s13, s13, 0
	global_load_dword v78, v196, s[12:13]
	global_load_dword v79, v196, s[12:13] offset:256
	s_add_u32 s12, s12, s18
	s_addc_u32 s13, s13, 0
	global_load_dword v80, v196, s[12:13]
	global_load_dword v81, v196, s[12:13] offset:256
	s_add_u32 s12, s12, s18
	s_addc_u32 s13, s13, 0
	global_load_dword v82, v196, s[12:13]
	global_load_dword v83, v196, s[12:13] offset:256
	s_add_u32 s12, s12, s18
	s_addc_u32 s13, s13, 0
	global_load_dword v84, v196, s[12:13]
	global_load_dword v85, v196, s[12:13] offset:256
	s_add_u32 s12, s12, s18
	s_addc_u32 s13, s13, 0
	global_load_dword v86, v196, s[12:13]
	global_load_dword v87, v196, s[12:13] offset:256
	s_add_u32 s12, s12, s18
	s_addc_u32 s13, s13, 0
	global_load_dword v88, v196, s[12:13]
	global_load_dword v89, v196, s[12:13] offset:256
	s_add_u32 s12, s12, s18
	s_addc_u32 s13, s13, 0
	global_load_dword v90, v196, s[12:13]
	global_load_dword v91, v196, s[12:13] offset:256
	s_add_u32 s12, s12, s18
	s_addc_u32 s13, s13, 0
	global_load_dword v92, v196, s[12:13]
	global_load_dword v93, v196, s[12:13] offset:256
	s_add_u32 s12, s12, s18
	s_addc_u32 s13, s13, 0
	global_load_dword v94, v196, s[12:13]
	global_load_dword v95, v196, s[12:13] offset:256
	s_add_u32 s12, s12, s18
	s_addc_u32 s13, s13, 0
	s_waitcnt vmcnt(0)
	ds_write2st64_b32 v206, v64, v65 offset0:0 offset1:1
	ds_write2st64_b32 v206, v66, v67 offset0:2 offset1:3
	ds_write2st64_b32 v206, v68, v69 offset0:4 offset1:5
	ds_write2st64_b32 v206, v70, v71 offset0:6 offset1:7
	ds_write2st64_b32 v206, v72, v73 offset0:8 offset1:9
	ds_write2st64_b32 v206, v74, v75 offset0:10 offset1:11
	ds_write2st64_b32 v206, v76, v77 offset0:12 offset1:13
	ds_write2st64_b32 v206, v78, v79 offset0:14 offset1:15
	ds_write2st64_b32 v206, v80, v81 offset0:16 offset1:17
	ds_write2st64_b32 v206, v82, v83 offset0:18 offset1:19
	ds_write2st64_b32 v206, v84, v85 offset0:20 offset1:21
	ds_write2st64_b32 v206, v86, v87 offset0:22 offset1:23
	ds_write2st64_b32 v206, v88, v89 offset0:24 offset1:25
	ds_write2st64_b32 v206, v90, v91 offset0:26 offset1:27
	ds_write2st64_b32 v206, v92, v93 offset0:28 offset1:29
	ds_write2st64_b32 v206, v94, v95 offset0:30 offset1:31
	s_add_u32 s12, s26, 0xf800000
	s_addc_u32 s13, s27, 0
	s_lshl_b32 s15, s101, 9
	s_add_u32 s12, s12, s15
	s_addc_u32 s13, s13, 0
	s_lshl_b32 s18, s92, 11
	global_load_dword v64, v196, s[12:13]
	global_load_dword v65, v196, s[12:13] offset:256
	s_add_u32 s12, s12, s18
	s_addc_u32 s13, s13, 0
	global_load_dword v66, v196, s[12:13]
	global_load_dword v67, v196, s[12:13] offset:256
	s_add_u32 s12, s12, s18
	s_addc_u32 s13, s13, 0
	global_load_dword v68, v196, s[12:13]
	global_load_dword v69, v196, s[12:13] offset:256
	s_add_u32 s12, s12, s18
	s_addc_u32 s13, s13, 0
	global_load_dword v70, v196, s[12:13]
	global_load_dword v71, v196, s[12:13] offset:256
	s_add_u32 s12, s12, s18
	s_addc_u32 s13, s13, 0
	global_load_dword v72, v196, s[12:13]
	global_load_dword v73, v196, s[12:13] offset:256
	s_add_u32 s12, s12, s18
	s_addc_u32 s13, s13, 0
	global_load_dword v74, v196, s[12:13]
	global_load_dword v75, v196, s[12:13] offset:256
	s_add_u32 s12, s12, s18
	s_addc_u32 s13, s13, 0
	global_load_dword v76, v196, s[12:13]
	global_load_dword v77, v196, s[12:13] offset:256
	s_add_u32 s12, s12, s18
	s_addc_u32 s13, s13, 0
	global_load_dword v78, v196, s[12:13]
	global_load_dword v79, v196, s[12:13] offset:256
	s_add_u32 s12, s12, s18
	s_addc_u32 s13, s13, 0
	global_load_dword v80, v196, s[12:13]
	global_load_dword v81, v196, s[12:13] offset:256
	s_add_u32 s12, s12, s18
	s_addc_u32 s13, s13, 0
	global_load_dword v82, v196, s[12:13]
	global_load_dword v83, v196, s[12:13] offset:256
	s_add_u32 s12, s12, s18
	s_addc_u32 s13, s13, 0
	global_load_dword v84, v196, s[12:13]
	global_load_dword v85, v196, s[12:13] offset:256
	s_add_u32 s12, s12, s18
	s_addc_u32 s13, s13, 0
	global_load_dword v86, v196, s[12:13]
	global_load_dword v87, v196, s[12:13] offset:256
	s_add_u32 s12, s12, s18
	s_addc_u32 s13, s13, 0
	global_load_dword v88, v196, s[12:13]
	global_load_dword v89, v196, s[12:13] offset:256
	s_add_u32 s12, s12, s18
	s_addc_u32 s13, s13, 0
	global_load_dword v90, v196, s[12:13]
	global_load_dword v91, v196, s[12:13] offset:256
	s_add_u32 s12, s12, s18
	s_addc_u32 s13, s13, 0
	global_load_dword v92, v196, s[12:13]
	global_load_dword v93, v196, s[12:13] offset:256
	s_add_u32 s12, s12, s18
	s_addc_u32 s13, s13, 0
	global_load_dword v94, v196, s[12:13]
	global_load_dword v95, v196, s[12:13] offset:256
	s_add_u32 s12, s12, s18
	s_addc_u32 s13, s13, 0
	s_waitcnt vmcnt(0)
	ds_write2st64_b32 v208, v64, v65 offset0:0 offset1:1
	ds_write2st64_b32 v208, v66, v67 offset0:2 offset1:3
	ds_write2st64_b32 v208, v68, v69 offset0:4 offset1:5
	ds_write2st64_b32 v208, v70, v71 offset0:6 offset1:7
	ds_write2st64_b32 v208, v72, v73 offset0:8 offset1:9
	ds_write2st64_b32 v208, v74, v75 offset0:10 offset1:11
	ds_write2st64_b32 v208, v76, v77 offset0:12 offset1:13
	ds_write2st64_b32 v208, v78, v79 offset0:14 offset1:15
	ds_write2st64_b32 v208, v80, v81 offset0:16 offset1:17
	ds_write2st64_b32 v208, v82, v83 offset0:18 offset1:19
	ds_write2st64_b32 v208, v84, v85 offset0:20 offset1:21
	ds_write2st64_b32 v208, v86, v87 offset0:22 offset1:23
	ds_write2st64_b32 v208, v88, v89 offset0:24 offset1:25
	ds_write2st64_b32 v208, v90, v91 offset0:26 offset1:27
	ds_write2st64_b32 v208, v92, v93 offset0:28 offset1:29
	ds_write2st64_b32 v208, v94, v95 offset0:30 offset1:31
	s_waitcnt lgkmcnt(0)
	v_mov_b32_e32 v209, 0x12000
	ds_read_b32 v212, v209
	s_waitcnt lgkmcnt(0)
	v_readfirstlane_b32 s13, v212
	s_nop 3
	s_lshl_b32 s13, s13, 2
	s_mov_b32 s14, 0
	s_mov_b32 s18, 0
	s_and_b32 s19, s18, 15
	s_lshr_b32 s98, s18, 4
	s_lshl_b32 s99, s19, 9
	s_mul_i32 s15, s19, s16
	s_lshl_b32 s18, s98, 7
	s_add_u32 s15, s15, s18
	s_lshl_b32 s18, s101, 12
	s_add_u32 s15, s15, s18
	s_add_u32 s8, s24, s15
	s_addc_u32 s9, s25, 0
	s_mul_i32 s15, s98, 0x300000
	s_add_u32 s4, s26, 0x3800000
	s_addc_u32 s5, s27, 0
	s_add_u32 s4, s4, s15
	s_addc_u32 s5, s5, 0
	v_add_u32_e32 v201, s99, v197
	v_add_u32_e32 v203, s99, v198
	ds_read2_b32 v[160:161], v201 offset0:0 offset1:8
	ds_read2_b32 v[162:163], v201 offset0:16 offset1:24
	s_waitcnt lgkmcnt(0)
	v_mad_u32_u24 v160, v160, s100, v199
	global_load_dwordx4 v[64:67], v160, s[4:5]
	global_load_dwordx2 v[68:69], v160, s[4:5] offset:16
	v_mad_u32_u24 v161, v161, s100, v199
	global_load_dwordx4 v[70:73], v161, s[4:5]
	global_load_dwordx2 v[74:75], v161, s[4:5] offset:16
	v_mad_u32_u24 v162, v162, s100, v199
	global_load_dwordx4 v[76:79], v162, s[4:5]
	global_load_dwordx2 v[80:81], v162, s[4:5] offset:16
	v_mad_u32_u24 v163, v163, s100, v199
	global_load_dwordx4 v[82:85], v163, s[4:5]
	global_load_dwordx2 v[86:87], v163, s[4:5] offset:16
	ds_read2_b32 v[168:169], v201 offset0:32 offset1:40
	ds_read2_b32 v[170:171], v201 offset0:48 offset1:56
	s_waitcnt lgkmcnt(0)
	v_mad_u32_u24 v168, v168, s100, v199
	global_load_dwordx4 v[88:91], v168, s[4:5]
	global_load_dwordx2 v[92:93], v168, s[4:5] offset:16
	v_mad_u32_u24 v169, v169, s100, v199
	global_load_dwordx4 v[94:97], v169, s[4:5]
	global_load_dwordx2 v[98:99], v169, s[4:5] offset:16
	v_mad_u32_u24 v170, v170, s100, v199
	global_load_dwordx4 v[100:103], v170, s[4:5]
	global_load_dwordx2 v[104:105], v170, s[4:5] offset:16
	v_mad_u32_u24 v171, v171, s100, v199
	global_load_dwordx4 v[106:109], v171, s[4:5]
	global_load_dwordx2 v[110:111], v171, s[4:5] offset:16
	ds_read2_b32 v[160:161], v201 offset0:64 offset1:72
	ds_read2_b32 v[162:163], v201 offset0:80 offset1:88
	s_waitcnt lgkmcnt(0)
	v_mad_u32_u24 v160, v160, s100, v199
	global_load_dwordx4 v[112:115], v160, s[4:5]
	global_load_dwordx2 v[116:117], v160, s[4:5] offset:16
	v_mad_u32_u24 v161, v161, s100, v199
	global_load_dwordx4 v[118:121], v161, s[4:5]
	global_load_dwordx2 v[122:123], v161, s[4:5] offset:16
	v_mad_u32_u24 v162, v162, s100, v199
	global_load_dwordx4 v[124:127], v162, s[4:5]
	global_load_dwordx2 v[128:129], v162, s[4:5] offset:16
	v_mad_u32_u24 v163, v163, s100, v199
	global_load_dwordx4 v[130:133], v163, s[4:5]
	global_load_dwordx2 v[134:135], v163, s[4:5] offset:16
	ds_read2_b32 v[168:169], v201 offset0:96 offset1:104
	ds_read2_b32 v[170:171], v201 offset0:112 offset1:120
	s_waitcnt lgkmcnt(0)
	v_mad_u32_u24 v168, v168, s100, v199
	global_load_dwordx4 v[136:139], v168, s[4:5]
	global_load_dwordx2 v[140:141], v168, s[4:5] offset:16
	v_mad_u32_u24 v169, v169, s100, v199
	global_load_dwordx4 v[142:145], v169, s[4:5]
	global_load_dwordx2 v[146:147], v169, s[4:5] offset:16
	v_mad_u32_u24 v170, v170, s100, v199
	global_load_dwordx4 v[148:151], v170, s[4:5]
	global_load_dwordx2 v[152:153], v170, s[4:5] offset:16
	v_mad_u32_u24 v171, v171, s100, v199
	global_load_dwordx4 v[154:157], v171, s[4:5]
	global_load_dwordx2 v[158:159], v171, s[4:5] offset:16
	global_load_dword v209, v200, s[8:9]
	ds_read2_b32 v[176:177], v203 offset0:0 offset1:8
	ds_read2_b32 v[178:179], v203 offset0:16 offset1:24
	s_mov_b32 s18, 1
	s_and_b32 s19, s18, 15
	s_lshr_b32 s98, s18, 4
	s_lshl_b32 s99, s19, 9
	s_mul_i32 s15, s19, s16
	s_lshl_b32 s18, s98, 7
	s_add_u32 s15, s15, s18
	s_lshl_b32 s18, s101, 12
	s_add_u32 s15, s15, s18
	s_add_u32 s10, s24, s15
	s_addc_u32 s11, s25, 0
	s_mul_i32 s15, s98, 0x300000
	s_add_u32 s4, s26, 0x3800000
	s_addc_u32 s5, s27, 0
	s_add_u32 s4, s4, s15
	s_addc_u32 s5, s5, 0
	v_add_u32_e32 v202, s99, v197
	v_add_u32_e32 v204, s99, v198
	ds_read2_b32 v[160:161], v202 offset0:0 offset1:8
	ds_read2_b32 v[162:163], v202 offset0:16 offset1:24
	s_waitcnt lgkmcnt(0)
.Lgv0_loop:
	global_load_dwordx4 v[192:195], v200, s[8:9]
	ds_read2_b32 v[184:185], v203 offset0:32 offset1:40
	ds_read2_b32 v[186:187], v203 offset0:48 offset1:56
	s_waitcnt vmcnt(32)
	v_cvt_scalef32_pk32_f32_fp6 v[32:63], v[64:69], 1.0
	v_pk_mul_f32 v[0:1], v[176:177], v[32:33] op_sel_hi:[0,1]
	v_pk_mul_f32 v[2:3], v[176:177], v[34:35] op_sel_hi:[0,1]
	v_pk_mul_f32 v[4:5], v[176:177], v[36:37] op_sel_hi:[0,1]
	v_pk_mul_f32 v[6:7], v[176:177], v[38:39] op_sel_hi:[0,1]
	v_pk_mul_f32 v[8:9], v[176:177], v[40:41] op_sel_hi:[0,1]
	v_pk_mul_f32 v[10:11], v[176:177], v[42:43] op_sel_hi:[0,1]
	v_pk_mul_f32 v[12:13], v[176:177], v[44:45] op_sel_hi:[0,1]
	v_pk_mul_f32 v[14:15], v[176:177], v[46:47] op_sel_hi:[0,1]
	v_pk_mul_f32 v[16:17], v[176:177], v[48:49] op_sel_hi:[0,1]
	v_pk_mul_f32 v[18:19], v[176:177], v[50:51] op_sel_hi:[0,1]
	v_pk_mul_f32 v[20:21], v[176:177], v[52:53] op_sel_hi:[0,1]
	v_pk_mul_f32 v[22:23], v[176:177], v[54:55] op_sel_hi:[0,1]
	v_pk_mul_f32 v[24:25], v[176:177], v[56:57] op_sel_hi:[0,1]
	v_pk_mul_f32 v[26:27], v[176:177], v[58:59] op_sel_hi:[0,1]
	v_pk_mul_f32 v[28:29], v[176:177], v[60:61] op_sel_hi:[0,1]
	v_pk_mul_f32 v[30:31], v[176:177], v[62:63] op_sel_hi:[0,1]
	s_waitcnt lgkmcnt(0)
	v_mad_u32_u24 v160, v160, s100, v199
	global_load_dwordx4 v[64:67], v160, s[4:5]
	global_load_dwordx2 v[68:69], v160, s[4:5] offset:16
	s_waitcnt vmcnt(32)
	v_cvt_scalef32_pk32_f32_fp6 v[32:63], v[70:75], 1.0
	v_pk_fma_f32 v[0:1], v[176:177], v[32:33], v[0:1] op_sel:[1,0,0] op_sel_hi:[1,1,1]
	v_pk_fma_f32 v[2:3], v[176:177], v[34:35], v[2:3] op_sel:[1,0,0] op_sel_hi:[1,1,1]
	v_pk_fma_f32 v[4:5], v[176:177], v[36:37], v[4:5] op_sel:[1,0,0] op_sel_hi:[1,1,1]
	v_pk_fma_f32 v[6:7], v[176:177], v[38:39], v[6:7] op_sel:[1,0,0] op_sel_hi:[1,1,1]
	v_pk_fma_f32 v[8:9], v[176:177], v[40:41], v[8:9] op_sel:[1,0,0] op_sel_hi:[1,1,1]
	v_pk_fma_f32 v[10:11], v[176:177], v[42:43], v[10:11] op_sel:[1,0,0] op_sel_hi:[1,1,1]
	v_pk_fma_f32 v[12:13], v[176:177], v[44:45], v[12:13] op_sel:[1,0,0] op_sel_hi:[1,1,1]
	v_pk_fma_f32 v[14:15], v[176:177], v[46:47], v[14:15] op_sel:[1,0,0] op_sel_hi:[1,1,1]
	v_pk_fma_f32 v[16:17], v[176:177], v[48:49], v[16:17] op_sel:[1,0,0] op_sel_hi:[1,1,1]
	v_pk_fma_f32 v[18:19], v[176:177], v[50:51], v[18:19] op_sel:[1,0,0] op_sel_hi:[1,1,1]
	v_pk_fma_f32 v[20:21], v[176:177], v[52:53], v[20:21] op_sel:[1,0,0] op_sel_hi:[1,1,1]
	v_pk_fma_f32 v[22:23], v[176:177], v[54:55], v[22:23] op_sel:[1,0,0] op_sel_hi:[1,1,1]
	v_pk_fma_f32 v[24:25], v[176:177], v[56:57], v[24:25] op_sel:[1,0,0] op_sel_hi:[1,1,1]
	v_pk_fma_f32 v[26:27], v[176:177], v[58:59], v[26:27] op_sel:[1,0,0] op_sel_hi:[1,1,1]
	v_pk_fma_f32 v[28:29], v[176:177], v[60:61], v[28:29] op_sel:[1,0,0] op_sel_hi:[1,1,1]
	v_pk_fma_f32 v[30:31], v[176:177], v[62:63], v[30:31] op_sel:[1,0,0] op_sel_hi:[1,1,1]
	v_mad_u32_u24 v161, v161, s100, v199
	global_load_dwordx4 v[70:73], v161, s[4:5]
	global_load_dwordx2 v[74:75], v161, s[4:5] offset:16
	s_waitcnt vmcnt(32)
	v_cvt_scalef32_pk32_f32_fp6 v[32:63], v[76:81], 1.0
	v_pk_fma_f32 v[0:1], v[178:179], v[32:33], v[0:1] op_sel_hi:[0,1,1]
	v_pk_fma_f32 v[2:3], v[178:179], v[34:35], v[2:3] op_sel_hi:[0,1,1]
	v_pk_fma_f32 v[4:5], v[178:179], v[36:37], v[4:5] op_sel_hi:[0,1,1]
	v_pk_fma_f32 v[6:7], v[178:179], v[38:39], v[6:7] op_sel_hi:[0,1,1]
	v_pk_fma_f32 v[8:9], v[178:179], v[40:41], v[8:9] op_sel_hi:[0,1,1]
	v_pk_fma_f32 v[10:11], v[178:179], v[42:43], v[10:11] op_sel_hi:[0,1,1]
	v_pk_fma_f32 v[12:13], v[178:179], v[44:45], v[12:13] op_sel_hi:[0,1,1]
	v_pk_fma_f32 v[14:15], v[178:179], v[46:47], v[14:15] op_sel_hi:[0,1,1]
	v_pk_fma_f32 v[16:17], v[178:179], v[48:49], v[16:17] op_sel_hi:[0,1,1]
	v_pk_fma_f32 v[18:19], v[178:179], v[50:51], v[18:19] op_sel_hi:[0,1,1]
	v_pk_fma_f32 v[20:21], v[178:179], v[52:53], v[20:21] op_sel_hi:[0,1,1]
	v_pk_fma_f32 v[22:23], v[178:179], v[54:55], v[22:23] op_sel_hi:[0,1,1]
	v_pk_fma_f32 v[24:25], v[178:179], v[56:57], v[24:25] op_sel_hi:[0,1,1]
	v_pk_fma_f32 v[26:27], v[178:179], v[58:59], v[26:27] op_sel_hi:[0,1,1]
	v_pk_fma_f32 v[28:29], v[178:179], v[60:61], v[28:29] op_sel_hi:[0,1,1]
	v_pk_fma_f32 v[30:31], v[178:179], v[62:63], v[30:31] op_sel_hi:[0,1,1]
	v_mad_u32_u24 v162, v162, s100, v199
	global_load_dwordx4 v[76:79], v162, s[4:5]
	global_load_dwordx2 v[80:81], v162, s[4:5] offset:16
	s_waitcnt vmcnt(32)
	v_cvt_scalef32_pk32_f32_fp6 v[32:63], v[82:87], 1.0
	v_pk_fma_f32 v[0:1], v[178:179], v[32:33], v[0:1] op_sel:[1,0,0] op_sel_hi:[1,1,1]
	v_pk_fma_f32 v[2:3], v[178:179], v[34:35], v[2:3] op_sel:[1,0,0] op_sel_hi:[1,1,1]
	v_pk_fma_f32 v[4:5], v[178:179], v[36:37], v[4:5] op_sel:[1,0,0] op_sel_hi:[1,1,1]
	v_pk_fma_f32 v[6:7], v[178:179], v[38:39], v[6:7] op_sel:[1,0,0] op_sel_hi:[1,1,1]
	v_pk_fma_f32 v[8:9], v[178:179], v[40:41], v[8:9] op_sel:[1,0,0] op_sel_hi:[1,1,1]
	v_pk_fma_f32 v[10:11], v[178:179], v[42:43], v[10:11] op_sel:[1,0,0] op_sel_hi:[1,1,1]
	v_pk_fma_f32 v[12:13], v[178:179], v[44:45], v[12:13] op_sel:[1,0,0] op_sel_hi:[1,1,1]
	v_pk_fma_f32 v[14:15], v[178:179], v[46:47], v[14:15] op_sel:[1,0,0] op_sel_hi:[1,1,1]
	v_pk_fma_f32 v[16:17], v[178:179], v[48:49], v[16:17] op_sel:[1,0,0] op_sel_hi:[1,1,1]
	v_pk_fma_f32 v[18:19], v[178:179], v[50:51], v[18:19] op_sel:[1,0,0] op_sel_hi:[1,1,1]
	v_pk_fma_f32 v[20:21], v[178:179], v[52:53], v[20:21] op_sel:[1,0,0] op_sel_hi:[1,1,1]
	v_pk_fma_f32 v[22:23], v[178:179], v[54:55], v[22:23] op_sel:[1,0,0] op_sel_hi:[1,1,1]
	v_pk_fma_f32 v[24:25], v[178:179], v[56:57], v[24:25] op_sel:[1,0,0] op_sel_hi:[1,1,1]
	v_pk_fma_f32 v[26:27], v[178:179], v[58:59], v[26:27] op_sel:[1,0,0] op_sel_hi:[1,1,1]
	v_pk_fma_f32 v[28:29], v[178:179], v[60:61], v[28:29] op_sel:[1,0,0] op_sel_hi:[1,1,1]
	v_pk_fma_f32 v[30:31], v[178:179], v[62:63], v[30:31] op_sel:[1,0,0] op_sel_hi:[1,1,1]
	v_mad_u32_u24 v163, v163, s100, v199
	global_load_dwordx4 v[82:85], v163, s[4:5]
	global_load_dwordx2 v[86:87], v163, s[4:5] offset:16
	ds_read2_b32 v[168:169], v202 offset0:32 offset1:40
	ds_read2_b32 v[170:171], v202 offset0:48 offset1:56
	ds_read2_b32 v[176:177], v203 offset0:64 offset1:72
	ds_read2_b32 v[178:179], v203 offset0:80 offset1:88
	s_waitcnt vmcnt(32)
	v_cvt_scalef32_pk32_f32_fp6 v[32:63], v[88:93], 1.0
	v_pk_fma_f32 v[0:1], v[184:185], v[32:33], v[0:1] op_sel_hi:[0,1,1]
	v_pk_fma_f32 v[2:3], v[184:185], v[34:35], v[2:3] op_sel_hi:[0,1,1]
	v_pk_fma_f32 v[4:5], v[184:185], v[36:37], v[4:5] op_sel_hi:[0,1,1]
	v_pk_fma_f32 v[6:7], v[184:185], v[38:39], v[6:7] op_sel_hi:[0,1,1]
	v_pk_fma_f32 v[8:9], v[184:185], v[40:41], v[8:9] op_sel_hi:[0,1,1]
	v_pk_fma_f32 v[10:11], v[184:185], v[42:43], v[10:11] op_sel_hi:[0,1,1]
	v_pk_fma_f32 v[12:13], v[184:185], v[44:45], v[12:13] op_sel_hi:[0,1,1]
	v_pk_fma_f32 v[14:15], v[184:185], v[46:47], v[14:15] op_sel_hi:[0,1,1]
	v_pk_fma_f32 v[16:17], v[184:185], v[48:49], v[16:17] op_sel_hi:[0,1,1]
	v_pk_fma_f32 v[18:19], v[184:185], v[50:51], v[18:19] op_sel_hi:[0,1,1]
	v_pk_fma_f32 v[20:21], v[184:185], v[52:53], v[20:21] op_sel_hi:[0,1,1]
	v_pk_fma_f32 v[22:23], v[184:185], v[54:55], v[22:23] op_sel_hi:[0,1,1]
	v_pk_fma_f32 v[24:25], v[184:185], v[56:57], v[24:25] op_sel_hi:[0,1,1]
	v_pk_fma_f32 v[26:27], v[184:185], v[58:59], v[26:27] op_sel_hi:[0,1,1]
	v_pk_fma_f32 v[28:29], v[184:185], v[60:61], v[28:29] op_sel_hi:[0,1,1]
	v_pk_fma_f32 v[30:31], v[184:185], v[62:63], v[30:31] op_sel_hi:[0,1,1]
	s_waitcnt lgkmcnt(0)
	v_mad_u32_u24 v168, v168, s100, v199
	global_load_dwordx4 v[88:91], v168, s[4:5]
	global_load_dwordx2 v[92:93], v168, s[4:5] offset:16
	s_waitcnt vmcnt(32)
	v_cvt_scalef32_pk32_f32_fp6 v[32:63], v[94:99], 1.0
	v_pk_fma_f32 v[0:1], v[184:185], v[32:33], v[0:1] op_sel:[1,0,0] op_sel_hi:[1,1,1]
	v_pk_fma_f32 v[2:3], v[184:185], v[34:35], v[2:3] op_sel:[1,0,0] op_sel_hi:[1,1,1]
	v_pk_fma_f32 v[4:5], v[184:185], v[36:37], v[4:5] op_sel:[1,0,0] op_sel_hi:[1,1,1]
	v_pk_fma_f32 v[6:7], v[184:185], v[38:39], v[6:7] op_sel:[1,0,0] op_sel_hi:[1,1,1]
	v_pk_fma_f32 v[8:9], v[184:185], v[40:41], v[8:9] op_sel:[1,0,0] op_sel_hi:[1,1,1]
	v_pk_fma_f32 v[10:11], v[184:185], v[42:43], v[10:11] op_sel:[1,0,0] op_sel_hi:[1,1,1]
	v_pk_fma_f32 v[12:13], v[184:185], v[44:45], v[12:13] op_sel:[1,0,0] op_sel_hi:[1,1,1]
	v_pk_fma_f32 v[14:15], v[184:185], v[46:47], v[14:15] op_sel:[1,0,0] op_sel_hi:[1,1,1]
	v_pk_fma_f32 v[16:17], v[184:185], v[48:49], v[16:17] op_sel:[1,0,0] op_sel_hi:[1,1,1]
	v_pk_fma_f32 v[18:19], v[184:185], v[50:51], v[18:19] op_sel:[1,0,0] op_sel_hi:[1,1,1]
	v_pk_fma_f32 v[20:21], v[184:185], v[52:53], v[20:21] op_sel:[1,0,0] op_sel_hi:[1,1,1]
	v_pk_fma_f32 v[22:23], v[184:185], v[54:55], v[22:23] op_sel:[1,0,0] op_sel_hi:[1,1,1]
	v_pk_fma_f32 v[24:25], v[184:185], v[56:57], v[24:25] op_sel:[1,0,0] op_sel_hi:[1,1,1]
	v_pk_fma_f32 v[26:27], v[184:185], v[58:59], v[26:27] op_sel:[1,0,0] op_sel_hi:[1,1,1]
	v_pk_fma_f32 v[28:29], v[184:185], v[60:61], v[28:29] op_sel:[1,0,0] op_sel_hi:[1,1,1]
	v_pk_fma_f32 v[30:31], v[184:185], v[62:63], v[30:31] op_sel:[1,0,0] op_sel_hi:[1,1,1]
	v_mad_u32_u24 v169, v169, s100, v199
	global_load_dwordx4 v[94:97], v169, s[4:5]
	global_load_dwordx2 v[98:99], v169, s[4:5] offset:16
	s_waitcnt vmcnt(32)
	v_cvt_scalef32_pk32_f32_fp6 v[32:63], v[100:105], 1.0
	v_pk_fma_f32 v[0:1], v[186:187], v[32:33], v[0:1] op_sel_hi:[0,1,1]
	v_pk_fma_f32 v[2:3], v[186:187], v[34:35], v[2:3] op_sel_hi:[0,1,1]
	v_pk_fma_f32 v[4:5], v[186:187], v[36:37], v[4:5] op_sel_hi:[0,1,1]
	v_pk_fma_f32 v[6:7], v[186:187], v[38:39], v[6:7] op_sel_hi:[0,1,1]
	v_pk_fma_f32 v[8:9], v[186:187], v[40:41], v[8:9] op_sel_hi:[0,1,1]
	v_pk_fma_f32 v[10:11], v[186:187], v[42:43], v[10:11] op_sel_hi:[0,1,1]
	v_pk_fma_f32 v[12:13], v[186:187], v[44:45], v[12:13] op_sel_hi:[0,1,1]
	v_pk_fma_f32 v[14:15], v[186:187], v[46:47], v[14:15] op_sel_hi:[0,1,1]
	v_pk_fma_f32 v[16:17], v[186:187], v[48:49], v[16:17] op_sel_hi:[0,1,1]
	v_pk_fma_f32 v[18:19], v[186:187], v[50:51], v[18:19] op_sel_hi:[0,1,1]
	v_pk_fma_f32 v[20:21], v[186:187], v[52:53], v[20:21] op_sel_hi:[0,1,1]
	v_pk_fma_f32 v[22:23], v[186:187], v[54:55], v[22:23] op_sel_hi:[0,1,1]
	v_pk_fma_f32 v[24:25], v[186:187], v[56:57], v[24:25] op_sel_hi:[0,1,1]
	v_pk_fma_f32 v[26:27], v[186:187], v[58:59], v[26:27] op_sel_hi:[0,1,1]
	v_pk_fma_f32 v[28:29], v[186:187], v[60:61], v[28:29] op_sel_hi:[0,1,1]
	v_pk_fma_f32 v[30:31], v[186:187], v[62:63], v[30:31] op_sel_hi:[0,1,1]
	v_mad_u32_u24 v170, v170, s100, v199
	global_load_dwordx4 v[100:103], v170, s[4:5]
	global_load_dwordx2 v[104:105], v170, s[4:5] offset:16
	s_waitcnt vmcnt(32)
	v_cvt_scalef32_pk32_f32_fp6 v[32:63], v[106:111], 1.0
	v_pk_fma_f32 v[0:1], v[186:187], v[32:33], v[0:1] op_sel:[1,0,0] op_sel_hi:[1,1,1]
	v_pk_fma_f32 v[2:3], v[186:187], v[34:35], v[2:3] op_sel:[1,0,0] op_sel_hi:[1,1,1]
	v_pk_fma_f32 v[4:5], v[186:187], v[36:37], v[4:5] op_sel:[1,0,0] op_sel_hi:[1,1,1]
	v_pk_fma_f32 v[6:7], v[186:187], v[38:39], v[6:7] op_sel:[1,0,0] op_sel_hi:[1,1,1]
	v_pk_fma_f32 v[8:9], v[186:187], v[40:41], v[8:9] op_sel:[1,0,0] op_sel_hi:[1,1,1]
	v_pk_fma_f32 v[10:11], v[186:187], v[42:43], v[10:11] op_sel:[1,0,0] op_sel_hi:[1,1,1]
	v_pk_fma_f32 v[12:13], v[186:187], v[44:45], v[12:13] op_sel:[1,0,0] op_sel_hi:[1,1,1]
	v_pk_fma_f32 v[14:15], v[186:187], v[46:47], v[14:15] op_sel:[1,0,0] op_sel_hi:[1,1,1]
	v_pk_fma_f32 v[16:17], v[186:187], v[48:49], v[16:17] op_sel:[1,0,0] op_sel_hi:[1,1,1]
	v_pk_fma_f32 v[18:19], v[186:187], v[50:51], v[18:19] op_sel:[1,0,0] op_sel_hi:[1,1,1]
	v_pk_fma_f32 v[20:21], v[186:187], v[52:53], v[20:21] op_sel:[1,0,0] op_sel_hi:[1,1,1]
	v_pk_fma_f32 v[22:23], v[186:187], v[54:55], v[22:23] op_sel:[1,0,0] op_sel_hi:[1,1,1]
	v_pk_fma_f32 v[24:25], v[186:187], v[56:57], v[24:25] op_sel:[1,0,0] op_sel_hi:[1,1,1]
	v_pk_fma_f32 v[26:27], v[186:187], v[58:59], v[26:27] op_sel:[1,0,0] op_sel_hi:[1,1,1]
	v_pk_fma_f32 v[28:29], v[186:187], v[60:61], v[28:29] op_sel:[1,0,0] op_sel_hi:[1,1,1]
	v_pk_fma_f32 v[30:31], v[186:187], v[62:63], v[30:31] op_sel:[1,0,0] op_sel_hi:[1,1,1]
	v_mad_u32_u24 v171, v171, s100, v199
	global_load_dwordx4 v[106:109], v171, s[4:5]
	global_load_dwordx2 v[110:111], v171, s[4:5] offset:16
	ds_read2_b32 v[160:161], v202 offset0:64 offset1:72
	ds_read2_b32 v[162:163], v202 offset0:80 offset1:88
	ds_read2_b32 v[184:185], v203 offset0:96 offset1:104
	ds_read2_b32 v[186:187], v203 offset0:112 offset1:120
	s_waitcnt vmcnt(32)
	v_cvt_scalef32_pk32_f32_fp6 v[32:63], v[112:117], 1.0
	v_pk_fma_f32 v[0:1], v[176:177], v[32:33], v[0:1] op_sel_hi:[0,1,1]
	v_pk_fma_f32 v[2:3], v[176:177], v[34:35], v[2:3] op_sel_hi:[0,1,1]
	v_pk_fma_f32 v[4:5], v[176:177], v[36:37], v[4:5] op_sel_hi:[0,1,1]
	v_pk_fma_f32 v[6:7], v[176:177], v[38:39], v[6:7] op_sel_hi:[0,1,1]
	v_pk_fma_f32 v[8:9], v[176:177], v[40:41], v[8:9] op_sel_hi:[0,1,1]
	v_pk_fma_f32 v[10:11], v[176:177], v[42:43], v[10:11] op_sel_hi:[0,1,1]
	v_pk_fma_f32 v[12:13], v[176:177], v[44:45], v[12:13] op_sel_hi:[0,1,1]
	v_pk_fma_f32 v[14:15], v[176:177], v[46:47], v[14:15] op_sel_hi:[0,1,1]
	v_pk_fma_f32 v[16:17], v[176:177], v[48:49], v[16:17] op_sel_hi:[0,1,1]
	v_pk_fma_f32 v[18:19], v[176:177], v[50:51], v[18:19] op_sel_hi:[0,1,1]
	v_pk_fma_f32 v[20:21], v[176:177], v[52:53], v[20:21] op_sel_hi:[0,1,1]
	v_pk_fma_f32 v[22:23], v[176:177], v[54:55], v[22:23] op_sel_hi:[0,1,1]
	v_pk_fma_f32 v[24:25], v[176:177], v[56:57], v[24:25] op_sel_hi:[0,1,1]
	v_pk_fma_f32 v[26:27], v[176:177], v[58:59], v[26:27] op_sel_hi:[0,1,1]
	v_pk_fma_f32 v[28:29], v[176:177], v[60:61], v[28:29] op_sel_hi:[0,1,1]
	v_pk_fma_f32 v[30:31], v[176:177], v[62:63], v[30:31] op_sel_hi:[0,1,1]
	s_waitcnt lgkmcnt(0)
	v_mad_u32_u24 v160, v160, s100, v199
	global_load_dwordx4 v[112:115], v160, s[4:5]
	global_load_dwordx2 v[116:117], v160, s[4:5] offset:16
	s_waitcnt vmcnt(32)
	v_cvt_scalef32_pk32_f32_fp6 v[32:63], v[118:123], 1.0
	v_pk_fma_f32 v[0:1], v[176:177], v[32:33], v[0:1] op_sel:[1,0,0] op_sel_hi:[1,1,1]
	v_pk_fma_f32 v[2:3], v[176:177], v[34:35], v[2:3] op_sel:[1,0,0] op_sel_hi:[1,1,1]
	v_pk_fma_f32 v[4:5], v[176:177], v[36:37], v[4:5] op_sel:[1,0,0] op_sel_hi:[1,1,1]
	v_pk_fma_f32 v[6:7], v[176:177], v[38:39], v[6:7] op_sel:[1,0,0] op_sel_hi:[1,1,1]
	v_pk_fma_f32 v[8:9], v[176:177], v[40:41], v[8:9] op_sel:[1,0,0] op_sel_hi:[1,1,1]
	v_pk_fma_f32 v[10:11], v[176:177], v[42:43], v[10:11] op_sel:[1,0,0] op_sel_hi:[1,1,1]
	v_pk_fma_f32 v[12:13], v[176:177], v[44:45], v[12:13] op_sel:[1,0,0] op_sel_hi:[1,1,1]
	v_pk_fma_f32 v[14:15], v[176:177], v[46:47], v[14:15] op_sel:[1,0,0] op_sel_hi:[1,1,1]
	v_pk_fma_f32 v[16:17], v[176:177], v[48:49], v[16:17] op_sel:[1,0,0] op_sel_hi:[1,1,1]
	v_pk_fma_f32 v[18:19], v[176:177], v[50:51], v[18:19] op_sel:[1,0,0] op_sel_hi:[1,1,1]
	v_pk_fma_f32 v[20:21], v[176:177], v[52:53], v[20:21] op_sel:[1,0,0] op_sel_hi:[1,1,1]
	v_pk_fma_f32 v[22:23], v[176:177], v[54:55], v[22:23] op_sel:[1,0,0] op_sel_hi:[1,1,1]
	v_pk_fma_f32 v[24:25], v[176:177], v[56:57], v[24:25] op_sel:[1,0,0] op_sel_hi:[1,1,1]
	v_pk_fma_f32 v[26:27], v[176:177], v[58:59], v[26:27] op_sel:[1,0,0] op_sel_hi:[1,1,1]
	v_pk_fma_f32 v[28:29], v[176:177], v[60:61], v[28:29] op_sel:[1,0,0] op_sel_hi:[1,1,1]
	v_pk_fma_f32 v[30:31], v[176:177], v[62:63], v[30:31] op_sel:[1,0,0] op_sel_hi:[1,1,1]
	v_mad_u32_u24 v161, v161, s100, v199
	global_load_dwordx4 v[118:121], v161, s[4:5]
	global_load_dwordx2 v[122:123], v161, s[4:5] offset:16
	s_waitcnt vmcnt(32)
	v_cvt_scalef32_pk32_f32_fp6 v[32:63], v[124:129], 1.0
	v_pk_fma_f32 v[0:1], v[178:179], v[32:33], v[0:1] op_sel_hi:[0,1,1]
	v_pk_fma_f32 v[2:3], v[178:179], v[34:35], v[2:3] op_sel_hi:[0,1,1]
	v_pk_fma_f32 v[4:5], v[178:179], v[36:37], v[4:5] op_sel_hi:[0,1,1]
	v_pk_fma_f32 v[6:7], v[178:179], v[38:39], v[6:7] op_sel_hi:[0,1,1]
	v_pk_fma_f32 v[8:9], v[178:179], v[40:41], v[8:9] op_sel_hi:[0,1,1]
	v_pk_fma_f32 v[10:11], v[178:179], v[42:43], v[10:11] op_sel_hi:[0,1,1]
	v_pk_fma_f32 v[12:13], v[178:179], v[44:45], v[12:13] op_sel_hi:[0,1,1]
	v_pk_fma_f32 v[14:15], v[178:179], v[46:47], v[14:15] op_sel_hi:[0,1,1]
	v_pk_fma_f32 v[16:17], v[178:179], v[48:49], v[16:17] op_sel_hi:[0,1,1]
	v_pk_fma_f32 v[18:19], v[178:179], v[50:51], v[18:19] op_sel_hi:[0,1,1]
	v_pk_fma_f32 v[20:21], v[178:179], v[52:53], v[20:21] op_sel_hi:[0,1,1]
	v_pk_fma_f32 v[22:23], v[178:179], v[54:55], v[22:23] op_sel_hi:[0,1,1]
	v_pk_fma_f32 v[24:25], v[178:179], v[56:57], v[24:25] op_sel_hi:[0,1,1]
	v_pk_fma_f32 v[26:27], v[178:179], v[58:59], v[26:27] op_sel_hi:[0,1,1]
	v_pk_fma_f32 v[28:29], v[178:179], v[60:61], v[28:29] op_sel_hi:[0,1,1]
	v_pk_fma_f32 v[30:31], v[178:179], v[62:63], v[30:31] op_sel_hi:[0,1,1]
	v_mad_u32_u24 v162, v162, s100, v199
	global_load_dwordx4 v[124:127], v162, s[4:5]
	global_load_dwordx2 v[128:129], v162, s[4:5] offset:16
	s_waitcnt vmcnt(32)
	v_cvt_scalef32_pk32_f32_fp6 v[32:63], v[130:135], 1.0
	v_pk_fma_f32 v[0:1], v[178:179], v[32:33], v[0:1] op_sel:[1,0,0] op_sel_hi:[1,1,1]
	v_pk_fma_f32 v[2:3], v[178:179], v[34:35], v[2:3] op_sel:[1,0,0] op_sel_hi:[1,1,1]
	v_pk_fma_f32 v[4:5], v[178:179], v[36:37], v[4:5] op_sel:[1,0,0] op_sel_hi:[1,1,1]
	v_pk_fma_f32 v[6:7], v[178:179], v[38:39], v[6:7] op_sel:[1,0,0] op_sel_hi:[1,1,1]
	v_pk_fma_f32 v[8:9], v[178:179], v[40:41], v[8:9] op_sel:[1,0,0] op_sel_hi:[1,1,1]
	v_pk_fma_f32 v[10:11], v[178:179], v[42:43], v[10:11] op_sel:[1,0,0] op_sel_hi:[1,1,1]
	v_pk_fma_f32 v[12:13], v[178:179], v[44:45], v[12:13] op_sel:[1,0,0] op_sel_hi:[1,1,1]
	v_pk_fma_f32 v[14:15], v[178:179], v[46:47], v[14:15] op_sel:[1,0,0] op_sel_hi:[1,1,1]
	v_pk_fma_f32 v[16:17], v[178:179], v[48:49], v[16:17] op_sel:[1,0,0] op_sel_hi:[1,1,1]
	v_pk_fma_f32 v[18:19], v[178:179], v[50:51], v[18:19] op_sel:[1,0,0] op_sel_hi:[1,1,1]
	v_pk_fma_f32 v[20:21], v[178:179], v[52:53], v[20:21] op_sel:[1,0,0] op_sel_hi:[1,1,1]
	v_pk_fma_f32 v[22:23], v[178:179], v[54:55], v[22:23] op_sel:[1,0,0] op_sel_hi:[1,1,1]
	v_pk_fma_f32 v[24:25], v[178:179], v[56:57], v[24:25] op_sel:[1,0,0] op_sel_hi:[1,1,1]
	v_pk_fma_f32 v[26:27], v[178:179], v[58:59], v[26:27] op_sel:[1,0,0] op_sel_hi:[1,1,1]
	v_pk_fma_f32 v[28:29], v[178:179], v[60:61], v[28:29] op_sel:[1,0,0] op_sel_hi:[1,1,1]
	v_pk_fma_f32 v[30:31], v[178:179], v[62:63], v[30:31] op_sel:[1,0,0] op_sel_hi:[1,1,1]
	v_mad_u32_u24 v163, v163, s100, v199
	global_load_dwordx4 v[130:133], v163, s[4:5]
	global_load_dwordx2 v[134:135], v163, s[4:5] offset:16
	ds_read2_b32 v[168:169], v202 offset0:96 offset1:104
	ds_read2_b32 v[170:171], v202 offset0:112 offset1:120
	ds_read2_b32 v[176:177], v204 offset0:0 offset1:8
	ds_read2_b32 v[178:179], v204 offset0:16 offset1:24
	s_waitcnt vmcnt(32)
	v_cvt_scalef32_pk32_f32_fp6 v[32:63], v[136:141], 1.0
	v_pk_fma_f32 v[0:1], v[184:185], v[32:33], v[0:1] op_sel_hi:[0,1,1]
	v_pk_fma_f32 v[2:3], v[184:185], v[34:35], v[2:3] op_sel_hi:[0,1,1]
	v_pk_fma_f32 v[4:5], v[184:185], v[36:37], v[4:5] op_sel_hi:[0,1,1]
	v_pk_fma_f32 v[6:7], v[184:185], v[38:39], v[6:7] op_sel_hi:[0,1,1]
	v_pk_fma_f32 v[8:9], v[184:185], v[40:41], v[8:9] op_sel_hi:[0,1,1]
	v_pk_fma_f32 v[10:11], v[184:185], v[42:43], v[10:11] op_sel_hi:[0,1,1]
	v_pk_fma_f32 v[12:13], v[184:185], v[44:45], v[12:13] op_sel_hi:[0,1,1]
	v_pk_fma_f32 v[14:15], v[184:185], v[46:47], v[14:15] op_sel_hi:[0,1,1]
	v_pk_fma_f32 v[16:17], v[184:185], v[48:49], v[16:17] op_sel_hi:[0,1,1]
	v_pk_fma_f32 v[18:19], v[184:185], v[50:51], v[18:19] op_sel_hi:[0,1,1]
	v_pk_fma_f32 v[20:21], v[184:185], v[52:53], v[20:21] op_sel_hi:[0,1,1]
	v_pk_fma_f32 v[22:23], v[184:185], v[54:55], v[22:23] op_sel_hi:[0,1,1]
	v_pk_fma_f32 v[24:25], v[184:185], v[56:57], v[24:25] op_sel_hi:[0,1,1]
	v_pk_fma_f32 v[26:27], v[184:185], v[58:59], v[26:27] op_sel_hi:[0,1,1]
	v_pk_fma_f32 v[28:29], v[184:185], v[60:61], v[28:29] op_sel_hi:[0,1,1]
	v_pk_fma_f32 v[30:31], v[184:185], v[62:63], v[30:31] op_sel_hi:[0,1,1]
	s_waitcnt lgkmcnt(0)
	v_mad_u32_u24 v168, v168, s100, v199
	global_load_dwordx4 v[136:139], v168, s[4:5]
	global_load_dwordx2 v[140:141], v168, s[4:5] offset:16
	s_waitcnt vmcnt(32)
	v_cvt_scalef32_pk32_f32_fp6 v[32:63], v[142:147], 1.0
	v_pk_fma_f32 v[0:1], v[184:185], v[32:33], v[0:1] op_sel:[1,0,0] op_sel_hi:[1,1,1]
	v_pk_fma_f32 v[2:3], v[184:185], v[34:35], v[2:3] op_sel:[1,0,0] op_sel_hi:[1,1,1]
	v_pk_fma_f32 v[4:5], v[184:185], v[36:37], v[4:5] op_sel:[1,0,0] op_sel_hi:[1,1,1]
	v_pk_fma_f32 v[6:7], v[184:185], v[38:39], v[6:7] op_sel:[1,0,0] op_sel_hi:[1,1,1]
	v_pk_fma_f32 v[8:9], v[184:185], v[40:41], v[8:9] op_sel:[1,0,0] op_sel_hi:[1,1,1]
	v_pk_fma_f32 v[10:11], v[184:185], v[42:43], v[10:11] op_sel:[1,0,0] op_sel_hi:[1,1,1]
	v_pk_fma_f32 v[12:13], v[184:185], v[44:45], v[12:13] op_sel:[1,0,0] op_sel_hi:[1,1,1]
	v_pk_fma_f32 v[14:15], v[184:185], v[46:47], v[14:15] op_sel:[1,0,0] op_sel_hi:[1,1,1]
	v_pk_fma_f32 v[16:17], v[184:185], v[48:49], v[16:17] op_sel:[1,0,0] op_sel_hi:[1,1,1]
	v_pk_fma_f32 v[18:19], v[184:185], v[50:51], v[18:19] op_sel:[1,0,0] op_sel_hi:[1,1,1]
	v_pk_fma_f32 v[20:21], v[184:185], v[52:53], v[20:21] op_sel:[1,0,0] op_sel_hi:[1,1,1]
	v_pk_fma_f32 v[22:23], v[184:185], v[54:55], v[22:23] op_sel:[1,0,0] op_sel_hi:[1,1,1]
	v_pk_fma_f32 v[24:25], v[184:185], v[56:57], v[24:25] op_sel:[1,0,0] op_sel_hi:[1,1,1]
	v_pk_fma_f32 v[26:27], v[184:185], v[58:59], v[26:27] op_sel:[1,0,0] op_sel_hi:[1,1,1]
	v_pk_fma_f32 v[28:29], v[184:185], v[60:61], v[28:29] op_sel:[1,0,0] op_sel_hi:[1,1,1]
	v_pk_fma_f32 v[30:31], v[184:185], v[62:63], v[30:31] op_sel:[1,0,0] op_sel_hi:[1,1,1]
	v_mad_u32_u24 v169, v169, s100, v199
	global_load_dwordx4 v[142:145], v169, s[4:5]
	global_load_dwordx2 v[146:147], v169, s[4:5] offset:16
	s_waitcnt vmcnt(32)
	v_cvt_scalef32_pk32_f32_fp6 v[32:63], v[148:153], 1.0
	v_pk_fma_f32 v[0:1], v[186:187], v[32:33], v[0:1] op_sel_hi:[0,1,1]
	v_pk_fma_f32 v[2:3], v[186:187], v[34:35], v[2:3] op_sel_hi:[0,1,1]
	v_pk_fma_f32 v[4:5], v[186:187], v[36:37], v[4:5] op_sel_hi:[0,1,1]
	v_pk_fma_f32 v[6:7], v[186:187], v[38:39], v[6:7] op_sel_hi:[0,1,1]
	v_pk_fma_f32 v[8:9], v[186:187], v[40:41], v[8:9] op_sel_hi:[0,1,1]
	v_pk_fma_f32 v[10:11], v[186:187], v[42:43], v[10:11] op_sel_hi:[0,1,1]
	v_pk_fma_f32 v[12:13], v[186:187], v[44:45], v[12:13] op_sel_hi:[0,1,1]
	v_pk_fma_f32 v[14:15], v[186:187], v[46:47], v[14:15] op_sel_hi:[0,1,1]
	v_pk_fma_f32 v[16:17], v[186:187], v[48:49], v[16:17] op_sel_hi:[0,1,1]
	v_pk_fma_f32 v[18:19], v[186:187], v[50:51], v[18:19] op_sel_hi:[0,1,1]
	v_pk_fma_f32 v[20:21], v[186:187], v[52:53], v[20:21] op_sel_hi:[0,1,1]
	v_pk_fma_f32 v[22:23], v[186:187], v[54:55], v[22:23] op_sel_hi:[0,1,1]
	v_pk_fma_f32 v[24:25], v[186:187], v[56:57], v[24:25] op_sel_hi:[0,1,1]
	v_pk_fma_f32 v[26:27], v[186:187], v[58:59], v[26:27] op_sel_hi:[0,1,1]
	v_pk_fma_f32 v[28:29], v[186:187], v[60:61], v[28:29] op_sel_hi:[0,1,1]
	v_pk_fma_f32 v[30:31], v[186:187], v[62:63], v[30:31] op_sel_hi:[0,1,1]
	v_mad_u32_u24 v170, v170, s100, v199
	global_load_dwordx4 v[148:151], v170, s[4:5]
	global_load_dwordx2 v[152:153], v170, s[4:5] offset:16
	s_waitcnt vmcnt(32)
	v_cvt_scalef32_pk32_f32_fp6 v[32:63], v[154:159], 1.0
	v_pk_fma_f32 v[0:1], v[186:187], v[32:33], v[0:1] op_sel:[1,0,0] op_sel_hi:[1,1,1]
	v_pk_fma_f32 v[2:3], v[186:187], v[34:35], v[2:3] op_sel:[1,0,0] op_sel_hi:[1,1,1]
	v_pk_fma_f32 v[4:5], v[186:187], v[36:37], v[4:5] op_sel:[1,0,0] op_sel_hi:[1,1,1]
	v_pk_fma_f32 v[6:7], v[186:187], v[38:39], v[6:7] op_sel:[1,0,0] op_sel_hi:[1,1,1]
	v_pk_fma_f32 v[8:9], v[186:187], v[40:41], v[8:9] op_sel:[1,0,0] op_sel_hi:[1,1,1]
	v_pk_fma_f32 v[10:11], v[186:187], v[42:43], v[10:11] op_sel:[1,0,0] op_sel_hi:[1,1,1]
	v_pk_fma_f32 v[12:13], v[186:187], v[44:45], v[12:13] op_sel:[1,0,0] op_sel_hi:[1,1,1]
	v_pk_fma_f32 v[14:15], v[186:187], v[46:47], v[14:15] op_sel:[1,0,0] op_sel_hi:[1,1,1]
	v_pk_fma_f32 v[16:17], v[186:187], v[48:49], v[16:17] op_sel:[1,0,0] op_sel_hi:[1,1,1]
	v_pk_fma_f32 v[18:19], v[186:187], v[50:51], v[18:19] op_sel:[1,0,0] op_sel_hi:[1,1,1]
	v_pk_fma_f32 v[20:21], v[186:187], v[52:53], v[20:21] op_sel:[1,0,0] op_sel_hi:[1,1,1]
	v_pk_fma_f32 v[22:23], v[186:187], v[54:55], v[22:23] op_sel:[1,0,0] op_sel_hi:[1,1,1]
	v_pk_fma_f32 v[24:25], v[186:187], v[56:57], v[24:25] op_sel:[1,0,0] op_sel_hi:[1,1,1]
	v_pk_fma_f32 v[26:27], v[186:187], v[58:59], v[26:27] op_sel:[1,0,0] op_sel_hi:[1,1,1]
	v_pk_fma_f32 v[28:29], v[186:187], v[60:61], v[28:29] op_sel:[1,0,0] op_sel_hi:[1,1,1]
	v_pk_fma_f32 v[30:31], v[186:187], v[62:63], v[30:31] op_sel:[1,0,0] op_sel_hi:[1,1,1]
	v_mad_u32_u24 v171, v171, s100, v199
	global_load_dwordx4 v[154:157], v171, s[4:5]
	global_load_dwordx2 v[158:159], v171, s[4:5] offset:16
	s_nop 1
	v_permlane32_swap_b32_e32 v0, v16
	v_permlane32_swap_b32_e32 v1, v17
	v_permlane32_swap_b32_e32 v2, v18
	v_permlane32_swap_b32_e32 v3, v19
	v_permlane32_swap_b32_e32 v4, v20
	v_permlane32_swap_b32_e32 v5, v21
	v_permlane32_swap_b32_e32 v6, v22
	v_permlane32_swap_b32_e32 v7, v23
	v_permlane32_swap_b32_e32 v8, v24
	v_permlane32_swap_b32_e32 v9, v25
	v_permlane32_swap_b32_e32 v10, v26
	v_permlane32_swap_b32_e32 v11, v27
	v_permlane32_swap_b32_e32 v12, v28
	v_permlane32_swap_b32_e32 v13, v29
	v_permlane32_swap_b32_e32 v14, v30
	v_permlane32_swap_b32_e32 v15, v31
	v_pk_add_f32 v[0:1], v[0:1], v[16:17]
	v_pk_add_f32 v[2:3], v[2:3], v[18:19]
	v_pk_add_f32 v[4:5], v[4:5], v[20:21]
	v_pk_add_f32 v[6:7], v[6:7], v[22:23]
	v_pk_add_f32 v[8:9], v[8:9], v[24:25]
	v_pk_add_f32 v[10:11], v[10:11], v[26:27]
	v_pk_add_f32 v[12:13], v[12:13], v[28:29]
	v_pk_add_f32 v[14:15], v[14:15], v[30:31]
	s_nop 1
	v_permlane16_swap_b32_e32 v0, v8
	v_permlane16_swap_b32_e32 v1, v9
	v_permlane16_swap_b32_e32 v2, v10
	v_permlane16_swap_b32_e32 v3, v11
	v_permlane16_swap_b32_e32 v4, v12
	v_permlane16_swap_b32_e32 v5, v13
	v_permlane16_swap_b32_e32 v6, v14
	v_permlane16_swap_b32_e32 v7, v15
	v_pk_add_f32 v[0:1], v[0:1], v[8:9]
	v_pk_add_f32 v[2:3], v[2:3], v[10:11]
	v_pk_add_f32 v[4:5], v[4:5], v[12:13]
	v_pk_add_f32 v[6:7], v[6:7], v[14:15]
	s_nop 1
	v_add_f32_dpp v0, v0, v0 row_ror:8 row_mask:0xf bank_mask:0x3
	v_add_f32_dpp v1, v1, v1 row_ror:8 row_mask:0xf bank_mask:0x3
	v_add_f32_dpp v2, v2, v2 row_ror:8 row_mask:0xf bank_mask:0x3
	v_add_f32_dpp v3, v3, v3 row_ror:8 row_mask:0xf bank_mask:0x3
	v_add_f32_dpp v0, v4, v4 row_ror:8 row_mask:0xf bank_mask:0xc
	v_add_f32_dpp v1, v5, v5 row_ror:8 row_mask:0xf bank_mask:0xc
	v_add_f32_dpp v2, v6, v6 row_ror:8 row_mask:0xf bank_mask:0xc
	v_add_f32_dpp v3, v7, v7 row_ror:8 row_mask:0xf bank_mask:0xc
	s_waitcnt vmcnt(32)
	v_pk_add_f32 v[192:193], v[192:193], v[0:1]
	v_pk_add_f32 v[194:195], v[194:195], v[2:3]
	global_store_dwordx4 v200, v[192:195], s[8:9]
	s_add_u32 s14, s14, 1
	s_and_b32 s14, s14, 63
	s_add_u32 s18, s14, 1
	s_and_b32 s98, s18, 63
	s_mov_b32 s100, s98
	s_and_b32 s19, s100, 15
	s_lshr_b32 s98, s100, 4
	s_lshl_b32 s99, s19, 9
	s_mul_i32 s15, s19, s16
	s_lshl_b32 s18, s98, 7
	s_add_u32 s15, s15, s18
	s_lshl_b32 s18, s101, 12
	s_add_u32 s15, s15, s18
	s_add_u32 s8, s24, s15
	s_addc_u32 s9, s25, 0
	s_mul_i32 s15, s98, 0x300000
	s_add_u32 s4, s26, 0x3800000
	s_addc_u32 s5, s27, 0
	s_add_u32 s4, s4, s15
	s_addc_u32 s5, s5, 0
	v_add_u32_e32 v201, s99, v197
	v_add_u32_e32 v203, s99, v198
	s_movk_i32 s100, 0xc0
	ds_read2_b32 v[160:161], v201 offset0:0 offset1:8
	ds_read2_b32 v[162:163], v201 offset0:16 offset1:24
	global_load_dwordx4 v[192:195], v200, s[10:11]
	ds_read2_b32 v[184:185], v204 offset0:32 offset1:40
	ds_read2_b32 v[186:187], v204 offset0:48 offset1:56
	s_waitcnt vmcnt(32)
	v_cvt_scalef32_pk32_f32_fp6 v[32:63], v[64:69], 1.0
	v_pk_mul_f32 v[0:1], v[176:177], v[32:33] op_sel_hi:[0,1]
	v_pk_mul_f32 v[2:3], v[176:177], v[34:35] op_sel_hi:[0,1]
	v_pk_mul_f32 v[4:5], v[176:177], v[36:37] op_sel_hi:[0,1]
	v_pk_mul_f32 v[6:7], v[176:177], v[38:39] op_sel_hi:[0,1]
	v_pk_mul_f32 v[8:9], v[176:177], v[40:41] op_sel_hi:[0,1]
	v_pk_mul_f32 v[10:11], v[176:177], v[42:43] op_sel_hi:[0,1]
	v_pk_mul_f32 v[12:13], v[176:177], v[44:45] op_sel_hi:[0,1]
	v_pk_mul_f32 v[14:15], v[176:177], v[46:47] op_sel_hi:[0,1]
	v_pk_mul_f32 v[16:17], v[176:177], v[48:49] op_sel_hi:[0,1]
	v_pk_mul_f32 v[18:19], v[176:177], v[50:51] op_sel_hi:[0,1]
	v_pk_mul_f32 v[20:21], v[176:177], v[52:53] op_sel_hi:[0,1]
	v_pk_mul_f32 v[22:23], v[176:177], v[54:55] op_sel_hi:[0,1]
	v_pk_mul_f32 v[24:25], v[176:177], v[56:57] op_sel_hi:[0,1]
	v_pk_mul_f32 v[26:27], v[176:177], v[58:59] op_sel_hi:[0,1]
	v_pk_mul_f32 v[28:29], v[176:177], v[60:61] op_sel_hi:[0,1]
	v_pk_mul_f32 v[30:31], v[176:177], v[62:63] op_sel_hi:[0,1]
	s_waitcnt lgkmcnt(0)
	v_mad_u32_u24 v160, v160, s100, v199
	global_load_dwordx4 v[64:67], v160, s[4:5]
	global_load_dwordx2 v[68:69], v160, s[4:5] offset:16
	s_waitcnt vmcnt(32)
	v_cvt_scalef32_pk32_f32_fp6 v[32:63], v[70:75], 1.0
	v_pk_fma_f32 v[0:1], v[176:177], v[32:33], v[0:1] op_sel:[1,0,0] op_sel_hi:[1,1,1]
	v_pk_fma_f32 v[2:3], v[176:177], v[34:35], v[2:3] op_sel:[1,0,0] op_sel_hi:[1,1,1]
	v_pk_fma_f32 v[4:5], v[176:177], v[36:37], v[4:5] op_sel:[1,0,0] op_sel_hi:[1,1,1]
	v_pk_fma_f32 v[6:7], v[176:177], v[38:39], v[6:7] op_sel:[1,0,0] op_sel_hi:[1,1,1]
	v_pk_fma_f32 v[8:9], v[176:177], v[40:41], v[8:9] op_sel:[1,0,0] op_sel_hi:[1,1,1]
	v_pk_fma_f32 v[10:11], v[176:177], v[42:43], v[10:11] op_sel:[1,0,0] op_sel_hi:[1,1,1]
	v_pk_fma_f32 v[12:13], v[176:177], v[44:45], v[12:13] op_sel:[1,0,0] op_sel_hi:[1,1,1]
	v_pk_fma_f32 v[14:15], v[176:177], v[46:47], v[14:15] op_sel:[1,0,0] op_sel_hi:[1,1,1]
	v_pk_fma_f32 v[16:17], v[176:177], v[48:49], v[16:17] op_sel:[1,0,0] op_sel_hi:[1,1,1]
	v_pk_fma_f32 v[18:19], v[176:177], v[50:51], v[18:19] op_sel:[1,0,0] op_sel_hi:[1,1,1]
	v_pk_fma_f32 v[20:21], v[176:177], v[52:53], v[20:21] op_sel:[1,0,0] op_sel_hi:[1,1,1]
	v_pk_fma_f32 v[22:23], v[176:177], v[54:55], v[22:23] op_sel:[1,0,0] op_sel_hi:[1,1,1]
	v_pk_fma_f32 v[24:25], v[176:177], v[56:57], v[24:25] op_sel:[1,0,0] op_sel_hi:[1,1,1]
	v_pk_fma_f32 v[26:27], v[176:177], v[58:59], v[26:27] op_sel:[1,0,0] op_sel_hi:[1,1,1]
	v_pk_fma_f32 v[28:29], v[176:177], v[60:61], v[28:29] op_sel:[1,0,0] op_sel_hi:[1,1,1]
	v_pk_fma_f32 v[30:31], v[176:177], v[62:63], v[30:31] op_sel:[1,0,0] op_sel_hi:[1,1,1]
	v_mad_u32_u24 v161, v161, s100, v199
	global_load_dwordx4 v[70:73], v161, s[4:5]
	global_load_dwordx2 v[74:75], v161, s[4:5] offset:16
	s_waitcnt vmcnt(32)
	v_cvt_scalef32_pk32_f32_fp6 v[32:63], v[76:81], 1.0
	v_pk_fma_f32 v[0:1], v[178:179], v[32:33], v[0:1] op_sel_hi:[0,1,1]
	v_pk_fma_f32 v[2:3], v[178:179], v[34:35], v[2:3] op_sel_hi:[0,1,1]
	v_pk_fma_f32 v[4:5], v[178:179], v[36:37], v[4:5] op_sel_hi:[0,1,1]
	v_pk_fma_f32 v[6:7], v[178:179], v[38:39], v[6:7] op_sel_hi:[0,1,1]
	v_pk_fma_f32 v[8:9], v[178:179], v[40:41], v[8:9] op_sel_hi:[0,1,1]
	v_pk_fma_f32 v[10:11], v[178:179], v[42:43], v[10:11] op_sel_hi:[0,1,1]
	v_pk_fma_f32 v[12:13], v[178:179], v[44:45], v[12:13] op_sel_hi:[0,1,1]
	v_pk_fma_f32 v[14:15], v[178:179], v[46:47], v[14:15] op_sel_hi:[0,1,1]
	v_pk_fma_f32 v[16:17], v[178:179], v[48:49], v[16:17] op_sel_hi:[0,1,1]
	v_pk_fma_f32 v[18:19], v[178:179], v[50:51], v[18:19] op_sel_hi:[0,1,1]
	v_pk_fma_f32 v[20:21], v[178:179], v[52:53], v[20:21] op_sel_hi:[0,1,1]
	v_pk_fma_f32 v[22:23], v[178:179], v[54:55], v[22:23] op_sel_hi:[0,1,1]
	v_pk_fma_f32 v[24:25], v[178:179], v[56:57], v[24:25] op_sel_hi:[0,1,1]
	v_pk_fma_f32 v[26:27], v[178:179], v[58:59], v[26:27] op_sel_hi:[0,1,1]
	v_pk_fma_f32 v[28:29], v[178:179], v[60:61], v[28:29] op_sel_hi:[0,1,1]
	v_pk_fma_f32 v[30:31], v[178:179], v[62:63], v[30:31] op_sel_hi:[0,1,1]
	v_mad_u32_u24 v162, v162, s100, v199
	global_load_dwordx4 v[76:79], v162, s[4:5]
	global_load_dwordx2 v[80:81], v162, s[4:5] offset:16
	s_waitcnt vmcnt(32)
	v_cvt_scalef32_pk32_f32_fp6 v[32:63], v[82:87], 1.0
	v_pk_fma_f32 v[0:1], v[178:179], v[32:33], v[0:1] op_sel:[1,0,0] op_sel_hi:[1,1,1]
	v_pk_fma_f32 v[2:3], v[178:179], v[34:35], v[2:3] op_sel:[1,0,0] op_sel_hi:[1,1,1]
	v_pk_fma_f32 v[4:5], v[178:179], v[36:37], v[4:5] op_sel:[1,0,0] op_sel_hi:[1,1,1]
	v_pk_fma_f32 v[6:7], v[178:179], v[38:39], v[6:7] op_sel:[1,0,0] op_sel_hi:[1,1,1]
	v_pk_fma_f32 v[8:9], v[178:179], v[40:41], v[8:9] op_sel:[1,0,0] op_sel_hi:[1,1,1]
	v_pk_fma_f32 v[10:11], v[178:179], v[42:43], v[10:11] op_sel:[1,0,0] op_sel_hi:[1,1,1]
	v_pk_fma_f32 v[12:13], v[178:179], v[44:45], v[12:13] op_sel:[1,0,0] op_sel_hi:[1,1,1]
	v_pk_fma_f32 v[14:15], v[178:179], v[46:47], v[14:15] op_sel:[1,0,0] op_sel_hi:[1,1,1]
	v_pk_fma_f32 v[16:17], v[178:179], v[48:49], v[16:17] op_sel:[1,0,0] op_sel_hi:[1,1,1]
	v_pk_fma_f32 v[18:19], v[178:179], v[50:51], v[18:19] op_sel:[1,0,0] op_sel_hi:[1,1,1]
	v_pk_fma_f32 v[20:21], v[178:179], v[52:53], v[20:21] op_sel:[1,0,0] op_sel_hi:[1,1,1]
	v_pk_fma_f32 v[22:23], v[178:179], v[54:55], v[22:23] op_sel:[1,0,0] op_sel_hi:[1,1,1]
	v_pk_fma_f32 v[24:25], v[178:179], v[56:57], v[24:25] op_sel:[1,0,0] op_sel_hi:[1,1,1]
	v_pk_fma_f32 v[26:27], v[178:179], v[58:59], v[26:27] op_sel:[1,0,0] op_sel_hi:[1,1,1]
	v_pk_fma_f32 v[28:29], v[178:179], v[60:61], v[28:29] op_sel:[1,0,0] op_sel_hi:[1,1,1]
	v_pk_fma_f32 v[30:31], v[178:179], v[62:63], v[30:31] op_sel:[1,0,0] op_sel_hi:[1,1,1]
	v_mad_u32_u24 v163, v163, s100, v199
	global_load_dwordx4 v[82:85], v163, s[4:5]
	global_load_dwordx2 v[86:87], v163, s[4:5] offset:16
	ds_read2_b32 v[168:169], v201 offset0:32 offset1:40
	ds_read2_b32 v[170:171], v201 offset0:48 offset1:56
	ds_read2_b32 v[176:177], v204 offset0:64 offset1:72
	ds_read2_b32 v[178:179], v204 offset0:80 offset1:88
	s_waitcnt vmcnt(32)
	v_cvt_scalef32_pk32_f32_fp6 v[32:63], v[88:93], 1.0
	v_pk_fma_f32 v[0:1], v[184:185], v[32:33], v[0:1] op_sel_hi:[0,1,1]
	v_pk_fma_f32 v[2:3], v[184:185], v[34:35], v[2:3] op_sel_hi:[0,1,1]
	v_pk_fma_f32 v[4:5], v[184:185], v[36:37], v[4:5] op_sel_hi:[0,1,1]
	v_pk_fma_f32 v[6:7], v[184:185], v[38:39], v[6:7] op_sel_hi:[0,1,1]
	v_pk_fma_f32 v[8:9], v[184:185], v[40:41], v[8:9] op_sel_hi:[0,1,1]
	v_pk_fma_f32 v[10:11], v[184:185], v[42:43], v[10:11] op_sel_hi:[0,1,1]
	v_pk_fma_f32 v[12:13], v[184:185], v[44:45], v[12:13] op_sel_hi:[0,1,1]
	v_pk_fma_f32 v[14:15], v[184:185], v[46:47], v[14:15] op_sel_hi:[0,1,1]
	v_pk_fma_f32 v[16:17], v[184:185], v[48:49], v[16:17] op_sel_hi:[0,1,1]
	v_pk_fma_f32 v[18:19], v[184:185], v[50:51], v[18:19] op_sel_hi:[0,1,1]
	v_pk_fma_f32 v[20:21], v[184:185], v[52:53], v[20:21] op_sel_hi:[0,1,1]
	v_pk_fma_f32 v[22:23], v[184:185], v[54:55], v[22:23] op_sel_hi:[0,1,1]
	v_pk_fma_f32 v[24:25], v[184:185], v[56:57], v[24:25] op_sel_hi:[0,1,1]
	v_pk_fma_f32 v[26:27], v[184:185], v[58:59], v[26:27] op_sel_hi:[0,1,1]
	v_pk_fma_f32 v[28:29], v[184:185], v[60:61], v[28:29] op_sel_hi:[0,1,1]
	v_pk_fma_f32 v[30:31], v[184:185], v[62:63], v[30:31] op_sel_hi:[0,1,1]
	s_waitcnt lgkmcnt(0)
	v_mad_u32_u24 v168, v168, s100, v199
	global_load_dwordx4 v[88:91], v168, s[4:5]
	global_load_dwordx2 v[92:93], v168, s[4:5] offset:16
	s_waitcnt vmcnt(32)
	v_cvt_scalef32_pk32_f32_fp6 v[32:63], v[94:99], 1.0
	v_pk_fma_f32 v[0:1], v[184:185], v[32:33], v[0:1] op_sel:[1,0,0] op_sel_hi:[1,1,1]
	v_pk_fma_f32 v[2:3], v[184:185], v[34:35], v[2:3] op_sel:[1,0,0] op_sel_hi:[1,1,1]
	v_pk_fma_f32 v[4:5], v[184:185], v[36:37], v[4:5] op_sel:[1,0,0] op_sel_hi:[1,1,1]
	v_pk_fma_f32 v[6:7], v[184:185], v[38:39], v[6:7] op_sel:[1,0,0] op_sel_hi:[1,1,1]
	v_pk_fma_f32 v[8:9], v[184:185], v[40:41], v[8:9] op_sel:[1,0,0] op_sel_hi:[1,1,1]
	v_pk_fma_f32 v[10:11], v[184:185], v[42:43], v[10:11] op_sel:[1,0,0] op_sel_hi:[1,1,1]
	v_pk_fma_f32 v[12:13], v[184:185], v[44:45], v[12:13] op_sel:[1,0,0] op_sel_hi:[1,1,1]
	v_pk_fma_f32 v[14:15], v[184:185], v[46:47], v[14:15] op_sel:[1,0,0] op_sel_hi:[1,1,1]
	v_pk_fma_f32 v[16:17], v[184:185], v[48:49], v[16:17] op_sel:[1,0,0] op_sel_hi:[1,1,1]
	v_pk_fma_f32 v[18:19], v[184:185], v[50:51], v[18:19] op_sel:[1,0,0] op_sel_hi:[1,1,1]
	v_pk_fma_f32 v[20:21], v[184:185], v[52:53], v[20:21] op_sel:[1,0,0] op_sel_hi:[1,1,1]
	v_pk_fma_f32 v[22:23], v[184:185], v[54:55], v[22:23] op_sel:[1,0,0] op_sel_hi:[1,1,1]
	v_pk_fma_f32 v[24:25], v[184:185], v[56:57], v[24:25] op_sel:[1,0,0] op_sel_hi:[1,1,1]
	v_pk_fma_f32 v[26:27], v[184:185], v[58:59], v[26:27] op_sel:[1,0,0] op_sel_hi:[1,1,1]
	v_pk_fma_f32 v[28:29], v[184:185], v[60:61], v[28:29] op_sel:[1,0,0] op_sel_hi:[1,1,1]
	v_pk_fma_f32 v[30:31], v[184:185], v[62:63], v[30:31] op_sel:[1,0,0] op_sel_hi:[1,1,1]
	v_mad_u32_u24 v169, v169, s100, v199
	global_load_dwordx4 v[94:97], v169, s[4:5]
	global_load_dwordx2 v[98:99], v169, s[4:5] offset:16
	s_waitcnt vmcnt(32)
	v_cvt_scalef32_pk32_f32_fp6 v[32:63], v[100:105], 1.0
	v_pk_fma_f32 v[0:1], v[186:187], v[32:33], v[0:1] op_sel_hi:[0,1,1]
	v_pk_fma_f32 v[2:3], v[186:187], v[34:35], v[2:3] op_sel_hi:[0,1,1]
	v_pk_fma_f32 v[4:5], v[186:187], v[36:37], v[4:5] op_sel_hi:[0,1,1]
	v_pk_fma_f32 v[6:7], v[186:187], v[38:39], v[6:7] op_sel_hi:[0,1,1]
	v_pk_fma_f32 v[8:9], v[186:187], v[40:41], v[8:9] op_sel_hi:[0,1,1]
	v_pk_fma_f32 v[10:11], v[186:187], v[42:43], v[10:11] op_sel_hi:[0,1,1]
	v_pk_fma_f32 v[12:13], v[186:187], v[44:45], v[12:13] op_sel_hi:[0,1,1]
	v_pk_fma_f32 v[14:15], v[186:187], v[46:47], v[14:15] op_sel_hi:[0,1,1]
	v_pk_fma_f32 v[16:17], v[186:187], v[48:49], v[16:17] op_sel_hi:[0,1,1]
	v_pk_fma_f32 v[18:19], v[186:187], v[50:51], v[18:19] op_sel_hi:[0,1,1]
	v_pk_fma_f32 v[20:21], v[186:187], v[52:53], v[20:21] op_sel_hi:[0,1,1]
	v_pk_fma_f32 v[22:23], v[186:187], v[54:55], v[22:23] op_sel_hi:[0,1,1]
	v_pk_fma_f32 v[24:25], v[186:187], v[56:57], v[24:25] op_sel_hi:[0,1,1]
	v_pk_fma_f32 v[26:27], v[186:187], v[58:59], v[26:27] op_sel_hi:[0,1,1]
	v_pk_fma_f32 v[28:29], v[186:187], v[60:61], v[28:29] op_sel_hi:[0,1,1]
	v_pk_fma_f32 v[30:31], v[186:187], v[62:63], v[30:31] op_sel_hi:[0,1,1]
	v_mad_u32_u24 v170, v170, s100, v199
	global_load_dwordx4 v[100:103], v170, s[4:5]
	global_load_dwordx2 v[104:105], v170, s[4:5] offset:16
	s_waitcnt vmcnt(32)
	v_cvt_scalef32_pk32_f32_fp6 v[32:63], v[106:111], 1.0
	v_pk_fma_f32 v[0:1], v[186:187], v[32:33], v[0:1] op_sel:[1,0,0] op_sel_hi:[1,1,1]
	v_pk_fma_f32 v[2:3], v[186:187], v[34:35], v[2:3] op_sel:[1,0,0] op_sel_hi:[1,1,1]
	v_pk_fma_f32 v[4:5], v[186:187], v[36:37], v[4:5] op_sel:[1,0,0] op_sel_hi:[1,1,1]
	v_pk_fma_f32 v[6:7], v[186:187], v[38:39], v[6:7] op_sel:[1,0,0] op_sel_hi:[1,1,1]
	v_pk_fma_f32 v[8:9], v[186:187], v[40:41], v[8:9] op_sel:[1,0,0] op_sel_hi:[1,1,1]
	v_pk_fma_f32 v[10:11], v[186:187], v[42:43], v[10:11] op_sel:[1,0,0] op_sel_hi:[1,1,1]
	v_pk_fma_f32 v[12:13], v[186:187], v[44:45], v[12:13] op_sel:[1,0,0] op_sel_hi:[1,1,1]
	v_pk_fma_f32 v[14:15], v[186:187], v[46:47], v[14:15] op_sel:[1,0,0] op_sel_hi:[1,1,1]
	v_pk_fma_f32 v[16:17], v[186:187], v[48:49], v[16:17] op_sel:[1,0,0] op_sel_hi:[1,1,1]
	v_pk_fma_f32 v[18:19], v[186:187], v[50:51], v[18:19] op_sel:[1,0,0] op_sel_hi:[1,1,1]
	v_pk_fma_f32 v[20:21], v[186:187], v[52:53], v[20:21] op_sel:[1,0,0] op_sel_hi:[1,1,1]
	v_pk_fma_f32 v[22:23], v[186:187], v[54:55], v[22:23] op_sel:[1,0,0] op_sel_hi:[1,1,1]
	v_pk_fma_f32 v[24:25], v[186:187], v[56:57], v[24:25] op_sel:[1,0,0] op_sel_hi:[1,1,1]
	v_pk_fma_f32 v[26:27], v[186:187], v[58:59], v[26:27] op_sel:[1,0,0] op_sel_hi:[1,1,1]
	v_pk_fma_f32 v[28:29], v[186:187], v[60:61], v[28:29] op_sel:[1,0,0] op_sel_hi:[1,1,1]
	v_pk_fma_f32 v[30:31], v[186:187], v[62:63], v[30:31] op_sel:[1,0,0] op_sel_hi:[1,1,1]
	v_mad_u32_u24 v171, v171, s100, v199
	global_load_dwordx4 v[106:109], v171, s[4:5]
	global_load_dwordx2 v[110:111], v171, s[4:5] offset:16
	ds_read2_b32 v[160:161], v201 offset0:64 offset1:72
	ds_read2_b32 v[162:163], v201 offset0:80 offset1:88
	ds_read2_b32 v[184:185], v204 offset0:96 offset1:104
	ds_read2_b32 v[186:187], v204 offset0:112 offset1:120
	s_waitcnt vmcnt(32)
	v_cvt_scalef32_pk32_f32_fp6 v[32:63], v[112:117], 1.0
	v_pk_fma_f32 v[0:1], v[176:177], v[32:33], v[0:1] op_sel_hi:[0,1,1]
	v_pk_fma_f32 v[2:3], v[176:177], v[34:35], v[2:3] op_sel_hi:[0,1,1]
	v_pk_fma_f32 v[4:5], v[176:177], v[36:37], v[4:5] op_sel_hi:[0,1,1]
	v_pk_fma_f32 v[6:7], v[176:177], v[38:39], v[6:7] op_sel_hi:[0,1,1]
	v_pk_fma_f32 v[8:9], v[176:177], v[40:41], v[8:9] op_sel_hi:[0,1,1]
	v_pk_fma_f32 v[10:11], v[176:177], v[42:43], v[10:11] op_sel_hi:[0,1,1]
	v_pk_fma_f32 v[12:13], v[176:177], v[44:45], v[12:13] op_sel_hi:[0,1,1]
	v_pk_fma_f32 v[14:15], v[176:177], v[46:47], v[14:15] op_sel_hi:[0,1,1]
	v_pk_fma_f32 v[16:17], v[176:177], v[48:49], v[16:17] op_sel_hi:[0,1,1]
	v_pk_fma_f32 v[18:19], v[176:177], v[50:51], v[18:19] op_sel_hi:[0,1,1]
	v_pk_fma_f32 v[20:21], v[176:177], v[52:53], v[20:21] op_sel_hi:[0,1,1]
	v_pk_fma_f32 v[22:23], v[176:177], v[54:55], v[22:23] op_sel_hi:[0,1,1]
	v_pk_fma_f32 v[24:25], v[176:177], v[56:57], v[24:25] op_sel_hi:[0,1,1]
	v_pk_fma_f32 v[26:27], v[176:177], v[58:59], v[26:27] op_sel_hi:[0,1,1]
	v_pk_fma_f32 v[28:29], v[176:177], v[60:61], v[28:29] op_sel_hi:[0,1,1]
	v_pk_fma_f32 v[30:31], v[176:177], v[62:63], v[30:31] op_sel_hi:[0,1,1]
	s_waitcnt lgkmcnt(0)
	v_mad_u32_u24 v160, v160, s100, v199
	global_load_dwordx4 v[112:115], v160, s[4:5]
	global_load_dwordx2 v[116:117], v160, s[4:5] offset:16
	s_waitcnt vmcnt(32)
	v_cvt_scalef32_pk32_f32_fp6 v[32:63], v[118:123], 1.0
	v_pk_fma_f32 v[0:1], v[176:177], v[32:33], v[0:1] op_sel:[1,0,0] op_sel_hi:[1,1,1]
	v_pk_fma_f32 v[2:3], v[176:177], v[34:35], v[2:3] op_sel:[1,0,0] op_sel_hi:[1,1,1]
	v_pk_fma_f32 v[4:5], v[176:177], v[36:37], v[4:5] op_sel:[1,0,0] op_sel_hi:[1,1,1]
	v_pk_fma_f32 v[6:7], v[176:177], v[38:39], v[6:7] op_sel:[1,0,0] op_sel_hi:[1,1,1]
	v_pk_fma_f32 v[8:9], v[176:177], v[40:41], v[8:9] op_sel:[1,0,0] op_sel_hi:[1,1,1]
	v_pk_fma_f32 v[10:11], v[176:177], v[42:43], v[10:11] op_sel:[1,0,0] op_sel_hi:[1,1,1]
	v_pk_fma_f32 v[12:13], v[176:177], v[44:45], v[12:13] op_sel:[1,0,0] op_sel_hi:[1,1,1]
	v_pk_fma_f32 v[14:15], v[176:177], v[46:47], v[14:15] op_sel:[1,0,0] op_sel_hi:[1,1,1]
	v_pk_fma_f32 v[16:17], v[176:177], v[48:49], v[16:17] op_sel:[1,0,0] op_sel_hi:[1,1,1]
	v_pk_fma_f32 v[18:19], v[176:177], v[50:51], v[18:19] op_sel:[1,0,0] op_sel_hi:[1,1,1]
	v_pk_fma_f32 v[20:21], v[176:177], v[52:53], v[20:21] op_sel:[1,0,0] op_sel_hi:[1,1,1]
	v_pk_fma_f32 v[22:23], v[176:177], v[54:55], v[22:23] op_sel:[1,0,0] op_sel_hi:[1,1,1]
	v_pk_fma_f32 v[24:25], v[176:177], v[56:57], v[24:25] op_sel:[1,0,0] op_sel_hi:[1,1,1]
	v_pk_fma_f32 v[26:27], v[176:177], v[58:59], v[26:27] op_sel:[1,0,0] op_sel_hi:[1,1,1]
	v_pk_fma_f32 v[28:29], v[176:177], v[60:61], v[28:29] op_sel:[1,0,0] op_sel_hi:[1,1,1]
	v_pk_fma_f32 v[30:31], v[176:177], v[62:63], v[30:31] op_sel:[1,0,0] op_sel_hi:[1,1,1]
	v_mad_u32_u24 v161, v161, s100, v199
	global_load_dwordx4 v[118:121], v161, s[4:5]
	global_load_dwordx2 v[122:123], v161, s[4:5] offset:16
	s_waitcnt vmcnt(32)
	v_cvt_scalef32_pk32_f32_fp6 v[32:63], v[124:129], 1.0
	v_pk_fma_f32 v[0:1], v[178:179], v[32:33], v[0:1] op_sel_hi:[0,1,1]
	v_pk_fma_f32 v[2:3], v[178:179], v[34:35], v[2:3] op_sel_hi:[0,1,1]
	v_pk_fma_f32 v[4:5], v[178:179], v[36:37], v[4:5] op_sel_hi:[0,1,1]
	v_pk_fma_f32 v[6:7], v[178:179], v[38:39], v[6:7] op_sel_hi:[0,1,1]
	v_pk_fma_f32 v[8:9], v[178:179], v[40:41], v[8:9] op_sel_hi:[0,1,1]
	v_pk_fma_f32 v[10:11], v[178:179], v[42:43], v[10:11] op_sel_hi:[0,1,1]
	v_pk_fma_f32 v[12:13], v[178:179], v[44:45], v[12:13] op_sel_hi:[0,1,1]
	v_pk_fma_f32 v[14:15], v[178:179], v[46:47], v[14:15] op_sel_hi:[0,1,1]
	v_pk_fma_f32 v[16:17], v[178:179], v[48:49], v[16:17] op_sel_hi:[0,1,1]
	v_pk_fma_f32 v[18:19], v[178:179], v[50:51], v[18:19] op_sel_hi:[0,1,1]
	v_pk_fma_f32 v[20:21], v[178:179], v[52:53], v[20:21] op_sel_hi:[0,1,1]
	v_pk_fma_f32 v[22:23], v[178:179], v[54:55], v[22:23] op_sel_hi:[0,1,1]
	v_pk_fma_f32 v[24:25], v[178:179], v[56:57], v[24:25] op_sel_hi:[0,1,1]
	v_pk_fma_f32 v[26:27], v[178:179], v[58:59], v[26:27] op_sel_hi:[0,1,1]
	v_pk_fma_f32 v[28:29], v[178:179], v[60:61], v[28:29] op_sel_hi:[0,1,1]
	v_pk_fma_f32 v[30:31], v[178:179], v[62:63], v[30:31] op_sel_hi:[0,1,1]
	v_mad_u32_u24 v162, v162, s100, v199
	global_load_dwordx4 v[124:127], v162, s[4:5]
	global_load_dwordx2 v[128:129], v162, s[4:5] offset:16
	s_waitcnt vmcnt(32)
	v_cvt_scalef32_pk32_f32_fp6 v[32:63], v[130:135], 1.0
	v_pk_fma_f32 v[0:1], v[178:179], v[32:33], v[0:1] op_sel:[1,0,0] op_sel_hi:[1,1,1]
	v_pk_fma_f32 v[2:3], v[178:179], v[34:35], v[2:3] op_sel:[1,0,0] op_sel_hi:[1,1,1]
	v_pk_fma_f32 v[4:5], v[178:179], v[36:37], v[4:5] op_sel:[1,0,0] op_sel_hi:[1,1,1]
	v_pk_fma_f32 v[6:7], v[178:179], v[38:39], v[6:7] op_sel:[1,0,0] op_sel_hi:[1,1,1]
	v_pk_fma_f32 v[8:9], v[178:179], v[40:41], v[8:9] op_sel:[1,0,0] op_sel_hi:[1,1,1]
	v_pk_fma_f32 v[10:11], v[178:179], v[42:43], v[10:11] op_sel:[1,0,0] op_sel_hi:[1,1,1]
	v_pk_fma_f32 v[12:13], v[178:179], v[44:45], v[12:13] op_sel:[1,0,0] op_sel_hi:[1,1,1]
	v_pk_fma_f32 v[14:15], v[178:179], v[46:47], v[14:15] op_sel:[1,0,0] op_sel_hi:[1,1,1]
	v_pk_fma_f32 v[16:17], v[178:179], v[48:49], v[16:17] op_sel:[1,0,0] op_sel_hi:[1,1,1]
	v_pk_fma_f32 v[18:19], v[178:179], v[50:51], v[18:19] op_sel:[1,0,0] op_sel_hi:[1,1,1]
	v_pk_fma_f32 v[20:21], v[178:179], v[52:53], v[20:21] op_sel:[1,0,0] op_sel_hi:[1,1,1]
	v_pk_fma_f32 v[22:23], v[178:179], v[54:55], v[22:23] op_sel:[1,0,0] op_sel_hi:[1,1,1]
	v_pk_fma_f32 v[24:25], v[178:179], v[56:57], v[24:25] op_sel:[1,0,0] op_sel_hi:[1,1,1]
	v_pk_fma_f32 v[26:27], v[178:179], v[58:59], v[26:27] op_sel:[1,0,0] op_sel_hi:[1,1,1]
	v_pk_fma_f32 v[28:29], v[178:179], v[60:61], v[28:29] op_sel:[1,0,0] op_sel_hi:[1,1,1]
	v_pk_fma_f32 v[30:31], v[178:179], v[62:63], v[30:31] op_sel:[1,0,0] op_sel_hi:[1,1,1]
	v_mad_u32_u24 v163, v163, s100, v199
	global_load_dwordx4 v[130:133], v163, s[4:5]
	global_load_dwordx2 v[134:135], v163, s[4:5] offset:16
	ds_read2_b32 v[168:169], v201 offset0:96 offset1:104
	ds_read2_b32 v[170:171], v201 offset0:112 offset1:120
	ds_read2_b32 v[176:177], v203 offset0:0 offset1:8
	ds_read2_b32 v[178:179], v203 offset0:16 offset1:24
	s_waitcnt vmcnt(32)
	v_cvt_scalef32_pk32_f32_fp6 v[32:63], v[136:141], 1.0
	v_pk_fma_f32 v[0:1], v[184:185], v[32:33], v[0:1] op_sel_hi:[0,1,1]
	v_pk_fma_f32 v[2:3], v[184:185], v[34:35], v[2:3] op_sel_hi:[0,1,1]
	v_pk_fma_f32 v[4:5], v[184:185], v[36:37], v[4:5] op_sel_hi:[0,1,1]
	v_pk_fma_f32 v[6:7], v[184:185], v[38:39], v[6:7] op_sel_hi:[0,1,1]
	v_pk_fma_f32 v[8:9], v[184:185], v[40:41], v[8:9] op_sel_hi:[0,1,1]
	v_pk_fma_f32 v[10:11], v[184:185], v[42:43], v[10:11] op_sel_hi:[0,1,1]
	v_pk_fma_f32 v[12:13], v[184:185], v[44:45], v[12:13] op_sel_hi:[0,1,1]
	v_pk_fma_f32 v[14:15], v[184:185], v[46:47], v[14:15] op_sel_hi:[0,1,1]
	v_pk_fma_f32 v[16:17], v[184:185], v[48:49], v[16:17] op_sel_hi:[0,1,1]
	v_pk_fma_f32 v[18:19], v[184:185], v[50:51], v[18:19] op_sel_hi:[0,1,1]
	v_pk_fma_f32 v[20:21], v[184:185], v[52:53], v[20:21] op_sel_hi:[0,1,1]
	v_pk_fma_f32 v[22:23], v[184:185], v[54:55], v[22:23] op_sel_hi:[0,1,1]
	v_pk_fma_f32 v[24:25], v[184:185], v[56:57], v[24:25] op_sel_hi:[0,1,1]
	v_pk_fma_f32 v[26:27], v[184:185], v[58:59], v[26:27] op_sel_hi:[0,1,1]
	v_pk_fma_f32 v[28:29], v[184:185], v[60:61], v[28:29] op_sel_hi:[0,1,1]
	v_pk_fma_f32 v[30:31], v[184:185], v[62:63], v[30:31] op_sel_hi:[0,1,1]
	s_waitcnt lgkmcnt(0)
	v_mad_u32_u24 v168, v168, s100, v199
	global_load_dwordx4 v[136:139], v168, s[4:5]
	global_load_dwordx2 v[140:141], v168, s[4:5] offset:16
	s_waitcnt vmcnt(32)
	v_cvt_scalef32_pk32_f32_fp6 v[32:63], v[142:147], 1.0
	v_pk_fma_f32 v[0:1], v[184:185], v[32:33], v[0:1] op_sel:[1,0,0] op_sel_hi:[1,1,1]
	v_pk_fma_f32 v[2:3], v[184:185], v[34:35], v[2:3] op_sel:[1,0,0] op_sel_hi:[1,1,1]
	v_pk_fma_f32 v[4:5], v[184:185], v[36:37], v[4:5] op_sel:[1,0,0] op_sel_hi:[1,1,1]
	v_pk_fma_f32 v[6:7], v[184:185], v[38:39], v[6:7] op_sel:[1,0,0] op_sel_hi:[1,1,1]
	v_pk_fma_f32 v[8:9], v[184:185], v[40:41], v[8:9] op_sel:[1,0,0] op_sel_hi:[1,1,1]
	v_pk_fma_f32 v[10:11], v[184:185], v[42:43], v[10:11] op_sel:[1,0,0] op_sel_hi:[1,1,1]
	v_pk_fma_f32 v[12:13], v[184:185], v[44:45], v[12:13] op_sel:[1,0,0] op_sel_hi:[1,1,1]
	v_pk_fma_f32 v[14:15], v[184:185], v[46:47], v[14:15] op_sel:[1,0,0] op_sel_hi:[1,1,1]
	v_pk_fma_f32 v[16:17], v[184:185], v[48:49], v[16:17] op_sel:[1,0,0] op_sel_hi:[1,1,1]
	v_pk_fma_f32 v[18:19], v[184:185], v[50:51], v[18:19] op_sel:[1,0,0] op_sel_hi:[1,1,1]
	v_pk_fma_f32 v[20:21], v[184:185], v[52:53], v[20:21] op_sel:[1,0,0] op_sel_hi:[1,1,1]
	v_pk_fma_f32 v[22:23], v[184:185], v[54:55], v[22:23] op_sel:[1,0,0] op_sel_hi:[1,1,1]
	v_pk_fma_f32 v[24:25], v[184:185], v[56:57], v[24:25] op_sel:[1,0,0] op_sel_hi:[1,1,1]
	v_pk_fma_f32 v[26:27], v[184:185], v[58:59], v[26:27] op_sel:[1,0,0] op_sel_hi:[1,1,1]
	v_pk_fma_f32 v[28:29], v[184:185], v[60:61], v[28:29] op_sel:[1,0,0] op_sel_hi:[1,1,1]
	v_pk_fma_f32 v[30:31], v[184:185], v[62:63], v[30:31] op_sel:[1,0,0] op_sel_hi:[1,1,1]
	v_mad_u32_u24 v169, v169, s100, v199
	global_load_dwordx4 v[142:145], v169, s[4:5]
	global_load_dwordx2 v[146:147], v169, s[4:5] offset:16
	s_waitcnt vmcnt(32)
	v_cvt_scalef32_pk32_f32_fp6 v[32:63], v[148:153], 1.0
	v_pk_fma_f32 v[0:1], v[186:187], v[32:33], v[0:1] op_sel_hi:[0,1,1]
	v_pk_fma_f32 v[2:3], v[186:187], v[34:35], v[2:3] op_sel_hi:[0,1,1]
	v_pk_fma_f32 v[4:5], v[186:187], v[36:37], v[4:5] op_sel_hi:[0,1,1]
	v_pk_fma_f32 v[6:7], v[186:187], v[38:39], v[6:7] op_sel_hi:[0,1,1]
	v_pk_fma_f32 v[8:9], v[186:187], v[40:41], v[8:9] op_sel_hi:[0,1,1]
	v_pk_fma_f32 v[10:11], v[186:187], v[42:43], v[10:11] op_sel_hi:[0,1,1]
	v_pk_fma_f32 v[12:13], v[186:187], v[44:45], v[12:13] op_sel_hi:[0,1,1]
	v_pk_fma_f32 v[14:15], v[186:187], v[46:47], v[14:15] op_sel_hi:[0,1,1]
	v_pk_fma_f32 v[16:17], v[186:187], v[48:49], v[16:17] op_sel_hi:[0,1,1]
	v_pk_fma_f32 v[18:19], v[186:187], v[50:51], v[18:19] op_sel_hi:[0,1,1]
	v_pk_fma_f32 v[20:21], v[186:187], v[52:53], v[20:21] op_sel_hi:[0,1,1]
	v_pk_fma_f32 v[22:23], v[186:187], v[54:55], v[22:23] op_sel_hi:[0,1,1]
	v_pk_fma_f32 v[24:25], v[186:187], v[56:57], v[24:25] op_sel_hi:[0,1,1]
	v_pk_fma_f32 v[26:27], v[186:187], v[58:59], v[26:27] op_sel_hi:[0,1,1]
	v_pk_fma_f32 v[28:29], v[186:187], v[60:61], v[28:29] op_sel_hi:[0,1,1]
	v_pk_fma_f32 v[30:31], v[186:187], v[62:63], v[30:31] op_sel_hi:[0,1,1]
	v_mad_u32_u24 v170, v170, s100, v199
	global_load_dwordx4 v[148:151], v170, s[4:5]
	global_load_dwordx2 v[152:153], v170, s[4:5] offset:16
	s_waitcnt vmcnt(32)
	v_cvt_scalef32_pk32_f32_fp6 v[32:63], v[154:159], 1.0
	v_pk_fma_f32 v[0:1], v[186:187], v[32:33], v[0:1] op_sel:[1,0,0] op_sel_hi:[1,1,1]
	v_pk_fma_f32 v[2:3], v[186:187], v[34:35], v[2:3] op_sel:[1,0,0] op_sel_hi:[1,1,1]
	v_pk_fma_f32 v[4:5], v[186:187], v[36:37], v[4:5] op_sel:[1,0,0] op_sel_hi:[1,1,1]
	v_pk_fma_f32 v[6:7], v[186:187], v[38:39], v[6:7] op_sel:[1,0,0] op_sel_hi:[1,1,1]
	v_pk_fma_f32 v[8:9], v[186:187], v[40:41], v[8:9] op_sel:[1,0,0] op_sel_hi:[1,1,1]
	v_pk_fma_f32 v[10:11], v[186:187], v[42:43], v[10:11] op_sel:[1,0,0] op_sel_hi:[1,1,1]
	v_pk_fma_f32 v[12:13], v[186:187], v[44:45], v[12:13] op_sel:[1,0,0] op_sel_hi:[1,1,1]
	v_pk_fma_f32 v[14:15], v[186:187], v[46:47], v[14:15] op_sel:[1,0,0] op_sel_hi:[1,1,1]
	v_pk_fma_f32 v[16:17], v[186:187], v[48:49], v[16:17] op_sel:[1,0,0] op_sel_hi:[1,1,1]
	v_pk_fma_f32 v[18:19], v[186:187], v[50:51], v[18:19] op_sel:[1,0,0] op_sel_hi:[1,1,1]
	v_pk_fma_f32 v[20:21], v[186:187], v[52:53], v[20:21] op_sel:[1,0,0] op_sel_hi:[1,1,1]
	v_pk_fma_f32 v[22:23], v[186:187], v[54:55], v[22:23] op_sel:[1,0,0] op_sel_hi:[1,1,1]
	v_pk_fma_f32 v[24:25], v[186:187], v[56:57], v[24:25] op_sel:[1,0,0] op_sel_hi:[1,1,1]
	v_pk_fma_f32 v[26:27], v[186:187], v[58:59], v[26:27] op_sel:[1,0,0] op_sel_hi:[1,1,1]
	v_pk_fma_f32 v[28:29], v[186:187], v[60:61], v[28:29] op_sel:[1,0,0] op_sel_hi:[1,1,1]
	v_pk_fma_f32 v[30:31], v[186:187], v[62:63], v[30:31] op_sel:[1,0,0] op_sel_hi:[1,1,1]
	v_mad_u32_u24 v171, v171, s100, v199
	global_load_dwordx4 v[154:157], v171, s[4:5]
	global_load_dwordx2 v[158:159], v171, s[4:5] offset:16
	s_nop 1
	v_permlane32_swap_b32_e32 v0, v16
	v_permlane32_swap_b32_e32 v1, v17
	v_permlane32_swap_b32_e32 v2, v18
	v_permlane32_swap_b32_e32 v3, v19
	v_permlane32_swap_b32_e32 v4, v20
	v_permlane32_swap_b32_e32 v5, v21
	v_permlane32_swap_b32_e32 v6, v22
	v_permlane32_swap_b32_e32 v7, v23
	v_permlane32_swap_b32_e32 v8, v24
	v_permlane32_swap_b32_e32 v9, v25
	v_permlane32_swap_b32_e32 v10, v26
	v_permlane32_swap_b32_e32 v11, v27
	v_permlane32_swap_b32_e32 v12, v28
	v_permlane32_swap_b32_e32 v13, v29
	v_permlane32_swap_b32_e32 v14, v30
	v_permlane32_swap_b32_e32 v15, v31
	v_pk_add_f32 v[0:1], v[0:1], v[16:17]
	v_pk_add_f32 v[2:3], v[2:3], v[18:19]
	v_pk_add_f32 v[4:5], v[4:5], v[20:21]
	v_pk_add_f32 v[6:7], v[6:7], v[22:23]
	v_pk_add_f32 v[8:9], v[8:9], v[24:25]
	v_pk_add_f32 v[10:11], v[10:11], v[26:27]
	v_pk_add_f32 v[12:13], v[12:13], v[28:29]
	v_pk_add_f32 v[14:15], v[14:15], v[30:31]
	s_nop 1
	v_permlane16_swap_b32_e32 v0, v8
	v_permlane16_swap_b32_e32 v1, v9
	v_permlane16_swap_b32_e32 v2, v10
	v_permlane16_swap_b32_e32 v3, v11
	v_permlane16_swap_b32_e32 v4, v12
	v_permlane16_swap_b32_e32 v5, v13
	v_permlane16_swap_b32_e32 v6, v14
	v_permlane16_swap_b32_e32 v7, v15
	v_pk_add_f32 v[0:1], v[0:1], v[8:9]
	v_pk_add_f32 v[2:3], v[2:3], v[10:11]
	v_pk_add_f32 v[4:5], v[4:5], v[12:13]
	v_pk_add_f32 v[6:7], v[6:7], v[14:15]
	s_nop 1
	v_add_f32_dpp v0, v0, v0 row_ror:8 row_mask:0xf bank_mask:0x3
	v_add_f32_dpp v1, v1, v1 row_ror:8 row_mask:0xf bank_mask:0x3
	v_add_f32_dpp v2, v2, v2 row_ror:8 row_mask:0xf bank_mask:0x3
	v_add_f32_dpp v3, v3, v3 row_ror:8 row_mask:0xf bank_mask:0x3
	v_add_f32_dpp v0, v4, v4 row_ror:8 row_mask:0xf bank_mask:0xc
	v_add_f32_dpp v1, v5, v5 row_ror:8 row_mask:0xf bank_mask:0xc
	v_add_f32_dpp v2, v6, v6 row_ror:8 row_mask:0xf bank_mask:0xc
	v_add_f32_dpp v3, v7, v7 row_ror:8 row_mask:0xf bank_mask:0xc
	s_waitcnt vmcnt(32)
	v_pk_add_f32 v[192:193], v[192:193], v[0:1]
	v_pk_add_f32 v[194:195], v[194:195], v[2:3]
	global_store_dwordx4 v200, v[192:195], s[10:11]
	s_add_u32 s14, s14, 1
	s_and_b32 s14, s14, 63
	s_add_u32 s18, s14, 1
	s_and_b32 s98, s18, 63
	s_mov_b32 s100, s98
	s_and_b32 s19, s100, 15
	s_lshr_b32 s98, s100, 4
	s_lshl_b32 s99, s19, 9
	s_mul_i32 s15, s19, s16
	s_lshl_b32 s18, s98, 7
	s_add_u32 s15, s15, s18
	s_lshl_b32 s18, s101, 12
	s_add_u32 s15, s15, s18
	s_add_u32 s10, s24, s15
	s_addc_u32 s11, s25, 0
	s_mul_i32 s15, s98, 0x300000
	s_add_u32 s4, s26, 0x3800000
	s_addc_u32 s5, s27, 0
	s_add_u32 s4, s4, s15
	s_addc_u32 s5, s5, 0
	v_add_u32_e32 v202, s99, v197
	v_add_u32_e32 v204, s99, v198
	s_movk_i32 s100, 0xc0
	ds_read2_b32 v[160:161], v202 offset0:0 offset1:8
	ds_read2_b32 v[162:163], v202 offset0:16 offset1:24
	s_cmp_lg_u32 s14, 0
	s_cbranch_scc1 .Lgv0_loop
	s_waitcnt vmcnt(0) lgkmcnt(0)
	s_add_u32 s4, s40, 0x1000
	s_addc_u32 s5, s41, 0
	global_load_dwordx4 v[64:67], v211, s[4:5] offset:0
	global_load_dwordx4 v[68:71], v211, s[4:5] offset:1024
	global_load_dwordx4 v[72:75], v211, s[4:5] offset:2048
	global_load_dwordx4 v[76:79], v211, s[4:5] offset:3072
	s_lshl_b32 s15, s101, 12
	s_add_u32 s8, s24, s15
	s_addc_u32 s9, s25, 0
	s_lshl_b32 s15, s101, 11
	s_add_u32 s10, s34, s15
	s_addc_u32 s11, s35, 0
	s_lshl_b32 s18, s92, 13
	v_lshlrev_b32_e32 v146, 3, v210
	v_mov_b32_e32 v147, 0x358637bd
	s_mov_b32 s19, 0x800000
	v_mov_b32_e32 v148, v146
	global_load_dwordx4 v[80:83], v211, s[8:9] offset:0
	global_load_dwordx4 v[84:87], v211, s[8:9] offset:1024
	global_load_dwordx4 v[88:91], v211, s[8:9] offset:2048
	global_load_dwordx4 v[92:95], v211, s[8:9] offset:3072
	s_add_u32 s8, s8, s16
	s_addc_u32 s9, s9, 0
	global_load_dwordx4 v[96:99], v211, s[8:9] offset:0
	global_load_dwordx4 v[100:103], v211, s[8:9] offset:1024
	global_load_dwordx4 v[104:107], v211, s[8:9] offset:2048
	global_load_dwordx4 v[108:111], v211, s[8:9] offset:3072
	s_add_u32 s8, s8, s16
	s_addc_u32 s9, s9, 0
	global_load_dwordx4 v[112:115], v211, s[8:9] offset:0
	global_load_dwordx4 v[116:119], v211, s[8:9] offset:1024
	global_load_dwordx4 v[120:123], v211, s[8:9] offset:2048
	global_load_dwordx4 v[124:127], v211, s[8:9] offset:3072
	s_add_u32 s8, s8, s16
	s_addc_u32 s9, s9, 0
	global_load_dwordx4 v[128:131], v211, s[8:9] offset:0
	global_load_dwordx4 v[132:135], v211, s[8:9] offset:1024
	global_load_dwordx4 v[136:139], v211, s[8:9] offset:2048
	global_load_dwordx4 v[140:143], v211, s[8:9] offset:3072
	s_add_u32 s8, s8, s16
	s_addc_u32 s9, s9, 0
	s_waitcnt vmcnt(0)
	v_mul_f32_e32 v144, v80, v80
	v_fmac_f32_e32 v144, v81, v81
	v_fmac_f32_e32 v144, v82, v82
	v_fmac_f32_e32 v144, v83, v83
	v_fmac_f32_e32 v144, v84, v84
	v_fmac_f32_e32 v144, v85, v85
	v_fmac_f32_e32 v144, v86, v86
	v_fmac_f32_e32 v144, v87, v87
	v_fmac_f32_e32 v144, v88, v88
	v_fmac_f32_e32 v144, v89, v89
	v_fmac_f32_e32 v144, v90, v90
	v_fmac_f32_e32 v144, v91, v91
	v_fmac_f32_e32 v144, v92, v92
	v_fmac_f32_e32 v144, v93, v93
	v_fmac_f32_e32 v144, v94, v94
	v_fmac_f32_e32 v144, v95, v95
	s_nop 1
	v_add_f32_dpp v144, v144, v144 quad_perm:[1,0,3,2] row_mask:0xf bank_mask:0xf
	s_nop 1
	v_add_f32_dpp v144, v144, v144 quad_perm:[2,3,0,1] row_mask:0xf bank_mask:0xf
	s_nop 1
	v_add_f32_dpp v144, v144, v144 row_half_mirror row_mask:0xf bank_mask:0xf
	s_nop 1
	v_add_f32_dpp v144, v144, v144 row_mirror row_mask:0xf bank_mask:0xf
	v_mov_b32_e32 v145, v144
	s_nop 1
	v_permlane16_swap_b32_e32 v144, v145
	v_add_f32_e32 v144, v144, v145
	v_mov_b32_e32 v145, v144
	s_nop 1
	v_permlane32_swap_b32_e32 v144, v145
	v_add_f32_e32 v144, v144, v145
	v_fmamk_f32 v144, v144, 0x3a800000, v147
	v_mul_f32_e32 v145, 0x4b800000, v144
	v_cmp_gt_f32_e32 vcc, s19, v144
	s_nop 1
	v_cndmask_b32_e32 v144, v144, v145, vcc
	v_rsq_f32_e32 v144, v144
	s_nop 0
	v_mul_f32_e32 v145, 0x45800000, v144
	v_cndmask_b32_e32 v144, v144, v145, vcc
	v_mul_f32_e32 v80, v80, v144
	v_mul_f32_e32 v80, v64, v80
	v_mul_f32_e32 v81, v81, v144
	v_mul_f32_e32 v81, v65, v81
	v_mul_f32_e32 v82, v82, v144
	v_mul_f32_e32 v82, v66, v82
	v_mul_f32_e32 v83, v83, v144
	v_mul_f32_e32 v83, v67, v83
	v_cvt_pk_bf16_f32 v80, v80, v81
	v_cvt_pk_bf16_f32 v81, v82, v83
	global_store_dwordx2 v148, v[80:81], s[10:11] offset:0
	v_mul_f32_e32 v84, v84, v144
	v_mul_f32_e32 v84, v68, v84
	v_mul_f32_e32 v85, v85, v144
	v_mul_f32_e32 v85, v69, v85
	v_mul_f32_e32 v86, v86, v144
	v_mul_f32_e32 v86, v70, v86
	v_mul_f32_e32 v87, v87, v144
	v_mul_f32_e32 v87, v71, v87
	v_cvt_pk_bf16_f32 v84, v84, v85
	v_cvt_pk_bf16_f32 v85, v86, v87
	global_store_dwordx2 v148, v[84:85], s[10:11] offset:512
	v_mul_f32_e32 v88, v88, v144
	v_mul_f32_e32 v88, v72, v88
	v_mul_f32_e32 v89, v89, v144
	v_mul_f32_e32 v89, v73, v89
	v_mul_f32_e32 v90, v90, v144
	v_mul_f32_e32 v90, v74, v90
	v_mul_f32_e32 v91, v91, v144
	v_mul_f32_e32 v91, v75, v91
	v_cvt_pk_bf16_f32 v88, v88, v89
	v_cvt_pk_bf16_f32 v89, v90, v91
	global_store_dwordx2 v148, v[88:89], s[10:11] offset:1024
	v_mul_f32_e32 v92, v92, v144
	v_mul_f32_e32 v92, v76, v92
	v_mul_f32_e32 v93, v93, v144
	v_mul_f32_e32 v93, v77, v93
	v_mul_f32_e32 v94, v94, v144
	v_mul_f32_e32 v94, v78, v94
	v_mul_f32_e32 v95, v95, v144
	v_mul_f32_e32 v95, v79, v95
	v_cvt_pk_bf16_f32 v92, v92, v93
	v_cvt_pk_bf16_f32 v93, v94, v95
	global_store_dwordx2 v148, v[92:93], s[10:11] offset:1536
	s_add_u32 s10, s10, s18
	s_addc_u32 s11, s11, 0
	v_mul_f32_e32 v144, v96, v96
	v_fmac_f32_e32 v144, v97, v97
	v_fmac_f32_e32 v144, v98, v98
	v_fmac_f32_e32 v144, v99, v99
	v_fmac_f32_e32 v144, v100, v100
	v_fmac_f32_e32 v144, v101, v101
	v_fmac_f32_e32 v144, v102, v102
	v_fmac_f32_e32 v144, v103, v103
	v_fmac_f32_e32 v144, v104, v104
	v_fmac_f32_e32 v144, v105, v105
	v_fmac_f32_e32 v144, v106, v106
	v_fmac_f32_e32 v144, v107, v107
	v_fmac_f32_e32 v144, v108, v108
	v_fmac_f32_e32 v144, v109, v109
	v_fmac_f32_e32 v144, v110, v110
	v_fmac_f32_e32 v144, v111, v111
	s_nop 1
	v_add_f32_dpp v144, v144, v144 quad_perm:[1,0,3,2] row_mask:0xf bank_mask:0xf
	s_nop 1
	v_add_f32_dpp v144, v144, v144 quad_perm:[2,3,0,1] row_mask:0xf bank_mask:0xf
	s_nop 1
	v_add_f32_dpp v144, v144, v144 row_half_mirror row_mask:0xf bank_mask:0xf
	s_nop 1
	v_add_f32_dpp v144, v144, v144 row_mirror row_mask:0xf bank_mask:0xf
	v_mov_b32_e32 v145, v144
	s_nop 1
	v_permlane16_swap_b32_e32 v144, v145
	v_add_f32_e32 v144, v144, v145
	v_mov_b32_e32 v145, v144
	s_nop 1
	v_permlane32_swap_b32_e32 v144, v145
	v_add_f32_e32 v144, v144, v145
	v_fmamk_f32 v144, v144, 0x3a800000, v147
	v_mul_f32_e32 v145, 0x4b800000, v144
	v_cmp_gt_f32_e32 vcc, s19, v144
	s_nop 1
	v_cndmask_b32_e32 v144, v144, v145, vcc
	v_rsq_f32_e32 v144, v144
	s_nop 0
	v_mul_f32_e32 v145, 0x45800000, v144
	v_cndmask_b32_e32 v144, v144, v145, vcc
	v_mul_f32_e32 v96, v96, v144
	v_mul_f32_e32 v96, v64, v96
	v_mul_f32_e32 v97, v97, v144
	v_mul_f32_e32 v97, v65, v97
	v_mul_f32_e32 v98, v98, v144
	v_mul_f32_e32 v98, v66, v98
	v_mul_f32_e32 v99, v99, v144
	v_mul_f32_e32 v99, v67, v99
	v_cvt_pk_bf16_f32 v96, v96, v97
	v_cvt_pk_bf16_f32 v97, v98, v99
	global_store_dwordx2 v148, v[96:97], s[10:11] offset:0
	v_mul_f32_e32 v100, v100, v144
	v_mul_f32_e32 v100, v68, v100
	v_mul_f32_e32 v101, v101, v144
	v_mul_f32_e32 v101, v69, v101
	v_mul_f32_e32 v102, v102, v144
	v_mul_f32_e32 v102, v70, v102
	v_mul_f32_e32 v103, v103, v144
	v_mul_f32_e32 v103, v71, v103
	v_cvt_pk_bf16_f32 v100, v100, v101
	v_cvt_pk_bf16_f32 v101, v102, v103
	global_store_dwordx2 v148, v[100:101], s[10:11] offset:512
	v_mul_f32_e32 v104, v104, v144
	v_mul_f32_e32 v104, v72, v104
	v_mul_f32_e32 v105, v105, v144
	v_mul_f32_e32 v105, v73, v105
	v_mul_f32_e32 v106, v106, v144
	v_mul_f32_e32 v106, v74, v106
	v_mul_f32_e32 v107, v107, v144
	v_mul_f32_e32 v107, v75, v107
	v_cvt_pk_bf16_f32 v104, v104, v105
	v_cvt_pk_bf16_f32 v105, v106, v107
	global_store_dwordx2 v148, v[104:105], s[10:11] offset:1024
	v_mul_f32_e32 v108, v108, v144
	v_mul_f32_e32 v108, v76, v108
	v_mul_f32_e32 v109, v109, v144
	v_mul_f32_e32 v109, v77, v109
	v_mul_f32_e32 v110, v110, v144
	v_mul_f32_e32 v110, v78, v110
	v_mul_f32_e32 v111, v111, v144
	v_mul_f32_e32 v111, v79, v111
	v_cvt_pk_bf16_f32 v108, v108, v109
	v_cvt_pk_bf16_f32 v109, v110, v111
	global_store_dwordx2 v148, v[108:109], s[10:11] offset:1536
	s_add_u32 s10, s10, s18
	s_addc_u32 s11, s11, 0
	v_mul_f32_e32 v144, v112, v112
	v_fmac_f32_e32 v144, v113, v113
	v_fmac_f32_e32 v144, v114, v114
	v_fmac_f32_e32 v144, v115, v115
	v_fmac_f32_e32 v144, v116, v116
	v_fmac_f32_e32 v144, v117, v117
	v_fmac_f32_e32 v144, v118, v118
	v_fmac_f32_e32 v144, v119, v119
	v_fmac_f32_e32 v144, v120, v120
	v_fmac_f32_e32 v144, v121, v121
	v_fmac_f32_e32 v144, v122, v122
	v_fmac_f32_e32 v144, v123, v123
	v_fmac_f32_e32 v144, v124, v124
	v_fmac_f32_e32 v144, v125, v125
	v_fmac_f32_e32 v144, v126, v126
	v_fmac_f32_e32 v144, v127, v127
	s_nop 1
	v_add_f32_dpp v144, v144, v144 quad_perm:[1,0,3,2] row_mask:0xf bank_mask:0xf
	s_nop 1
	v_add_f32_dpp v144, v144, v144 quad_perm:[2,3,0,1] row_mask:0xf bank_mask:0xf
	s_nop 1
	v_add_f32_dpp v144, v144, v144 row_half_mirror row_mask:0xf bank_mask:0xf
	s_nop 1
	v_add_f32_dpp v144, v144, v144 row_mirror row_mask:0xf bank_mask:0xf
	v_mov_b32_e32 v145, v144
	s_nop 1
	v_permlane16_swap_b32_e32 v144, v145
	v_add_f32_e32 v144, v144, v145
	v_mov_b32_e32 v145, v144
	s_nop 1
	v_permlane32_swap_b32_e32 v144, v145
	v_add_f32_e32 v144, v144, v145
	v_fmamk_f32 v144, v144, 0x3a800000, v147
	v_mul_f32_e32 v145, 0x4b800000, v144
	v_cmp_gt_f32_e32 vcc, s19, v144
	s_nop 1
	v_cndmask_b32_e32 v144, v144, v145, vcc
	v_rsq_f32_e32 v144, v144
	s_nop 0
	v_mul_f32_e32 v145, 0x45800000, v144
	v_cndmask_b32_e32 v144, v144, v145, vcc
	v_mul_f32_e32 v112, v112, v144
	v_mul_f32_e32 v112, v64, v112
	v_mul_f32_e32 v113, v113, v144
	v_mul_f32_e32 v113, v65, v113
	v_mul_f32_e32 v114, v114, v144
	v_mul_f32_e32 v114, v66, v114
	v_mul_f32_e32 v115, v115, v144
	v_mul_f32_e32 v115, v67, v115
	v_cvt_pk_bf16_f32 v112, v112, v113
	v_cvt_pk_bf16_f32 v113, v114, v115
	global_store_dwordx2 v148, v[112:113], s[10:11] offset:0
	v_mul_f32_e32 v116, v116, v144
	v_mul_f32_e32 v116, v68, v116
	v_mul_f32_e32 v117, v117, v144
	v_mul_f32_e32 v117, v69, v117
	v_mul_f32_e32 v118, v118, v144
	v_mul_f32_e32 v118, v70, v118
	v_mul_f32_e32 v119, v119, v144
	v_mul_f32_e32 v119, v71, v119
	v_cvt_pk_bf16_f32 v116, v116, v117
	v_cvt_pk_bf16_f32 v117, v118, v119
	global_store_dwordx2 v148, v[116:117], s[10:11] offset:512
	v_mul_f32_e32 v120, v120, v144
	v_mul_f32_e32 v120, v72, v120
	v_mul_f32_e32 v121, v121, v144
	v_mul_f32_e32 v121, v73, v121
	v_mul_f32_e32 v122, v122, v144
	v_mul_f32_e32 v122, v74, v122
	v_mul_f32_e32 v123, v123, v144
	v_mul_f32_e32 v123, v75, v123
	v_cvt_pk_bf16_f32 v120, v120, v121
	v_cvt_pk_bf16_f32 v121, v122, v123
	global_store_dwordx2 v148, v[120:121], s[10:11] offset:1024
	v_mul_f32_e32 v124, v124, v144
	v_mul_f32_e32 v124, v76, v124
	v_mul_f32_e32 v125, v125, v144
	v_mul_f32_e32 v125, v77, v125
	v_mul_f32_e32 v126, v126, v144
	v_mul_f32_e32 v126, v78, v126
	v_mul_f32_e32 v127, v127, v144
	v_mul_f32_e32 v127, v79, v127
	v_cvt_pk_bf16_f32 v124, v124, v125
	v_cvt_pk_bf16_f32 v125, v126, v127
	global_store_dwordx2 v148, v[124:125], s[10:11] offset:1536
	s_add_u32 s10, s10, s18
	s_addc_u32 s11, s11, 0
	v_mul_f32_e32 v144, v128, v128
	v_fmac_f32_e32 v144, v129, v129
	v_fmac_f32_e32 v144, v130, v130
	v_fmac_f32_e32 v144, v131, v131
	v_fmac_f32_e32 v144, v132, v132
	v_fmac_f32_e32 v144, v133, v133
	v_fmac_f32_e32 v144, v134, v134
	v_fmac_f32_e32 v144, v135, v135
	v_fmac_f32_e32 v144, v136, v136
	v_fmac_f32_e32 v144, v137, v137
	v_fmac_f32_e32 v144, v138, v138
	v_fmac_f32_e32 v144, v139, v139
	v_fmac_f32_e32 v144, v140, v140
	v_fmac_f32_e32 v144, v141, v141
	v_fmac_f32_e32 v144, v142, v142
	v_fmac_f32_e32 v144, v143, v143
	s_nop 1
	v_add_f32_dpp v144, v144, v144 quad_perm:[1,0,3,2] row_mask:0xf bank_mask:0xf
	s_nop 1
	v_add_f32_dpp v144, v144, v144 quad_perm:[2,3,0,1] row_mask:0xf bank_mask:0xf
	s_nop 1
	v_add_f32_dpp v144, v144, v144 row_half_mirror row_mask:0xf bank_mask:0xf
	s_nop 1
	v_add_f32_dpp v144, v144, v144 row_mirror row_mask:0xf bank_mask:0xf
	v_mov_b32_e32 v145, v144
	s_nop 1
	v_permlane16_swap_b32_e32 v144, v145
	v_add_f32_e32 v144, v144, v145
	v_mov_b32_e32 v145, v144
	s_nop 1
	v_permlane32_swap_b32_e32 v144, v145
	v_add_f32_e32 v144, v144, v145
	v_fmamk_f32 v144, v144, 0x3a800000, v147
	v_mul_f32_e32 v145, 0x4b800000, v144
	v_cmp_gt_f32_e32 vcc, s19, v144
	s_nop 1
	v_cndmask_b32_e32 v144, v144, v145, vcc
	v_rsq_f32_e32 v144, v144
	s_nop 0
	v_mul_f32_e32 v145, 0x45800000, v144
	v_cndmask_b32_e32 v144, v144, v145, vcc
	v_mul_f32_e32 v128, v128, v144
	v_mul_f32_e32 v128, v64, v128
	v_mul_f32_e32 v129, v129, v144
	v_mul_f32_e32 v129, v65, v129
	v_mul_f32_e32 v130, v130, v144
	v_mul_f32_e32 v130, v66, v130
	v_mul_f32_e32 v131, v131, v144
	v_mul_f32_e32 v131, v67, v131
	v_cvt_pk_bf16_f32 v128, v128, v129
	v_cvt_pk_bf16_f32 v129, v130, v131
	global_store_dwordx2 v148, v[128:129], s[10:11] offset:0
	v_mul_f32_e32 v132, v132, v144
	v_mul_f32_e32 v132, v68, v132
	v_mul_f32_e32 v133, v133, v144
	v_mul_f32_e32 v133, v69, v133
	v_mul_f32_e32 v134, v134, v144
	v_mul_f32_e32 v134, v70, v134
	v_mul_f32_e32 v135, v135, v144
	v_mul_f32_e32 v135, v71, v135
	v_cvt_pk_bf16_f32 v132, v132, v133
	v_cvt_pk_bf16_f32 v133, v134, v135
	global_store_dwordx2 v148, v[132:133], s[10:11] offset:512
	v_mul_f32_e32 v136, v136, v144
	v_mul_f32_e32 v136, v72, v136
	v_mul_f32_e32 v137, v137, v144
	v_mul_f32_e32 v137, v73, v137
	v_mul_f32_e32 v138, v138, v144
	v_mul_f32_e32 v138, v74, v138
	v_mul_f32_e32 v139, v139, v144
	v_mul_f32_e32 v139, v75, v139
	v_cvt_pk_bf16_f32 v136, v136, v137
	v_cvt_pk_bf16_f32 v137, v138, v139
	global_store_dwordx2 v148, v[136:137], s[10:11] offset:1024
	v_mul_f32_e32 v140, v140, v144
	v_mul_f32_e32 v140, v76, v140
	v_mul_f32_e32 v141, v141, v144
	v_mul_f32_e32 v141, v77, v141
	v_mul_f32_e32 v142, v142, v144
	v_mul_f32_e32 v142, v78, v142
	v_mul_f32_e32 v143, v143, v144
	v_mul_f32_e32 v143, v79, v143
	v_cvt_pk_bf16_f32 v140, v140, v141
	v_cvt_pk_bf16_f32 v141, v142, v143
	global_store_dwordx2 v148, v[140:141], s[10:11] offset:1536
	s_add_u32 s10, s10, s18
	s_addc_u32 s11, s11, 0
	global_load_dwordx4 v[80:83], v211, s[8:9] offset:0
	global_load_dwordx4 v[84:87], v211, s[8:9] offset:1024
	global_load_dwordx4 v[88:91], v211, s[8:9] offset:2048
	global_load_dwordx4 v[92:95], v211, s[8:9] offset:3072
	s_add_u32 s8, s8, s16
	s_addc_u32 s9, s9, 0
	global_load_dwordx4 v[96:99], v211, s[8:9] offset:0
	global_load_dwordx4 v[100:103], v211, s[8:9] offset:1024
	global_load_dwordx4 v[104:107], v211, s[8:9] offset:2048
	global_load_dwordx4 v[108:111], v211, s[8:9] offset:3072
	s_add_u32 s8, s8, s16
	s_addc_u32 s9, s9, 0
	global_load_dwordx4 v[112:115], v211, s[8:9] offset:0
	global_load_dwordx4 v[116:119], v211, s[8:9] offset:1024
	global_load_dwordx4 v[120:123], v211, s[8:9] offset:2048
	global_load_dwordx4 v[124:127], v211, s[8:9] offset:3072
	s_add_u32 s8, s8, s16
	s_addc_u32 s9, s9, 0
	global_load_dwordx4 v[128:131], v211, s[8:9] offset:0
	global_load_dwordx4 v[132:135], v211, s[8:9] offset:1024
	global_load_dwordx4 v[136:139], v211, s[8:9] offset:2048
	global_load_dwordx4 v[140:143], v211, s[8:9] offset:3072
	s_add_u32 s8, s8, s16
	s_addc_u32 s9, s9, 0
	s_waitcnt vmcnt(0)
	v_mul_f32_e32 v144, v80, v80
	v_fmac_f32_e32 v144, v81, v81
	v_fmac_f32_e32 v144, v82, v82
	v_fmac_f32_e32 v144, v83, v83
	v_fmac_f32_e32 v144, v84, v84
	v_fmac_f32_e32 v144, v85, v85
	v_fmac_f32_e32 v144, v86, v86
	v_fmac_f32_e32 v144, v87, v87
	v_fmac_f32_e32 v144, v88, v88
	v_fmac_f32_e32 v144, v89, v89
	v_fmac_f32_e32 v144, v90, v90
	v_fmac_f32_e32 v144, v91, v91
	v_fmac_f32_e32 v144, v92, v92
	v_fmac_f32_e32 v144, v93, v93
	v_fmac_f32_e32 v144, v94, v94
	v_fmac_f32_e32 v144, v95, v95
	s_nop 1
	v_add_f32_dpp v144, v144, v144 quad_perm:[1,0,3,2] row_mask:0xf bank_mask:0xf
	s_nop 1
	v_add_f32_dpp v144, v144, v144 quad_perm:[2,3,0,1] row_mask:0xf bank_mask:0xf
	s_nop 1
	v_add_f32_dpp v144, v144, v144 row_half_mirror row_mask:0xf bank_mask:0xf
	s_nop 1
	v_add_f32_dpp v144, v144, v144 row_mirror row_mask:0xf bank_mask:0xf
	v_mov_b32_e32 v145, v144
	s_nop 1
	v_permlane16_swap_b32_e32 v144, v145
	v_add_f32_e32 v144, v144, v145
	v_mov_b32_e32 v145, v144
	s_nop 1
	v_permlane32_swap_b32_e32 v144, v145
	v_add_f32_e32 v144, v144, v145
	v_fmamk_f32 v144, v144, 0x3a800000, v147
	v_mul_f32_e32 v145, 0x4b800000, v144
	v_cmp_gt_f32_e32 vcc, s19, v144
	s_nop 1
	v_cndmask_b32_e32 v144, v144, v145, vcc
	v_rsq_f32_e32 v144, v144
	s_nop 0
	v_mul_f32_e32 v145, 0x45800000, v144
	v_cndmask_b32_e32 v144, v144, v145, vcc
	v_mul_f32_e32 v80, v80, v144
	v_mul_f32_e32 v80, v64, v80
	v_mul_f32_e32 v81, v81, v144
	v_mul_f32_e32 v81, v65, v81
	v_mul_f32_e32 v82, v82, v144
	v_mul_f32_e32 v82, v66, v82
	v_mul_f32_e32 v83, v83, v144
	v_mul_f32_e32 v83, v67, v83
	v_cvt_pk_bf16_f32 v80, v80, v81
	v_cvt_pk_bf16_f32 v81, v82, v83
	global_store_dwordx2 v148, v[80:81], s[10:11] offset:0
	v_mul_f32_e32 v84, v84, v144
	v_mul_f32_e32 v84, v68, v84
	v_mul_f32_e32 v85, v85, v144
	v_mul_f32_e32 v85, v69, v85
	v_mul_f32_e32 v86, v86, v144
	v_mul_f32_e32 v86, v70, v86
	v_mul_f32_e32 v87, v87, v144
	v_mul_f32_e32 v87, v71, v87
	v_cvt_pk_bf16_f32 v84, v84, v85
	v_cvt_pk_bf16_f32 v85, v86, v87
	global_store_dwordx2 v148, v[84:85], s[10:11] offset:512
	v_mul_f32_e32 v88, v88, v144
	v_mul_f32_e32 v88, v72, v88
	v_mul_f32_e32 v89, v89, v144
	v_mul_f32_e32 v89, v73, v89
	v_mul_f32_e32 v90, v90, v144
	v_mul_f32_e32 v90, v74, v90
	v_mul_f32_e32 v91, v91, v144
	v_mul_f32_e32 v91, v75, v91
	v_cvt_pk_bf16_f32 v88, v88, v89
	v_cvt_pk_bf16_f32 v89, v90, v91
	global_store_dwordx2 v148, v[88:89], s[10:11] offset:1024
	v_mul_f32_e32 v92, v92, v144
	v_mul_f32_e32 v92, v76, v92
	v_mul_f32_e32 v93, v93, v144
	v_mul_f32_e32 v93, v77, v93
	v_mul_f32_e32 v94, v94, v144
	v_mul_f32_e32 v94, v78, v94
	v_mul_f32_e32 v95, v95, v144
	v_mul_f32_e32 v95, v79, v95
	v_cvt_pk_bf16_f32 v92, v92, v93
	v_cvt_pk_bf16_f32 v93, v94, v95
	global_store_dwordx2 v148, v[92:93], s[10:11] offset:1536
	s_add_u32 s10, s10, s18
	s_addc_u32 s11, s11, 0
	v_mul_f32_e32 v144, v96, v96
	v_fmac_f32_e32 v144, v97, v97
	v_fmac_f32_e32 v144, v98, v98
	v_fmac_f32_e32 v144, v99, v99
	v_fmac_f32_e32 v144, v100, v100
	v_fmac_f32_e32 v144, v101, v101
	v_fmac_f32_e32 v144, v102, v102
	v_fmac_f32_e32 v144, v103, v103
	v_fmac_f32_e32 v144, v104, v104
	v_fmac_f32_e32 v144, v105, v105
	v_fmac_f32_e32 v144, v106, v106
	v_fmac_f32_e32 v144, v107, v107
	v_fmac_f32_e32 v144, v108, v108
	v_fmac_f32_e32 v144, v109, v109
	v_fmac_f32_e32 v144, v110, v110
	v_fmac_f32_e32 v144, v111, v111
	s_nop 1
	v_add_f32_dpp v144, v144, v144 quad_perm:[1,0,3,2] row_mask:0xf bank_mask:0xf
	s_nop 1
	v_add_f32_dpp v144, v144, v144 quad_perm:[2,3,0,1] row_mask:0xf bank_mask:0xf
	s_nop 1
	v_add_f32_dpp v144, v144, v144 row_half_mirror row_mask:0xf bank_mask:0xf
	s_nop 1
	v_add_f32_dpp v144, v144, v144 row_mirror row_mask:0xf bank_mask:0xf
	v_mov_b32_e32 v145, v144
	s_nop 1
	v_permlane16_swap_b32_e32 v144, v145
	v_add_f32_e32 v144, v144, v145
	v_mov_b32_e32 v145, v144
	s_nop 1
	v_permlane32_swap_b32_e32 v144, v145
	v_add_f32_e32 v144, v144, v145
	v_fmamk_f32 v144, v144, 0x3a800000, v147
	v_mul_f32_e32 v145, 0x4b800000, v144
	v_cmp_gt_f32_e32 vcc, s19, v144
	s_nop 1
	v_cndmask_b32_e32 v144, v144, v145, vcc
	v_rsq_f32_e32 v144, v144
	s_nop 0
	v_mul_f32_e32 v145, 0x45800000, v144
	v_cndmask_b32_e32 v144, v144, v145, vcc
	v_mul_f32_e32 v96, v96, v144
	v_mul_f32_e32 v96, v64, v96
	v_mul_f32_e32 v97, v97, v144
	v_mul_f32_e32 v97, v65, v97
	v_mul_f32_e32 v98, v98, v144
	v_mul_f32_e32 v98, v66, v98
	v_mul_f32_e32 v99, v99, v144
	v_mul_f32_e32 v99, v67, v99
	v_cvt_pk_bf16_f32 v96, v96, v97
	v_cvt_pk_bf16_f32 v97, v98, v99
	global_store_dwordx2 v148, v[96:97], s[10:11] offset:0
	v_mul_f32_e32 v100, v100, v144
	v_mul_f32_e32 v100, v68, v100
	v_mul_f32_e32 v101, v101, v144
	v_mul_f32_e32 v101, v69, v101
	v_mul_f32_e32 v102, v102, v144
	v_mul_f32_e32 v102, v70, v102
	v_mul_f32_e32 v103, v103, v144
	v_mul_f32_e32 v103, v71, v103
	v_cvt_pk_bf16_f32 v100, v100, v101
	v_cvt_pk_bf16_f32 v101, v102, v103
	global_store_dwordx2 v148, v[100:101], s[10:11] offset:512
	v_mul_f32_e32 v104, v104, v144
	v_mul_f32_e32 v104, v72, v104
	v_mul_f32_e32 v105, v105, v144
	v_mul_f32_e32 v105, v73, v105
	v_mul_f32_e32 v106, v106, v144
	v_mul_f32_e32 v106, v74, v106
	v_mul_f32_e32 v107, v107, v144
	v_mul_f32_e32 v107, v75, v107
	v_cvt_pk_bf16_f32 v104, v104, v105
	v_cvt_pk_bf16_f32 v105, v106, v107
	global_store_dwordx2 v148, v[104:105], s[10:11] offset:1024
	v_mul_f32_e32 v108, v108, v144
	v_mul_f32_e32 v108, v76, v108
	v_mul_f32_e32 v109, v109, v144
	v_mul_f32_e32 v109, v77, v109
	v_mul_f32_e32 v110, v110, v144
	v_mul_f32_e32 v110, v78, v110
	v_mul_f32_e32 v111, v111, v144
	v_mul_f32_e32 v111, v79, v111
	v_cvt_pk_bf16_f32 v108, v108, v109
	v_cvt_pk_bf16_f32 v109, v110, v111
	global_store_dwordx2 v148, v[108:109], s[10:11] offset:1536
	s_add_u32 s10, s10, s18
	s_addc_u32 s11, s11, 0
	v_mul_f32_e32 v144, v112, v112
	v_fmac_f32_e32 v144, v113, v113
	v_fmac_f32_e32 v144, v114, v114
	v_fmac_f32_e32 v144, v115, v115
	v_fmac_f32_e32 v144, v116, v116
	v_fmac_f32_e32 v144, v117, v117
	v_fmac_f32_e32 v144, v118, v118
	v_fmac_f32_e32 v144, v119, v119
	v_fmac_f32_e32 v144, v120, v120
	v_fmac_f32_e32 v144, v121, v121
	v_fmac_f32_e32 v144, v122, v122
	v_fmac_f32_e32 v144, v123, v123
	v_fmac_f32_e32 v144, v124, v124
	v_fmac_f32_e32 v144, v125, v125
	v_fmac_f32_e32 v144, v126, v126
	v_fmac_f32_e32 v144, v127, v127
	s_nop 1
	v_add_f32_dpp v144, v144, v144 quad_perm:[1,0,3,2] row_mask:0xf bank_mask:0xf
	s_nop 1
	v_add_f32_dpp v144, v144, v144 quad_perm:[2,3,0,1] row_mask:0xf bank_mask:0xf
	s_nop 1
	v_add_f32_dpp v144, v144, v144 row_half_mirror row_mask:0xf bank_mask:0xf
	s_nop 1
	v_add_f32_dpp v144, v144, v144 row_mirror row_mask:0xf bank_mask:0xf
	v_mov_b32_e32 v145, v144
	s_nop 1
	v_permlane16_swap_b32_e32 v144, v145
	v_add_f32_e32 v144, v144, v145
	v_mov_b32_e32 v145, v144
	s_nop 1
	v_permlane32_swap_b32_e32 v144, v145
	v_add_f32_e32 v144, v144, v145
	v_fmamk_f32 v144, v144, 0x3a800000, v147
	v_mul_f32_e32 v145, 0x4b800000, v144
	v_cmp_gt_f32_e32 vcc, s19, v144
	s_nop 1
	v_cndmask_b32_e32 v144, v144, v145, vcc
	v_rsq_f32_e32 v144, v144
	s_nop 0
	v_mul_f32_e32 v145, 0x45800000, v144
	v_cndmask_b32_e32 v144, v144, v145, vcc
	v_mul_f32_e32 v112, v112, v144
	v_mul_f32_e32 v112, v64, v112
	v_mul_f32_e32 v113, v113, v144
	v_mul_f32_e32 v113, v65, v113
	v_mul_f32_e32 v114, v114, v144
	v_mul_f32_e32 v114, v66, v114
	v_mul_f32_e32 v115, v115, v144
	v_mul_f32_e32 v115, v67, v115
	v_cvt_pk_bf16_f32 v112, v112, v113
	v_cvt_pk_bf16_f32 v113, v114, v115
	global_store_dwordx2 v148, v[112:113], s[10:11] offset:0
	v_mul_f32_e32 v116, v116, v144
	v_mul_f32_e32 v116, v68, v116
	v_mul_f32_e32 v117, v117, v144
	v_mul_f32_e32 v117, v69, v117
	v_mul_f32_e32 v118, v118, v144
	v_mul_f32_e32 v118, v70, v118
	v_mul_f32_e32 v119, v119, v144
	v_mul_f32_e32 v119, v71, v119
	v_cvt_pk_bf16_f32 v116, v116, v117
	v_cvt_pk_bf16_f32 v117, v118, v119
	global_store_dwordx2 v148, v[116:117], s[10:11] offset:512
	v_mul_f32_e32 v120, v120, v144
	v_mul_f32_e32 v120, v72, v120
	v_mul_f32_e32 v121, v121, v144
	v_mul_f32_e32 v121, v73, v121
	v_mul_f32_e32 v122, v122, v144
	v_mul_f32_e32 v122, v74, v122
	v_mul_f32_e32 v123, v123, v144
	v_mul_f32_e32 v123, v75, v123
	v_cvt_pk_bf16_f32 v120, v120, v121
	v_cvt_pk_bf16_f32 v121, v122, v123
	global_store_dwordx2 v148, v[120:121], s[10:11] offset:1024
	v_mul_f32_e32 v124, v124, v144
	v_mul_f32_e32 v124, v76, v124
	v_mul_f32_e32 v125, v125, v144
	v_mul_f32_e32 v125, v77, v125
	v_mul_f32_e32 v126, v126, v144
	v_mul_f32_e32 v126, v78, v126
	v_mul_f32_e32 v127, v127, v144
	v_mul_f32_e32 v127, v79, v127
	v_cvt_pk_bf16_f32 v124, v124, v125
	v_cvt_pk_bf16_f32 v125, v126, v127
	global_store_dwordx2 v148, v[124:125], s[10:11] offset:1536
	s_add_u32 s10, s10, s18
	s_addc_u32 s11, s11, 0
	v_mul_f32_e32 v144, v128, v128
	v_fmac_f32_e32 v144, v129, v129
	v_fmac_f32_e32 v144, v130, v130
	v_fmac_f32_e32 v144, v131, v131
	v_fmac_f32_e32 v144, v132, v132
	v_fmac_f32_e32 v144, v133, v133
	v_fmac_f32_e32 v144, v134, v134
	v_fmac_f32_e32 v144, v135, v135
	v_fmac_f32_e32 v144, v136, v136
	v_fmac_f32_e32 v144, v137, v137
	v_fmac_f32_e32 v144, v138, v138
	v_fmac_f32_e32 v144, v139, v139
	v_fmac_f32_e32 v144, v140, v140
	v_fmac_f32_e32 v144, v141, v141
	v_fmac_f32_e32 v144, v142, v142
	v_fmac_f32_e32 v144, v143, v143
	s_nop 1
	v_add_f32_dpp v144, v144, v144 quad_perm:[1,0,3,2] row_mask:0xf bank_mask:0xf
	s_nop 1
	v_add_f32_dpp v144, v144, v144 quad_perm:[2,3,0,1] row_mask:0xf bank_mask:0xf
	s_nop 1
	v_add_f32_dpp v144, v144, v144 row_half_mirror row_mask:0xf bank_mask:0xf
	s_nop 1
	v_add_f32_dpp v144, v144, v144 row_mirror row_mask:0xf bank_mask:0xf
	v_mov_b32_e32 v145, v144
	s_nop 1
	v_permlane16_swap_b32_e32 v144, v145
	v_add_f32_e32 v144, v144, v145
	v_mov_b32_e32 v145, v144
	s_nop 1
	v_permlane32_swap_b32_e32 v144, v145
	v_add_f32_e32 v144, v144, v145
	v_fmamk_f32 v144, v144, 0x3a800000, v147
	v_mul_f32_e32 v145, 0x4b800000, v144
	v_cmp_gt_f32_e32 vcc, s19, v144
	s_nop 1
	v_cndmask_b32_e32 v144, v144, v145, vcc
	v_rsq_f32_e32 v144, v144
	s_nop 0
	v_mul_f32_e32 v145, 0x45800000, v144
	v_cndmask_b32_e32 v144, v144, v145, vcc
	v_mul_f32_e32 v128, v128, v144
	v_mul_f32_e32 v128, v64, v128
	v_mul_f32_e32 v129, v129, v144
	v_mul_f32_e32 v129, v65, v129
	v_mul_f32_e32 v130, v130, v144
	v_mul_f32_e32 v130, v66, v130
	v_mul_f32_e32 v131, v131, v144
	v_mul_f32_e32 v131, v67, v131
	v_cvt_pk_bf16_f32 v128, v128, v129
	v_cvt_pk_bf16_f32 v129, v130, v131
	global_store_dwordx2 v148, v[128:129], s[10:11] offset:0
	v_mul_f32_e32 v132, v132, v144
	v_mul_f32_e32 v132, v68, v132
	v_mul_f32_e32 v133, v133, v144
	v_mul_f32_e32 v133, v69, v133
	v_mul_f32_e32 v134, v134, v144
	v_mul_f32_e32 v134, v70, v134
	v_mul_f32_e32 v135, v135, v144
	v_mul_f32_e32 v135, v71, v135
	v_cvt_pk_bf16_f32 v132, v132, v133
	v_cvt_pk_bf16_f32 v133, v134, v135
	global_store_dwordx2 v148, v[132:133], s[10:11] offset:512
	v_mul_f32_e32 v136, v136, v144
	v_mul_f32_e32 v136, v72, v136
	v_mul_f32_e32 v137, v137, v144
	v_mul_f32_e32 v137, v73, v137
	v_mul_f32_e32 v138, v138, v144
	v_mul_f32_e32 v138, v74, v138
	v_mul_f32_e32 v139, v139, v144
	v_mul_f32_e32 v139, v75, v139
	v_cvt_pk_bf16_f32 v136, v136, v137
	v_cvt_pk_bf16_f32 v137, v138, v139
	global_store_dwordx2 v148, v[136:137], s[10:11] offset:1024
	v_mul_f32_e32 v140, v140, v144
	v_mul_f32_e32 v140, v76, v140
	v_mul_f32_e32 v141, v141, v144
	v_mul_f32_e32 v141, v77, v141
	v_mul_f32_e32 v142, v142, v144
	v_mul_f32_e32 v142, v78, v142
	v_mul_f32_e32 v143, v143, v144
	v_mul_f32_e32 v143, v79, v143
	v_cvt_pk_bf16_f32 v140, v140, v141
	v_cvt_pk_bf16_f32 v141, v142, v143
	global_store_dwordx2 v148, v[140:141], s[10:11] offset:1536
	s_add_u32 s10, s10, s18
	s_addc_u32 s11, s11, 0
	global_load_dwordx4 v[80:83], v211, s[8:9] offset:0
	global_load_dwordx4 v[84:87], v211, s[8:9] offset:1024
	global_load_dwordx4 v[88:91], v211, s[8:9] offset:2048
	global_load_dwordx4 v[92:95], v211, s[8:9] offset:3072
	s_add_u32 s8, s8, s16
	s_addc_u32 s9, s9, 0
	global_load_dwordx4 v[96:99], v211, s[8:9] offset:0
	global_load_dwordx4 v[100:103], v211, s[8:9] offset:1024
	global_load_dwordx4 v[104:107], v211, s[8:9] offset:2048
	global_load_dwordx4 v[108:111], v211, s[8:9] offset:3072
	s_add_u32 s8, s8, s16
	s_addc_u32 s9, s9, 0
	global_load_dwordx4 v[112:115], v211, s[8:9] offset:0
	global_load_dwordx4 v[116:119], v211, s[8:9] offset:1024
	global_load_dwordx4 v[120:123], v211, s[8:9] offset:2048
	global_load_dwordx4 v[124:127], v211, s[8:9] offset:3072
	s_add_u32 s8, s8, s16
	s_addc_u32 s9, s9, 0
	global_load_dwordx4 v[128:131], v211, s[8:9] offset:0
	global_load_dwordx4 v[132:135], v211, s[8:9] offset:1024
	global_load_dwordx4 v[136:139], v211, s[8:9] offset:2048
	global_load_dwordx4 v[140:143], v211, s[8:9] offset:3072
	s_add_u32 s8, s8, s16
	s_addc_u32 s9, s9, 0
	s_waitcnt vmcnt(0)
	v_mul_f32_e32 v144, v80, v80
	v_fmac_f32_e32 v144, v81, v81
	v_fmac_f32_e32 v144, v82, v82
	v_fmac_f32_e32 v144, v83, v83
	v_fmac_f32_e32 v144, v84, v84
	v_fmac_f32_e32 v144, v85, v85
	v_fmac_f32_e32 v144, v86, v86
	v_fmac_f32_e32 v144, v87, v87
	v_fmac_f32_e32 v144, v88, v88
	v_fmac_f32_e32 v144, v89, v89
	v_fmac_f32_e32 v144, v90, v90
	v_fmac_f32_e32 v144, v91, v91
	v_fmac_f32_e32 v144, v92, v92
	v_fmac_f32_e32 v144, v93, v93
	v_fmac_f32_e32 v144, v94, v94
	v_fmac_f32_e32 v144, v95, v95
	s_nop 1
	v_add_f32_dpp v144, v144, v144 quad_perm:[1,0,3,2] row_mask:0xf bank_mask:0xf
	s_nop 1
	v_add_f32_dpp v144, v144, v144 quad_perm:[2,3,0,1] row_mask:0xf bank_mask:0xf
	s_nop 1
	v_add_f32_dpp v144, v144, v144 row_half_mirror row_mask:0xf bank_mask:0xf
	s_nop 1
	v_add_f32_dpp v144, v144, v144 row_mirror row_mask:0xf bank_mask:0xf
	v_mov_b32_e32 v145, v144
	s_nop 1
	v_permlane16_swap_b32_e32 v144, v145
	v_add_f32_e32 v144, v144, v145
	v_mov_b32_e32 v145, v144
	s_nop 1
	v_permlane32_swap_b32_e32 v144, v145
	v_add_f32_e32 v144, v144, v145
	v_fmamk_f32 v144, v144, 0x3a800000, v147
	v_mul_f32_e32 v145, 0x4b800000, v144
	v_cmp_gt_f32_e32 vcc, s19, v144
	s_nop 1
	v_cndmask_b32_e32 v144, v144, v145, vcc
	v_rsq_f32_e32 v144, v144
	s_nop 0
	v_mul_f32_e32 v145, 0x45800000, v144
	v_cndmask_b32_e32 v144, v144, v145, vcc
	v_mul_f32_e32 v80, v80, v144
	v_mul_f32_e32 v80, v64, v80
	v_mul_f32_e32 v81, v81, v144
	v_mul_f32_e32 v81, v65, v81
	v_mul_f32_e32 v82, v82, v144
	v_mul_f32_e32 v82, v66, v82
	v_mul_f32_e32 v83, v83, v144
	v_mul_f32_e32 v83, v67, v83
	v_cvt_pk_bf16_f32 v80, v80, v81
	v_cvt_pk_bf16_f32 v81, v82, v83
	global_store_dwordx2 v148, v[80:81], s[10:11] offset:0
	v_mul_f32_e32 v84, v84, v144
	v_mul_f32_e32 v84, v68, v84
	v_mul_f32_e32 v85, v85, v144
	v_mul_f32_e32 v85, v69, v85
	v_mul_f32_e32 v86, v86, v144
	v_mul_f32_e32 v86, v70, v86
	v_mul_f32_e32 v87, v87, v144
	v_mul_f32_e32 v87, v71, v87
	v_cvt_pk_bf16_f32 v84, v84, v85
	v_cvt_pk_bf16_f32 v85, v86, v87
	global_store_dwordx2 v148, v[84:85], s[10:11] offset:512
	v_mul_f32_e32 v88, v88, v144
	v_mul_f32_e32 v88, v72, v88
	v_mul_f32_e32 v89, v89, v144
	v_mul_f32_e32 v89, v73, v89
	v_mul_f32_e32 v90, v90, v144
	v_mul_f32_e32 v90, v74, v90
	v_mul_f32_e32 v91, v91, v144
	v_mul_f32_e32 v91, v75, v91
	v_cvt_pk_bf16_f32 v88, v88, v89
	v_cvt_pk_bf16_f32 v89, v90, v91
	global_store_dwordx2 v148, v[88:89], s[10:11] offset:1024
	v_mul_f32_e32 v92, v92, v144
	v_mul_f32_e32 v92, v76, v92
	v_mul_f32_e32 v93, v93, v144
	v_mul_f32_e32 v93, v77, v93
	v_mul_f32_e32 v94, v94, v144
	v_mul_f32_e32 v94, v78, v94
	v_mul_f32_e32 v95, v95, v144
	v_mul_f32_e32 v95, v79, v95
	v_cvt_pk_bf16_f32 v92, v92, v93
	v_cvt_pk_bf16_f32 v93, v94, v95
	global_store_dwordx2 v148, v[92:93], s[10:11] offset:1536
	s_add_u32 s10, s10, s18
	s_addc_u32 s11, s11, 0
	v_mul_f32_e32 v144, v96, v96
	v_fmac_f32_e32 v144, v97, v97
	v_fmac_f32_e32 v144, v98, v98
	v_fmac_f32_e32 v144, v99, v99
	v_fmac_f32_e32 v144, v100, v100
	v_fmac_f32_e32 v144, v101, v101
	v_fmac_f32_e32 v144, v102, v102
	v_fmac_f32_e32 v144, v103, v103
	v_fmac_f32_e32 v144, v104, v104
	v_fmac_f32_e32 v144, v105, v105
	v_fmac_f32_e32 v144, v106, v106
	v_fmac_f32_e32 v144, v107, v107
	v_fmac_f32_e32 v144, v108, v108
	v_fmac_f32_e32 v144, v109, v109
	v_fmac_f32_e32 v144, v110, v110
	v_fmac_f32_e32 v144, v111, v111
	s_nop 1
	v_add_f32_dpp v144, v144, v144 quad_perm:[1,0,3,2] row_mask:0xf bank_mask:0xf
	s_nop 1
	v_add_f32_dpp v144, v144, v144 quad_perm:[2,3,0,1] row_mask:0xf bank_mask:0xf
	s_nop 1
	v_add_f32_dpp v144, v144, v144 row_half_mirror row_mask:0xf bank_mask:0xf
	s_nop 1
	v_add_f32_dpp v144, v144, v144 row_mirror row_mask:0xf bank_mask:0xf
	v_mov_b32_e32 v145, v144
	s_nop 1
	v_permlane16_swap_b32_e32 v144, v145
	v_add_f32_e32 v144, v144, v145
	v_mov_b32_e32 v145, v144
	s_nop 1
	v_permlane32_swap_b32_e32 v144, v145
	v_add_f32_e32 v144, v144, v145
	v_fmamk_f32 v144, v144, 0x3a800000, v147
	v_mul_f32_e32 v145, 0x4b800000, v144
	v_cmp_gt_f32_e32 vcc, s19, v144
	s_nop 1
	v_cndmask_b32_e32 v144, v144, v145, vcc
	v_rsq_f32_e32 v144, v144
	s_nop 0
	v_mul_f32_e32 v145, 0x45800000, v144
	v_cndmask_b32_e32 v144, v144, v145, vcc
	v_mul_f32_e32 v96, v96, v144
	v_mul_f32_e32 v96, v64, v96
	v_mul_f32_e32 v97, v97, v144
	v_mul_f32_e32 v97, v65, v97
	v_mul_f32_e32 v98, v98, v144
	v_mul_f32_e32 v98, v66, v98
	v_mul_f32_e32 v99, v99, v144
	v_mul_f32_e32 v99, v67, v99
	v_cvt_pk_bf16_f32 v96, v96, v97
	v_cvt_pk_bf16_f32 v97, v98, v99
	global_store_dwordx2 v148, v[96:97], s[10:11] offset:0
	v_mul_f32_e32 v100, v100, v144
	v_mul_f32_e32 v100, v68, v100
	v_mul_f32_e32 v101, v101, v144
	v_mul_f32_e32 v101, v69, v101
	v_mul_f32_e32 v102, v102, v144
	v_mul_f32_e32 v102, v70, v102
	v_mul_f32_e32 v103, v103, v144
	v_mul_f32_e32 v103, v71, v103
	v_cvt_pk_bf16_f32 v100, v100, v101
	v_cvt_pk_bf16_f32 v101, v102, v103
	global_store_dwordx2 v148, v[100:101], s[10:11] offset:512
	v_mul_f32_e32 v104, v104, v144
	v_mul_f32_e32 v104, v72, v104
	v_mul_f32_e32 v105, v105, v144
	v_mul_f32_e32 v105, v73, v105
	v_mul_f32_e32 v106, v106, v144
	v_mul_f32_e32 v106, v74, v106
	v_mul_f32_e32 v107, v107, v144
	v_mul_f32_e32 v107, v75, v107
	v_cvt_pk_bf16_f32 v104, v104, v105
	v_cvt_pk_bf16_f32 v105, v106, v107
	global_store_dwordx2 v148, v[104:105], s[10:11] offset:1024
	v_mul_f32_e32 v108, v108, v144
	v_mul_f32_e32 v108, v76, v108
	v_mul_f32_e32 v109, v109, v144
	v_mul_f32_e32 v109, v77, v109
	v_mul_f32_e32 v110, v110, v144
	v_mul_f32_e32 v110, v78, v110
	v_mul_f32_e32 v111, v111, v144
	v_mul_f32_e32 v111, v79, v111
	v_cvt_pk_bf16_f32 v108, v108, v109
	v_cvt_pk_bf16_f32 v109, v110, v111
	global_store_dwordx2 v148, v[108:109], s[10:11] offset:1536
	s_add_u32 s10, s10, s18
	s_addc_u32 s11, s11, 0
	v_mul_f32_e32 v144, v112, v112
	v_fmac_f32_e32 v144, v113, v113
	v_fmac_f32_e32 v144, v114, v114
	v_fmac_f32_e32 v144, v115, v115
	v_fmac_f32_e32 v144, v116, v116
	v_fmac_f32_e32 v144, v117, v117
	v_fmac_f32_e32 v144, v118, v118
	v_fmac_f32_e32 v144, v119, v119
	v_fmac_f32_e32 v144, v120, v120
	v_fmac_f32_e32 v144, v121, v121
	v_fmac_f32_e32 v144, v122, v122
	v_fmac_f32_e32 v144, v123, v123
	v_fmac_f32_e32 v144, v124, v124
	v_fmac_f32_e32 v144, v125, v125
	v_fmac_f32_e32 v144, v126, v126
	v_fmac_f32_e32 v144, v127, v127
	s_nop 1
	v_add_f32_dpp v144, v144, v144 quad_perm:[1,0,3,2] row_mask:0xf bank_mask:0xf
	s_nop 1
	v_add_f32_dpp v144, v144, v144 quad_perm:[2,3,0,1] row_mask:0xf bank_mask:0xf
	s_nop 1
	v_add_f32_dpp v144, v144, v144 row_half_mirror row_mask:0xf bank_mask:0xf
	s_nop 1
	v_add_f32_dpp v144, v144, v144 row_mirror row_mask:0xf bank_mask:0xf
	v_mov_b32_e32 v145, v144
	s_nop 1
	v_permlane16_swap_b32_e32 v144, v145
	v_add_f32_e32 v144, v144, v145
	v_mov_b32_e32 v145, v144
	s_nop 1
	v_permlane32_swap_b32_e32 v144, v145
	v_add_f32_e32 v144, v144, v145
	v_fmamk_f32 v144, v144, 0x3a800000, v147
	v_mul_f32_e32 v145, 0x4b800000, v144
	v_cmp_gt_f32_e32 vcc, s19, v144
	s_nop 1
	v_cndmask_b32_e32 v144, v144, v145, vcc
	v_rsq_f32_e32 v144, v144
	s_nop 0
	v_mul_f32_e32 v145, 0x45800000, v144
	v_cndmask_b32_e32 v144, v144, v145, vcc
	v_mul_f32_e32 v112, v112, v144
	v_mul_f32_e32 v112, v64, v112
	v_mul_f32_e32 v113, v113, v144
	v_mul_f32_e32 v113, v65, v113
	v_mul_f32_e32 v114, v114, v144
	v_mul_f32_e32 v114, v66, v114
	v_mul_f32_e32 v115, v115, v144
	v_mul_f32_e32 v115, v67, v115
	v_cvt_pk_bf16_f32 v112, v112, v113
	v_cvt_pk_bf16_f32 v113, v114, v115
	global_store_dwordx2 v148, v[112:113], s[10:11] offset:0
	v_mul_f32_e32 v116, v116, v144
	v_mul_f32_e32 v116, v68, v116
	v_mul_f32_e32 v117, v117, v144
	v_mul_f32_e32 v117, v69, v117
	v_mul_f32_e32 v118, v118, v144
	v_mul_f32_e32 v118, v70, v118
	v_mul_f32_e32 v119, v119, v144
	v_mul_f32_e32 v119, v71, v119
	v_cvt_pk_bf16_f32 v116, v116, v117
	v_cvt_pk_bf16_f32 v117, v118, v119
	global_store_dwordx2 v148, v[116:117], s[10:11] offset:512
	v_mul_f32_e32 v120, v120, v144
	v_mul_f32_e32 v120, v72, v120
	v_mul_f32_e32 v121, v121, v144
	v_mul_f32_e32 v121, v73, v121
	v_mul_f32_e32 v122, v122, v144
	v_mul_f32_e32 v122, v74, v122
	v_mul_f32_e32 v123, v123, v144
	v_mul_f32_e32 v123, v75, v123
	v_cvt_pk_bf16_f32 v120, v120, v121
	v_cvt_pk_bf16_f32 v121, v122, v123
	global_store_dwordx2 v148, v[120:121], s[10:11] offset:1024
	v_mul_f32_e32 v124, v124, v144
	v_mul_f32_e32 v124, v76, v124
	v_mul_f32_e32 v125, v125, v144
	v_mul_f32_e32 v125, v77, v125
	v_mul_f32_e32 v126, v126, v144
	v_mul_f32_e32 v126, v78, v126
	v_mul_f32_e32 v127, v127, v144
	v_mul_f32_e32 v127, v79, v127
	v_cvt_pk_bf16_f32 v124, v124, v125
	v_cvt_pk_bf16_f32 v125, v126, v127
	global_store_dwordx2 v148, v[124:125], s[10:11] offset:1536
	s_add_u32 s10, s10, s18
	s_addc_u32 s11, s11, 0
	v_mul_f32_e32 v144, v128, v128
	v_fmac_f32_e32 v144, v129, v129
	v_fmac_f32_e32 v144, v130, v130
	v_fmac_f32_e32 v144, v131, v131
	v_fmac_f32_e32 v144, v132, v132
	v_fmac_f32_e32 v144, v133, v133
	v_fmac_f32_e32 v144, v134, v134
	v_fmac_f32_e32 v144, v135, v135
	v_fmac_f32_e32 v144, v136, v136
	v_fmac_f32_e32 v144, v137, v137
	v_fmac_f32_e32 v144, v138, v138
	v_fmac_f32_e32 v144, v139, v139
	v_fmac_f32_e32 v144, v140, v140
	v_fmac_f32_e32 v144, v141, v141
	v_fmac_f32_e32 v144, v142, v142
	v_fmac_f32_e32 v144, v143, v143
	s_nop 1
	v_add_f32_dpp v144, v144, v144 quad_perm:[1,0,3,2] row_mask:0xf bank_mask:0xf
	s_nop 1
	v_add_f32_dpp v144, v144, v144 quad_perm:[2,3,0,1] row_mask:0xf bank_mask:0xf
	s_nop 1
	v_add_f32_dpp v144, v144, v144 row_half_mirror row_mask:0xf bank_mask:0xf
	s_nop 1
	v_add_f32_dpp v144, v144, v144 row_mirror row_mask:0xf bank_mask:0xf
	v_mov_b32_e32 v145, v144
	s_nop 1
	v_permlane16_swap_b32_e32 v144, v145
	v_add_f32_e32 v144, v144, v145
	v_mov_b32_e32 v145, v144
	s_nop 1
	v_permlane32_swap_b32_e32 v144, v145
	v_add_f32_e32 v144, v144, v145
	v_fmamk_f32 v144, v144, 0x3a800000, v147
	v_mul_f32_e32 v145, 0x4b800000, v144
	v_cmp_gt_f32_e32 vcc, s19, v144
	s_nop 1
	v_cndmask_b32_e32 v144, v144, v145, vcc
	v_rsq_f32_e32 v144, v144
	s_nop 0
	v_mul_f32_e32 v145, 0x45800000, v144
	v_cndmask_b32_e32 v144, v144, v145, vcc
	v_mul_f32_e32 v128, v128, v144
	v_mul_f32_e32 v128, v64, v128
	v_mul_f32_e32 v129, v129, v144
	v_mul_f32_e32 v129, v65, v129
	v_mul_f32_e32 v130, v130, v144
	v_mul_f32_e32 v130, v66, v130
	v_mul_f32_e32 v131, v131, v144
	v_mul_f32_e32 v131, v67, v131
	v_cvt_pk_bf16_f32 v128, v128, v129
	v_cvt_pk_bf16_f32 v129, v130, v131
	global_store_dwordx2 v148, v[128:129], s[10:11] offset:0
	v_mul_f32_e32 v132, v132, v144
	v_mul_f32_e32 v132, v68, v132
	v_mul_f32_e32 v133, v133, v144
	v_mul_f32_e32 v133, v69, v133
	v_mul_f32_e32 v134, v134, v144
	v_mul_f32_e32 v134, v70, v134
	v_mul_f32_e32 v135, v135, v144
	v_mul_f32_e32 v135, v71, v135
	v_cvt_pk_bf16_f32 v132, v132, v133
	v_cvt_pk_bf16_f32 v133, v134, v135
	global_store_dwordx2 v148, v[132:133], s[10:11] offset:512
	v_mul_f32_e32 v136, v136, v144
	v_mul_f32_e32 v136, v72, v136
	v_mul_f32_e32 v137, v137, v144
	v_mul_f32_e32 v137, v73, v137
	v_mul_f32_e32 v138, v138, v144
	v_mul_f32_e32 v138, v74, v138
	v_mul_f32_e32 v139, v139, v144
	v_mul_f32_e32 v139, v75, v139
	v_cvt_pk_bf16_f32 v136, v136, v137
	v_cvt_pk_bf16_f32 v137, v138, v139
	global_store_dwordx2 v148, v[136:137], s[10:11] offset:1024
	v_mul_f32_e32 v140, v140, v144
	v_mul_f32_e32 v140, v76, v140
	v_mul_f32_e32 v141, v141, v144
	v_mul_f32_e32 v141, v77, v141
	v_mul_f32_e32 v142, v142, v144
	v_mul_f32_e32 v142, v78, v142
	v_mul_f32_e32 v143, v143, v144
	v_mul_f32_e32 v143, v79, v143
	v_cvt_pk_bf16_f32 v140, v140, v141
	v_cvt_pk_bf16_f32 v141, v142, v143
	global_store_dwordx2 v148, v[140:141], s[10:11] offset:1536
	s_add_u32 s10, s10, s18
	s_addc_u32 s11, s11, 0
	global_load_dwordx4 v[80:83], v211, s[8:9] offset:0
	global_load_dwordx4 v[84:87], v211, s[8:9] offset:1024
	global_load_dwordx4 v[88:91], v211, s[8:9] offset:2048
	global_load_dwordx4 v[92:95], v211, s[8:9] offset:3072
	s_add_u32 s8, s8, s16
	s_addc_u32 s9, s9, 0
	global_load_dwordx4 v[96:99], v211, s[8:9] offset:0
	global_load_dwordx4 v[100:103], v211, s[8:9] offset:1024
	global_load_dwordx4 v[104:107], v211, s[8:9] offset:2048
	global_load_dwordx4 v[108:111], v211, s[8:9] offset:3072
	s_add_u32 s8, s8, s16
	s_addc_u32 s9, s9, 0
	global_load_dwordx4 v[112:115], v211, s[8:9] offset:0
	global_load_dwordx4 v[116:119], v211, s[8:9] offset:1024
	global_load_dwordx4 v[120:123], v211, s[8:9] offset:2048
	global_load_dwordx4 v[124:127], v211, s[8:9] offset:3072
	s_add_u32 s8, s8, s16
	s_addc_u32 s9, s9, 0
	global_load_dwordx4 v[128:131], v211, s[8:9] offset:0
	global_load_dwordx4 v[132:135], v211, s[8:9] offset:1024
	global_load_dwordx4 v[136:139], v211, s[8:9] offset:2048
	global_load_dwordx4 v[140:143], v211, s[8:9] offset:3072
	s_add_u32 s8, s8, s16
	s_addc_u32 s9, s9, 0
	s_waitcnt vmcnt(0)
	v_mul_f32_e32 v144, v80, v80
	v_fmac_f32_e32 v144, v81, v81
	v_fmac_f32_e32 v144, v82, v82
	v_fmac_f32_e32 v144, v83, v83
	v_fmac_f32_e32 v144, v84, v84
	v_fmac_f32_e32 v144, v85, v85
	v_fmac_f32_e32 v144, v86, v86
	v_fmac_f32_e32 v144, v87, v87
	v_fmac_f32_e32 v144, v88, v88
	v_fmac_f32_e32 v144, v89, v89
	v_fmac_f32_e32 v144, v90, v90
	v_fmac_f32_e32 v144, v91, v91
	v_fmac_f32_e32 v144, v92, v92
	v_fmac_f32_e32 v144, v93, v93
	v_fmac_f32_e32 v144, v94, v94
	v_fmac_f32_e32 v144, v95, v95
	s_nop 1
	v_add_f32_dpp v144, v144, v144 quad_perm:[1,0,3,2] row_mask:0xf bank_mask:0xf
	s_nop 1
	v_add_f32_dpp v144, v144, v144 quad_perm:[2,3,0,1] row_mask:0xf bank_mask:0xf
	s_nop 1
	v_add_f32_dpp v144, v144, v144 row_half_mirror row_mask:0xf bank_mask:0xf
	s_nop 1
	v_add_f32_dpp v144, v144, v144 row_mirror row_mask:0xf bank_mask:0xf
	v_mov_b32_e32 v145, v144
	s_nop 1
	v_permlane16_swap_b32_e32 v144, v145
	v_add_f32_e32 v144, v144, v145
	v_mov_b32_e32 v145, v144
	s_nop 1
	v_permlane32_swap_b32_e32 v144, v145
	v_add_f32_e32 v144, v144, v145
	v_fmamk_f32 v144, v144, 0x3a800000, v147
	v_mul_f32_e32 v145, 0x4b800000, v144
	v_cmp_gt_f32_e32 vcc, s19, v144
	s_nop 1
	v_cndmask_b32_e32 v144, v144, v145, vcc
	v_rsq_f32_e32 v144, v144
	s_nop 0
	v_mul_f32_e32 v145, 0x45800000, v144
	v_cndmask_b32_e32 v144, v144, v145, vcc
	v_mul_f32_e32 v80, v80, v144
	v_mul_f32_e32 v80, v64, v80
	v_mul_f32_e32 v81, v81, v144
	v_mul_f32_e32 v81, v65, v81
	v_mul_f32_e32 v82, v82, v144
	v_mul_f32_e32 v82, v66, v82
	v_mul_f32_e32 v83, v83, v144
	v_mul_f32_e32 v83, v67, v83
	v_cvt_pk_bf16_f32 v80, v80, v81
	v_cvt_pk_bf16_f32 v81, v82, v83
	global_store_dwordx2 v148, v[80:81], s[10:11] offset:0
	v_mul_f32_e32 v84, v84, v144
	v_mul_f32_e32 v84, v68, v84
	v_mul_f32_e32 v85, v85, v144
	v_mul_f32_e32 v85, v69, v85
	v_mul_f32_e32 v86, v86, v144
	v_mul_f32_e32 v86, v70, v86
	v_mul_f32_e32 v87, v87, v144
	v_mul_f32_e32 v87, v71, v87
	v_cvt_pk_bf16_f32 v84, v84, v85
	v_cvt_pk_bf16_f32 v85, v86, v87
	global_store_dwordx2 v148, v[84:85], s[10:11] offset:512
	v_mul_f32_e32 v88, v88, v144
	v_mul_f32_e32 v88, v72, v88
	v_mul_f32_e32 v89, v89, v144
	v_mul_f32_e32 v89, v73, v89
	v_mul_f32_e32 v90, v90, v144
	v_mul_f32_e32 v90, v74, v90
	v_mul_f32_e32 v91, v91, v144
	v_mul_f32_e32 v91, v75, v91
	v_cvt_pk_bf16_f32 v88, v88, v89
	v_cvt_pk_bf16_f32 v89, v90, v91
	global_store_dwordx2 v148, v[88:89], s[10:11] offset:1024
	v_mul_f32_e32 v92, v92, v144
	v_mul_f32_e32 v92, v76, v92
	v_mul_f32_e32 v93, v93, v144
	v_mul_f32_e32 v93, v77, v93
	v_mul_f32_e32 v94, v94, v144
	v_mul_f32_e32 v94, v78, v94
	v_mul_f32_e32 v95, v95, v144
	v_mul_f32_e32 v95, v79, v95
	v_cvt_pk_bf16_f32 v92, v92, v93
	v_cvt_pk_bf16_f32 v93, v94, v95
	global_store_dwordx2 v148, v[92:93], s[10:11] offset:1536
	s_add_u32 s10, s10, s18
	s_addc_u32 s11, s11, 0
	v_mul_f32_e32 v144, v96, v96
	v_fmac_f32_e32 v144, v97, v97
	v_fmac_f32_e32 v144, v98, v98
	v_fmac_f32_e32 v144, v99, v99
	v_fmac_f32_e32 v144, v100, v100
	v_fmac_f32_e32 v144, v101, v101
	v_fmac_f32_e32 v144, v102, v102
	v_fmac_f32_e32 v144, v103, v103
	v_fmac_f32_e32 v144, v104, v104
	v_fmac_f32_e32 v144, v105, v105
	v_fmac_f32_e32 v144, v106, v106
	v_fmac_f32_e32 v144, v107, v107
	v_fmac_f32_e32 v144, v108, v108
	v_fmac_f32_e32 v144, v109, v109
	v_fmac_f32_e32 v144, v110, v110
	v_fmac_f32_e32 v144, v111, v111
	s_nop 1
	v_add_f32_dpp v144, v144, v144 quad_perm:[1,0,3,2] row_mask:0xf bank_mask:0xf
	s_nop 1
	v_add_f32_dpp v144, v144, v144 quad_perm:[2,3,0,1] row_mask:0xf bank_mask:0xf
	s_nop 1
	v_add_f32_dpp v144, v144, v144 row_half_mirror row_mask:0xf bank_mask:0xf
	s_nop 1
	v_add_f32_dpp v144, v144, v144 row_mirror row_mask:0xf bank_mask:0xf
	v_mov_b32_e32 v145, v144
	s_nop 1
	v_permlane16_swap_b32_e32 v144, v145
	v_add_f32_e32 v144, v144, v145
	v_mov_b32_e32 v145, v144
	s_nop 1
	v_permlane32_swap_b32_e32 v144, v145
	v_add_f32_e32 v144, v144, v145
	v_fmamk_f32 v144, v144, 0x3a800000, v147
	v_mul_f32_e32 v145, 0x4b800000, v144
	v_cmp_gt_f32_e32 vcc, s19, v144
	s_nop 1
	v_cndmask_b32_e32 v144, v144, v145, vcc
	v_rsq_f32_e32 v144, v144
	s_nop 0
	v_mul_f32_e32 v145, 0x45800000, v144
	v_cndmask_b32_e32 v144, v144, v145, vcc
	v_mul_f32_e32 v96, v96, v144
	v_mul_f32_e32 v96, v64, v96
	v_mul_f32_e32 v97, v97, v144
	v_mul_f32_e32 v97, v65, v97
	v_mul_f32_e32 v98, v98, v144
	v_mul_f32_e32 v98, v66, v98
	v_mul_f32_e32 v99, v99, v144
	v_mul_f32_e32 v99, v67, v99
	v_cvt_pk_bf16_f32 v96, v96, v97
	v_cvt_pk_bf16_f32 v97, v98, v99
	global_store_dwordx2 v148, v[96:97], s[10:11] offset:0
	v_mul_f32_e32 v100, v100, v144
	v_mul_f32_e32 v100, v68, v100
	v_mul_f32_e32 v101, v101, v144
	v_mul_f32_e32 v101, v69, v101
	v_mul_f32_e32 v102, v102, v144
	v_mul_f32_e32 v102, v70, v102
	v_mul_f32_e32 v103, v103, v144
	v_mul_f32_e32 v103, v71, v103
	v_cvt_pk_bf16_f32 v100, v100, v101
	v_cvt_pk_bf16_f32 v101, v102, v103
	global_store_dwordx2 v148, v[100:101], s[10:11] offset:512
	v_mul_f32_e32 v104, v104, v144
	v_mul_f32_e32 v104, v72, v104
	v_mul_f32_e32 v105, v105, v144
	v_mul_f32_e32 v105, v73, v105
	v_mul_f32_e32 v106, v106, v144
	v_mul_f32_e32 v106, v74, v106
	v_mul_f32_e32 v107, v107, v144
	v_mul_f32_e32 v107, v75, v107
	v_cvt_pk_bf16_f32 v104, v104, v105
	v_cvt_pk_bf16_f32 v105, v106, v107
	global_store_dwordx2 v148, v[104:105], s[10:11] offset:1024
	v_mul_f32_e32 v108, v108, v144
	v_mul_f32_e32 v108, v76, v108
	v_mul_f32_e32 v109, v109, v144
	v_mul_f32_e32 v109, v77, v109
	v_mul_f32_e32 v110, v110, v144
	v_mul_f32_e32 v110, v78, v110
	v_mul_f32_e32 v111, v111, v144
	v_mul_f32_e32 v111, v79, v111
	v_cvt_pk_bf16_f32 v108, v108, v109
	v_cvt_pk_bf16_f32 v109, v110, v111
	global_store_dwordx2 v148, v[108:109], s[10:11] offset:1536
	s_add_u32 s10, s10, s18
	s_addc_u32 s11, s11, 0
	v_mul_f32_e32 v144, v112, v112
	v_fmac_f32_e32 v144, v113, v113
	v_fmac_f32_e32 v144, v114, v114
	v_fmac_f32_e32 v144, v115, v115
	v_fmac_f32_e32 v144, v116, v116
	v_fmac_f32_e32 v144, v117, v117
	v_fmac_f32_e32 v144, v118, v118
	v_fmac_f32_e32 v144, v119, v119
	v_fmac_f32_e32 v144, v120, v120
	v_fmac_f32_e32 v144, v121, v121
	v_fmac_f32_e32 v144, v122, v122
	v_fmac_f32_e32 v144, v123, v123
	v_fmac_f32_e32 v144, v124, v124
	v_fmac_f32_e32 v144, v125, v125
	v_fmac_f32_e32 v144, v126, v126
	v_fmac_f32_e32 v144, v127, v127
	s_nop 1
	v_add_f32_dpp v144, v144, v144 quad_perm:[1,0,3,2] row_mask:0xf bank_mask:0xf
	s_nop 1
	v_add_f32_dpp v144, v144, v144 quad_perm:[2,3,0,1] row_mask:0xf bank_mask:0xf
	s_nop 1
	v_add_f32_dpp v144, v144, v144 row_half_mirror row_mask:0xf bank_mask:0xf
	s_nop 1
	v_add_f32_dpp v144, v144, v144 row_mirror row_mask:0xf bank_mask:0xf
	v_mov_b32_e32 v145, v144
	s_nop 1
	v_permlane16_swap_b32_e32 v144, v145
	v_add_f32_e32 v144, v144, v145
	v_mov_b32_e32 v145, v144
	s_nop 1
	v_permlane32_swap_b32_e32 v144, v145
	v_add_f32_e32 v144, v144, v145
	v_fmamk_f32 v144, v144, 0x3a800000, v147
	v_mul_f32_e32 v145, 0x4b800000, v144
	v_cmp_gt_f32_e32 vcc, s19, v144
	s_nop 1
	v_cndmask_b32_e32 v144, v144, v145, vcc
	v_rsq_f32_e32 v144, v144
	s_nop 0
	v_mul_f32_e32 v145, 0x45800000, v144
	v_cndmask_b32_e32 v144, v144, v145, vcc
	v_mul_f32_e32 v112, v112, v144
	v_mul_f32_e32 v112, v64, v112
	v_mul_f32_e32 v113, v113, v144
	v_mul_f32_e32 v113, v65, v113
	v_mul_f32_e32 v114, v114, v144
	v_mul_f32_e32 v114, v66, v114
	v_mul_f32_e32 v115, v115, v144
	v_mul_f32_e32 v115, v67, v115
	v_cvt_pk_bf16_f32 v112, v112, v113
	v_cvt_pk_bf16_f32 v113, v114, v115
	global_store_dwordx2 v148, v[112:113], s[10:11] offset:0
	v_mul_f32_e32 v116, v116, v144
	v_mul_f32_e32 v116, v68, v116
	v_mul_f32_e32 v117, v117, v144
	v_mul_f32_e32 v117, v69, v117
	v_mul_f32_e32 v118, v118, v144
	v_mul_f32_e32 v118, v70, v118
	v_mul_f32_e32 v119, v119, v144
	v_mul_f32_e32 v119, v71, v119
	v_cvt_pk_bf16_f32 v116, v116, v117
	v_cvt_pk_bf16_f32 v117, v118, v119
	global_store_dwordx2 v148, v[116:117], s[10:11] offset:512
	v_mul_f32_e32 v120, v120, v144
	v_mul_f32_e32 v120, v72, v120
	v_mul_f32_e32 v121, v121, v144
	v_mul_f32_e32 v121, v73, v121
	v_mul_f32_e32 v122, v122, v144
	v_mul_f32_e32 v122, v74, v122
	v_mul_f32_e32 v123, v123, v144
	v_mul_f32_e32 v123, v75, v123
	v_cvt_pk_bf16_f32 v120, v120, v121
	v_cvt_pk_bf16_f32 v121, v122, v123
	global_store_dwordx2 v148, v[120:121], s[10:11] offset:1024
	v_mul_f32_e32 v124, v124, v144
	v_mul_f32_e32 v124, v76, v124
	v_mul_f32_e32 v125, v125, v144
	v_mul_f32_e32 v125, v77, v125
	v_mul_f32_e32 v126, v126, v144
	v_mul_f32_e32 v126, v78, v126
	v_mul_f32_e32 v127, v127, v144
	v_mul_f32_e32 v127, v79, v127
	v_cvt_pk_bf16_f32 v124, v124, v125
	v_cvt_pk_bf16_f32 v125, v126, v127
	global_store_dwordx2 v148, v[124:125], s[10:11] offset:1536
	s_add_u32 s10, s10, s18
	s_addc_u32 s11, s11, 0
	v_mul_f32_e32 v144, v128, v128
	v_fmac_f32_e32 v144, v129, v129
	v_fmac_f32_e32 v144, v130, v130
	v_fmac_f32_e32 v144, v131, v131
	v_fmac_f32_e32 v144, v132, v132
	v_fmac_f32_e32 v144, v133, v133
	v_fmac_f32_e32 v144, v134, v134
	v_fmac_f32_e32 v144, v135, v135
	v_fmac_f32_e32 v144, v136, v136
	v_fmac_f32_e32 v144, v137, v137
	v_fmac_f32_e32 v144, v138, v138
	v_fmac_f32_e32 v144, v139, v139
	v_fmac_f32_e32 v144, v140, v140
	v_fmac_f32_e32 v144, v141, v141
	v_fmac_f32_e32 v144, v142, v142
	v_fmac_f32_e32 v144, v143, v143
	s_nop 1
	v_add_f32_dpp v144, v144, v144 quad_perm:[1,0,3,2] row_mask:0xf bank_mask:0xf
	s_nop 1
	v_add_f32_dpp v144, v144, v144 quad_perm:[2,3,0,1] row_mask:0xf bank_mask:0xf
	s_nop 1
	v_add_f32_dpp v144, v144, v144 row_half_mirror row_mask:0xf bank_mask:0xf
	s_nop 1
	v_add_f32_dpp v144, v144, v144 row_mirror row_mask:0xf bank_mask:0xf
	v_mov_b32_e32 v145, v144
	s_nop 1
	v_permlane16_swap_b32_e32 v144, v145
	v_add_f32_e32 v144, v144, v145
	v_mov_b32_e32 v145, v144
	s_nop 1
	v_permlane32_swap_b32_e32 v144, v145
	v_add_f32_e32 v144, v144, v145
	v_fmamk_f32 v144, v144, 0x3a800000, v147
	v_mul_f32_e32 v145, 0x4b800000, v144
	v_cmp_gt_f32_e32 vcc, s19, v144
	s_nop 1
	v_cndmask_b32_e32 v144, v144, v145, vcc
	v_rsq_f32_e32 v144, v144
	s_nop 0
	v_mul_f32_e32 v145, 0x45800000, v144
	v_cndmask_b32_e32 v144, v144, v145, vcc
	v_mul_f32_e32 v128, v128, v144
	v_mul_f32_e32 v128, v64, v128
	v_mul_f32_e32 v129, v129, v144
	v_mul_f32_e32 v129, v65, v129
	v_mul_f32_e32 v130, v130, v144
	v_mul_f32_e32 v130, v66, v130
	v_mul_f32_e32 v131, v131, v144
	v_mul_f32_e32 v131, v67, v131
	v_cvt_pk_bf16_f32 v128, v128, v129
	v_cvt_pk_bf16_f32 v129, v130, v131
	global_store_dwordx2 v148, v[128:129], s[10:11] offset:0
	v_mul_f32_e32 v132, v132, v144
	v_mul_f32_e32 v132, v68, v132
	v_mul_f32_e32 v133, v133, v144
	v_mul_f32_e32 v133, v69, v133
	v_mul_f32_e32 v134, v134, v144
	v_mul_f32_e32 v134, v70, v134
	v_mul_f32_e32 v135, v135, v144
	v_mul_f32_e32 v135, v71, v135
	v_cvt_pk_bf16_f32 v132, v132, v133
	v_cvt_pk_bf16_f32 v133, v134, v135
	global_store_dwordx2 v148, v[132:133], s[10:11] offset:512
	v_mul_f32_e32 v136, v136, v144
	v_mul_f32_e32 v136, v72, v136
	v_mul_f32_e32 v137, v137, v144
	v_mul_f32_e32 v137, v73, v137
	v_mul_f32_e32 v138, v138, v144
	v_mul_f32_e32 v138, v74, v138
	v_mul_f32_e32 v139, v139, v144
	v_mul_f32_e32 v139, v75, v139
	v_cvt_pk_bf16_f32 v136, v136, v137
	v_cvt_pk_bf16_f32 v137, v138, v139
	global_store_dwordx2 v148, v[136:137], s[10:11] offset:1024
	v_mul_f32_e32 v140, v140, v144
	v_mul_f32_e32 v140, v76, v140
	v_mul_f32_e32 v141, v141, v144
	v_mul_f32_e32 v141, v77, v141
	v_mul_f32_e32 v142, v142, v144
	v_mul_f32_e32 v142, v78, v142
	v_mul_f32_e32 v143, v143, v144
	v_mul_f32_e32 v143, v79, v143
	v_cvt_pk_bf16_f32 v140, v140, v141
	v_cvt_pk_bf16_f32 v141, v142, v143
	global_store_dwordx2 v148, v[140:141], s[10:11] offset:1536
	s_add_u32 s10, s10, s18
	s_addc_u32 s11, s11, 0
	s_waitcnt vmcnt(0)
	s_lshl_b32 s15, s92, 6
	s_add_u32 s101, s101, s15
	s_cmpk_lt_u32 s101, 0x8000
	s_cbranch_scc1 .Lgv0_chunk
	s_branch .LBB0_637

.Lgv1_chunk:
	s_movk_i32 s100, 0xc0
	s_lshl_b32 s16, s92, 14
	s_add_u32 s12, s26, 0xd800000
	s_addc_u32 s13, s27, 0
	s_lshl_b32 s15, s101, 9
	s_add_u32 s12, s12, s15
	s_addc_u32 s13, s13, 0
	s_lshl_b32 s18, s92, 11
	global_load_dword v64, v196, s[12:13]
	global_load_dword v65, v196, s[12:13] offset:256
	s_add_u32 s12, s12, s18
	s_addc_u32 s13, s13, 0
	global_load_dword v66, v196, s[12:13]
	global_load_dword v67, v196, s[12:13] offset:256
	s_add_u32 s12, s12, s18
	s_addc_u32 s13, s13, 0
	global_load_dword v68, v196, s[12:13]
	global_load_dword v69, v196, s[12:13] offset:256
	s_add_u32 s12, s12, s18
	s_addc_u32 s13, s13, 0
	global_load_dword v70, v196, s[12:13]
	global_load_dword v71, v196, s[12:13] offset:256
	s_add_u32 s12, s12, s18
	s_addc_u32 s13, s13, 0
	global_load_dword v72, v196, s[12:13]
	global_load_dword v73, v196, s[12:13] offset:256
	s_add_u32 s12, s12, s18
	s_addc_u32 s13, s13, 0
	global_load_dword v74, v196, s[12:13]
	global_load_dword v75, v196, s[12:13] offset:256
	s_add_u32 s12, s12, s18
	s_addc_u32 s13, s13, 0
	global_load_dword v76, v196, s[12:13]
	global_load_dword v77, v196, s[12:13] offset:256
	s_add_u32 s12, s12, s18
	s_addc_u32 s13, s13, 0
	global_load_dword v78, v196, s[12:13]
	global_load_dword v79, v196, s[12:13] offset:256
	s_add_u32 s12, s12, s18
	s_addc_u32 s13, s13, 0
	global_load_dword v80, v196, s[12:13]
	global_load_dword v81, v196, s[12:13] offset:256
	s_add_u32 s12, s12, s18
	s_addc_u32 s13, s13, 0
	global_load_dword v82, v196, s[12:13]
	global_load_dword v83, v196, s[12:13] offset:256
	s_add_u32 s12, s12, s18
	s_addc_u32 s13, s13, 0
	global_load_dword v84, v196, s[12:13]
	global_load_dword v85, v196, s[12:13] offset:256
	s_add_u32 s12, s12, s18
	s_addc_u32 s13, s13, 0
	global_load_dword v86, v196, s[12:13]
	global_load_dword v87, v196, s[12:13] offset:256
	s_add_u32 s12, s12, s18
	s_addc_u32 s13, s13, 0
	global_load_dword v88, v196, s[12:13]
	global_load_dword v89, v196, s[12:13] offset:256
	s_add_u32 s12, s12, s18
	s_addc_u32 s13, s13, 0
	global_load_dword v90, v196, s[12:13]
	global_load_dword v91, v196, s[12:13] offset:256
	s_add_u32 s12, s12, s18
	s_addc_u32 s13, s13, 0
	global_load_dword v92, v196, s[12:13]
	global_load_dword v93, v196, s[12:13] offset:256
	s_add_u32 s12, s12, s18
	s_addc_u32 s13, s13, 0
	global_load_dword v94, v196, s[12:13]
	global_load_dword v95, v196, s[12:13] offset:256
	s_add_u32 s12, s12, s18
	s_addc_u32 s13, s13, 0
	s_waitcnt vmcnt(0)
	ds_write2st64_b32 v206, v64, v65 offset0:0 offset1:1
	ds_write2st64_b32 v206, v66, v67 offset0:2 offset1:3
	ds_write2st64_b32 v206, v68, v69 offset0:4 offset1:5
	ds_write2st64_b32 v206, v70, v71 offset0:6 offset1:7
	ds_write2st64_b32 v206, v72, v73 offset0:8 offset1:9
	ds_write2st64_b32 v206, v74, v75 offset0:10 offset1:11
	ds_write2st64_b32 v206, v76, v77 offset0:12 offset1:13
	ds_write2st64_b32 v206, v78, v79 offset0:14 offset1:15
	ds_write2st64_b32 v206, v80, v81 offset0:16 offset1:17
	ds_write2st64_b32 v206, v82, v83 offset0:18 offset1:19
	ds_write2st64_b32 v206, v84, v85 offset0:20 offset1:21
	ds_write2st64_b32 v206, v86, v87 offset0:22 offset1:23
	ds_write2st64_b32 v206, v88, v89 offset0:24 offset1:25
	ds_write2st64_b32 v206, v90, v91 offset0:26 offset1:27
	ds_write2st64_b32 v206, v92, v93 offset0:28 offset1:29
	ds_write2st64_b32 v206, v94, v95 offset0:30 offset1:31
	s_add_u32 s12, s26, 0xf800000
	s_addc_u32 s13, s27, 0
	s_lshl_b32 s15, s101, 9
	s_add_u32 s12, s12, s15
	s_addc_u32 s13, s13, 0
	s_lshl_b32 s18, s92, 11
	global_load_dword v64, v196, s[12:13]
	global_load_dword v65, v196, s[12:13] offset:256
	s_add_u32 s12, s12, s18
	s_addc_u32 s13, s13, 0
	global_load_dword v66, v196, s[12:13]
	global_load_dword v67, v196, s[12:13] offset:256
	s_add_u32 s12, s12, s18
	s_addc_u32 s13, s13, 0
	global_load_dword v68, v196, s[12:13]
	global_load_dword v69, v196, s[12:13] offset:256
	s_add_u32 s12, s12, s18
	s_addc_u32 s13, s13, 0
	global_load_dword v70, v196, s[12:13]
	global_load_dword v71, v196, s[12:13] offset:256
	s_add_u32 s12, s12, s18
	s_addc_u32 s13, s13, 0
	global_load_dword v72, v196, s[12:13]
	global_load_dword v73, v196, s[12:13] offset:256
	s_add_u32 s12, s12, s18
	s_addc_u32 s13, s13, 0
	global_load_dword v74, v196, s[12:13]
	global_load_dword v75, v196, s[12:13] offset:256
	s_add_u32 s12, s12, s18
	s_addc_u32 s13, s13, 0
	global_load_dword v76, v196, s[12:13]
	global_load_dword v77, v196, s[12:13] offset:256
	s_add_u32 s12, s12, s18
	s_addc_u32 s13, s13, 0
	global_load_dword v78, v196, s[12:13]
	global_load_dword v79, v196, s[12:13] offset:256
	s_add_u32 s12, s12, s18
	s_addc_u32 s13, s13, 0
	global_load_dword v80, v196, s[12:13]
	global_load_dword v81, v196, s[12:13] offset:256
	s_add_u32 s12, s12, s18
	s_addc_u32 s13, s13, 0
	global_load_dword v82, v196, s[12:13]
	global_load_dword v83, v196, s[12:13] offset:256
	s_add_u32 s12, s12, s18
	s_addc_u32 s13, s13, 0
	global_load_dword v84, v196, s[12:13]
	global_load_dword v85, v196, s[12:13] offset:256
	s_add_u32 s12, s12, s18
	s_addc_u32 s13, s13, 0
	global_load_dword v86, v196, s[12:13]
	global_load_dword v87, v196, s[12:13] offset:256
	s_add_u32 s12, s12, s18
	s_addc_u32 s13, s13, 0
	global_load_dword v88, v196, s[12:13]
	global_load_dword v89, v196, s[12:13] offset:256
	s_add_u32 s12, s12, s18
	s_addc_u32 s13, s13, 0
	global_load_dword v90, v196, s[12:13]
	global_load_dword v91, v196, s[12:13] offset:256
	s_add_u32 s12, s12, s18
	s_addc_u32 s13, s13, 0
	global_load_dword v92, v196, s[12:13]
	global_load_dword v93, v196, s[12:13] offset:256
	s_add_u32 s12, s12, s18
	s_addc_u32 s13, s13, 0
	global_load_dword v94, v196, s[12:13]
	global_load_dword v95, v196, s[12:13] offset:256
	s_add_u32 s12, s12, s18
	s_addc_u32 s13, s13, 0
	s_waitcnt vmcnt(0)
	ds_write2st64_b32 v208, v64, v65 offset0:0 offset1:1
	ds_write2st64_b32 v208, v66, v67 offset0:2 offset1:3
	ds_write2st64_b32 v208, v68, v69 offset0:4 offset1:5
	ds_write2st64_b32 v208, v70, v71 offset0:6 offset1:7
	ds_write2st64_b32 v208, v72, v73 offset0:8 offset1:9
	ds_write2st64_b32 v208, v74, v75 offset0:10 offset1:11
	ds_write2st64_b32 v208, v76, v77 offset0:12 offset1:13
	ds_write2st64_b32 v208, v78, v79 offset0:14 offset1:15
	ds_write2st64_b32 v208, v80, v81 offset0:16 offset1:17
	ds_write2st64_b32 v208, v82, v83 offset0:18 offset1:19
	ds_write2st64_b32 v208, v84, v85 offset0:20 offset1:21
	ds_write2st64_b32 v208, v86, v87 offset0:22 offset1:23
	ds_write2st64_b32 v208, v88, v89 offset0:24 offset1:25
	ds_write2st64_b32 v208, v90, v91 offset0:26 offset1:27
	ds_write2st64_b32 v208, v92, v93 offset0:28 offset1:29
	ds_write2st64_b32 v208, v94, v95 offset0:30 offset1:31
	s_waitcnt lgkmcnt(0)
	v_mov_b32_e32 v209, 0x12000
	ds_read_b32 v212, v209
	s_waitcnt lgkmcnt(0)
	v_readfirstlane_b32 s13, v212
	s_nop 3
	s_lshl_b32 s13, s13, 2
	s_mov_b32 s14, 0
	s_mov_b32 s18, 0
	s_and_b32 s19, s18, 15
	s_lshr_b32 s98, s18, 4
	s_lshl_b32 s99, s19, 9
	s_mul_i32 s15, s19, s16
	s_lshl_b32 s18, s98, 7
	s_add_u32 s15, s15, s18
	s_lshl_b32 s18, s101, 12
	s_add_u32 s15, s15, s18
	s_add_u32 s8, s24, s15
	s_addc_u32 s9, s25, 0
	s_mul_i32 s15, s98, 0x300000
	s_add_u32 s4, s26, 0x4800000
	s_addc_u32 s5, s27, 0
	s_add_u32 s4, s4, s15
	s_addc_u32 s5, s5, 0
	v_add_u32_e32 v201, s99, v197
	v_add_u32_e32 v203, s99, v198
	ds_read2_b32 v[160:161], v201 offset0:0 offset1:8
	ds_read2_b32 v[162:163], v201 offset0:16 offset1:24
	s_waitcnt lgkmcnt(0)
	v_mad_u32_u24 v160, v160, s100, v199
	global_load_dwordx4 v[64:67], v160, s[4:5]
	global_load_dwordx2 v[68:69], v160, s[4:5] offset:16
	v_mad_u32_u24 v161, v161, s100, v199
	global_load_dwordx4 v[70:73], v161, s[4:5]
	global_load_dwordx2 v[74:75], v161, s[4:5] offset:16
	v_mad_u32_u24 v162, v162, s100, v199
	global_load_dwordx4 v[76:79], v162, s[4:5]
	global_load_dwordx2 v[80:81], v162, s[4:5] offset:16
	v_mad_u32_u24 v163, v163, s100, v199
	global_load_dwordx4 v[82:85], v163, s[4:5]
	global_load_dwordx2 v[86:87], v163, s[4:5] offset:16
	ds_read2_b32 v[168:169], v201 offset0:32 offset1:40
	ds_read2_b32 v[170:171], v201 offset0:48 offset1:56
	s_waitcnt lgkmcnt(0)
	v_mad_u32_u24 v168, v168, s100, v199
	global_load_dwordx4 v[88:91], v168, s[4:5]
	global_load_dwordx2 v[92:93], v168, s[4:5] offset:16
	v_mad_u32_u24 v169, v169, s100, v199
	global_load_dwordx4 v[94:97], v169, s[4:5]
	global_load_dwordx2 v[98:99], v169, s[4:5] offset:16
	v_mad_u32_u24 v170, v170, s100, v199
	global_load_dwordx4 v[100:103], v170, s[4:5]
	global_load_dwordx2 v[104:105], v170, s[4:5] offset:16
	v_mad_u32_u24 v171, v171, s100, v199
	global_load_dwordx4 v[106:109], v171, s[4:5]
	global_load_dwordx2 v[110:111], v171, s[4:5] offset:16
	ds_read2_b32 v[160:161], v201 offset0:64 offset1:72
	ds_read2_b32 v[162:163], v201 offset0:80 offset1:88
	s_waitcnt lgkmcnt(0)
	v_mad_u32_u24 v160, v160, s100, v199
	global_load_dwordx4 v[112:115], v160, s[4:5]
	global_load_dwordx2 v[116:117], v160, s[4:5] offset:16
	v_mad_u32_u24 v161, v161, s100, v199
	global_load_dwordx4 v[118:121], v161, s[4:5]
	global_load_dwordx2 v[122:123], v161, s[4:5] offset:16
	v_mad_u32_u24 v162, v162, s100, v199
	global_load_dwordx4 v[124:127], v162, s[4:5]
	global_load_dwordx2 v[128:129], v162, s[4:5] offset:16
	v_mad_u32_u24 v163, v163, s100, v199
	global_load_dwordx4 v[130:133], v163, s[4:5]
	global_load_dwordx2 v[134:135], v163, s[4:5] offset:16
	ds_read2_b32 v[168:169], v201 offset0:96 offset1:104
	ds_read2_b32 v[170:171], v201 offset0:112 offset1:120
	s_waitcnt lgkmcnt(0)
	v_mad_u32_u24 v168, v168, s100, v199
	global_load_dwordx4 v[136:139], v168, s[4:5]
	global_load_dwordx2 v[140:141], v168, s[4:5] offset:16
	v_mad_u32_u24 v169, v169, s100, v199
	global_load_dwordx4 v[142:145], v169, s[4:5]
	global_load_dwordx2 v[146:147], v169, s[4:5] offset:16
	v_mad_u32_u24 v170, v170, s100, v199
	global_load_dwordx4 v[148:151], v170, s[4:5]
	global_load_dwordx2 v[152:153], v170, s[4:5] offset:16
	v_mad_u32_u24 v171, v171, s100, v199
	global_load_dwordx4 v[154:157], v171, s[4:5]
	global_load_dwordx2 v[158:159], v171, s[4:5] offset:16
	global_load_dword v209, v200, s[8:9]
	ds_read2_b32 v[176:177], v203 offset0:0 offset1:8
	ds_read2_b32 v[178:179], v203 offset0:16 offset1:24
	s_mov_b32 s18, 1
	s_and_b32 s19, s18, 15
	s_lshr_b32 s98, s18, 4
	s_lshl_b32 s99, s19, 9
	s_mul_i32 s15, s19, s16
	s_lshl_b32 s18, s98, 7
	s_add_u32 s15, s15, s18
	s_lshl_b32 s18, s101, 12
	s_add_u32 s15, s15, s18
	s_add_u32 s10, s24, s15
	s_addc_u32 s11, s25, 0
	s_mul_i32 s15, s98, 0x300000
	s_add_u32 s4, s26, 0x4800000
	s_addc_u32 s5, s27, 0
	s_add_u32 s4, s4, s15
	s_addc_u32 s5, s5, 0
	v_add_u32_e32 v202, s99, v197
	v_add_u32_e32 v204, s99, v198
	ds_read2_b32 v[160:161], v202 offset0:0 offset1:8
	ds_read2_b32 v[162:163], v202 offset0:16 offset1:24
	s_waitcnt lgkmcnt(0)
.Lgv1_loop:
	global_load_dwordx4 v[192:195], v200, s[8:9]
	ds_read2_b32 v[184:185], v203 offset0:32 offset1:40
	ds_read2_b32 v[186:187], v203 offset0:48 offset1:56
	s_waitcnt vmcnt(32)
	v_cvt_scalef32_pk32_f32_fp6 v[32:63], v[64:69], 1.0
	v_pk_mul_f32 v[0:1], v[176:177], v[32:33] op_sel_hi:[0,1]
	v_pk_mul_f32 v[2:3], v[176:177], v[34:35] op_sel_hi:[0,1]
	v_pk_mul_f32 v[4:5], v[176:177], v[36:37] op_sel_hi:[0,1]
	v_pk_mul_f32 v[6:7], v[176:177], v[38:39] op_sel_hi:[0,1]
	v_pk_mul_f32 v[8:9], v[176:177], v[40:41] op_sel_hi:[0,1]
	v_pk_mul_f32 v[10:11], v[176:177], v[42:43] op_sel_hi:[0,1]
	v_pk_mul_f32 v[12:13], v[176:177], v[44:45] op_sel_hi:[0,1]
	v_pk_mul_f32 v[14:15], v[176:177], v[46:47] op_sel_hi:[0,1]
	v_pk_mul_f32 v[16:17], v[176:177], v[48:49] op_sel_hi:[0,1]
	v_pk_mul_f32 v[18:19], v[176:177], v[50:51] op_sel_hi:[0,1]
	v_pk_mul_f32 v[20:21], v[176:177], v[52:53] op_sel_hi:[0,1]
	v_pk_mul_f32 v[22:23], v[176:177], v[54:55] op_sel_hi:[0,1]
	v_pk_mul_f32 v[24:25], v[176:177], v[56:57] op_sel_hi:[0,1]
	v_pk_mul_f32 v[26:27], v[176:177], v[58:59] op_sel_hi:[0,1]
	v_pk_mul_f32 v[28:29], v[176:177], v[60:61] op_sel_hi:[0,1]
	v_pk_mul_f32 v[30:31], v[176:177], v[62:63] op_sel_hi:[0,1]
	s_waitcnt lgkmcnt(0)
	v_mad_u32_u24 v160, v160, s100, v199
	global_load_dwordx4 v[64:67], v160, s[4:5]
	global_load_dwordx2 v[68:69], v160, s[4:5] offset:16
	s_waitcnt vmcnt(32)
	v_cvt_scalef32_pk32_f32_fp6 v[32:63], v[70:75], 1.0
	v_pk_fma_f32 v[0:1], v[176:177], v[32:33], v[0:1] op_sel:[1,0,0] op_sel_hi:[1,1,1]
	v_pk_fma_f32 v[2:3], v[176:177], v[34:35], v[2:3] op_sel:[1,0,0] op_sel_hi:[1,1,1]
	v_pk_fma_f32 v[4:5], v[176:177], v[36:37], v[4:5] op_sel:[1,0,0] op_sel_hi:[1,1,1]
	v_pk_fma_f32 v[6:7], v[176:177], v[38:39], v[6:7] op_sel:[1,0,0] op_sel_hi:[1,1,1]
	v_pk_fma_f32 v[8:9], v[176:177], v[40:41], v[8:9] op_sel:[1,0,0] op_sel_hi:[1,1,1]
	v_pk_fma_f32 v[10:11], v[176:177], v[42:43], v[10:11] op_sel:[1,0,0] op_sel_hi:[1,1,1]
	v_pk_fma_f32 v[12:13], v[176:177], v[44:45], v[12:13] op_sel:[1,0,0] op_sel_hi:[1,1,1]
	v_pk_fma_f32 v[14:15], v[176:177], v[46:47], v[14:15] op_sel:[1,0,0] op_sel_hi:[1,1,1]
	v_pk_fma_f32 v[16:17], v[176:177], v[48:49], v[16:17] op_sel:[1,0,0] op_sel_hi:[1,1,1]
	v_pk_fma_f32 v[18:19], v[176:177], v[50:51], v[18:19] op_sel:[1,0,0] op_sel_hi:[1,1,1]
	v_pk_fma_f32 v[20:21], v[176:177], v[52:53], v[20:21] op_sel:[1,0,0] op_sel_hi:[1,1,1]
	v_pk_fma_f32 v[22:23], v[176:177], v[54:55], v[22:23] op_sel:[1,0,0] op_sel_hi:[1,1,1]
	v_pk_fma_f32 v[24:25], v[176:177], v[56:57], v[24:25] op_sel:[1,0,0] op_sel_hi:[1,1,1]
	v_pk_fma_f32 v[26:27], v[176:177], v[58:59], v[26:27] op_sel:[1,0,0] op_sel_hi:[1,1,1]
	v_pk_fma_f32 v[28:29], v[176:177], v[60:61], v[28:29] op_sel:[1,0,0] op_sel_hi:[1,1,1]
	v_pk_fma_f32 v[30:31], v[176:177], v[62:63], v[30:31] op_sel:[1,0,0] op_sel_hi:[1,1,1]
	v_mad_u32_u24 v161, v161, s100, v199
	global_load_dwordx4 v[70:73], v161, s[4:5]
	global_load_dwordx2 v[74:75], v161, s[4:5] offset:16
	s_waitcnt vmcnt(32)
	v_cvt_scalef32_pk32_f32_fp6 v[32:63], v[76:81], 1.0
	v_pk_fma_f32 v[0:1], v[178:179], v[32:33], v[0:1] op_sel_hi:[0,1,1]
	v_pk_fma_f32 v[2:3], v[178:179], v[34:35], v[2:3] op_sel_hi:[0,1,1]
	v_pk_fma_f32 v[4:5], v[178:179], v[36:37], v[4:5] op_sel_hi:[0,1,1]
	v_pk_fma_f32 v[6:7], v[178:179], v[38:39], v[6:7] op_sel_hi:[0,1,1]
	v_pk_fma_f32 v[8:9], v[178:179], v[40:41], v[8:9] op_sel_hi:[0,1,1]
	v_pk_fma_f32 v[10:11], v[178:179], v[42:43], v[10:11] op_sel_hi:[0,1,1]
	v_pk_fma_f32 v[12:13], v[178:179], v[44:45], v[12:13] op_sel_hi:[0,1,1]
	v_pk_fma_f32 v[14:15], v[178:179], v[46:47], v[14:15] op_sel_hi:[0,1,1]
	v_pk_fma_f32 v[16:17], v[178:179], v[48:49], v[16:17] op_sel_hi:[0,1,1]
	v_pk_fma_f32 v[18:19], v[178:179], v[50:51], v[18:19] op_sel_hi:[0,1,1]
	v_pk_fma_f32 v[20:21], v[178:179], v[52:53], v[20:21] op_sel_hi:[0,1,1]
	v_pk_fma_f32 v[22:23], v[178:179], v[54:55], v[22:23] op_sel_hi:[0,1,1]
	v_pk_fma_f32 v[24:25], v[178:179], v[56:57], v[24:25] op_sel_hi:[0,1,1]
	v_pk_fma_f32 v[26:27], v[178:179], v[58:59], v[26:27] op_sel_hi:[0,1,1]
	v_pk_fma_f32 v[28:29], v[178:179], v[60:61], v[28:29] op_sel_hi:[0,1,1]
	v_pk_fma_f32 v[30:31], v[178:179], v[62:63], v[30:31] op_sel_hi:[0,1,1]
	v_mad_u32_u24 v162, v162, s100, v199
	global_load_dwordx4 v[76:79], v162, s[4:5]
	global_load_dwordx2 v[80:81], v162, s[4:5] offset:16
	s_waitcnt vmcnt(32)
	v_cvt_scalef32_pk32_f32_fp6 v[32:63], v[82:87], 1.0
	v_pk_fma_f32 v[0:1], v[178:179], v[32:33], v[0:1] op_sel:[1,0,0] op_sel_hi:[1,1,1]
	v_pk_fma_f32 v[2:3], v[178:179], v[34:35], v[2:3] op_sel:[1,0,0] op_sel_hi:[1,1,1]
	v_pk_fma_f32 v[4:5], v[178:179], v[36:37], v[4:5] op_sel:[1,0,0] op_sel_hi:[1,1,1]
	v_pk_fma_f32 v[6:7], v[178:179], v[38:39], v[6:7] op_sel:[1,0,0] op_sel_hi:[1,1,1]
	v_pk_fma_f32 v[8:9], v[178:179], v[40:41], v[8:9] op_sel:[1,0,0] op_sel_hi:[1,1,1]
	v_pk_fma_f32 v[10:11], v[178:179], v[42:43], v[10:11] op_sel:[1,0,0] op_sel_hi:[1,1,1]
	v_pk_fma_f32 v[12:13], v[178:179], v[44:45], v[12:13] op_sel:[1,0,0] op_sel_hi:[1,1,1]
	v_pk_fma_f32 v[14:15], v[178:179], v[46:47], v[14:15] op_sel:[1,0,0] op_sel_hi:[1,1,1]
	v_pk_fma_f32 v[16:17], v[178:179], v[48:49], v[16:17] op_sel:[1,0,0] op_sel_hi:[1,1,1]
	v_pk_fma_f32 v[18:19], v[178:179], v[50:51], v[18:19] op_sel:[1,0,0] op_sel_hi:[1,1,1]
	v_pk_fma_f32 v[20:21], v[178:179], v[52:53], v[20:21] op_sel:[1,0,0] op_sel_hi:[1,1,1]
	v_pk_fma_f32 v[22:23], v[178:179], v[54:55], v[22:23] op_sel:[1,0,0] op_sel_hi:[1,1,1]
	v_pk_fma_f32 v[24:25], v[178:179], v[56:57], v[24:25] op_sel:[1,0,0] op_sel_hi:[1,1,1]
	v_pk_fma_f32 v[26:27], v[178:179], v[58:59], v[26:27] op_sel:[1,0,0] op_sel_hi:[1,1,1]
	v_pk_fma_f32 v[28:29], v[178:179], v[60:61], v[28:29] op_sel:[1,0,0] op_sel_hi:[1,1,1]
	v_pk_fma_f32 v[30:31], v[178:179], v[62:63], v[30:31] op_sel:[1,0,0] op_sel_hi:[1,1,1]
	v_mad_u32_u24 v163, v163, s100, v199
	global_load_dwordx4 v[82:85], v163, s[4:5]
	global_load_dwordx2 v[86:87], v163, s[4:5] offset:16
	ds_read2_b32 v[168:169], v202 offset0:32 offset1:40
	ds_read2_b32 v[170:171], v202 offset0:48 offset1:56
	ds_read2_b32 v[176:177], v203 offset0:64 offset1:72
	ds_read2_b32 v[178:179], v203 offset0:80 offset1:88
	s_waitcnt vmcnt(32)
	v_cvt_scalef32_pk32_f32_fp6 v[32:63], v[88:93], 1.0
	v_pk_fma_f32 v[0:1], v[184:185], v[32:33], v[0:1] op_sel_hi:[0,1,1]
	v_pk_fma_f32 v[2:3], v[184:185], v[34:35], v[2:3] op_sel_hi:[0,1,1]
	v_pk_fma_f32 v[4:5], v[184:185], v[36:37], v[4:5] op_sel_hi:[0,1,1]
	v_pk_fma_f32 v[6:7], v[184:185], v[38:39], v[6:7] op_sel_hi:[0,1,1]
	v_pk_fma_f32 v[8:9], v[184:185], v[40:41], v[8:9] op_sel_hi:[0,1,1]
	v_pk_fma_f32 v[10:11], v[184:185], v[42:43], v[10:11] op_sel_hi:[0,1,1]
	v_pk_fma_f32 v[12:13], v[184:185], v[44:45], v[12:13] op_sel_hi:[0,1,1]
	v_pk_fma_f32 v[14:15], v[184:185], v[46:47], v[14:15] op_sel_hi:[0,1,1]
	v_pk_fma_f32 v[16:17], v[184:185], v[48:49], v[16:17] op_sel_hi:[0,1,1]
	v_pk_fma_f32 v[18:19], v[184:185], v[50:51], v[18:19] op_sel_hi:[0,1,1]
	v_pk_fma_f32 v[20:21], v[184:185], v[52:53], v[20:21] op_sel_hi:[0,1,1]
	v_pk_fma_f32 v[22:23], v[184:185], v[54:55], v[22:23] op_sel_hi:[0,1,1]
	v_pk_fma_f32 v[24:25], v[184:185], v[56:57], v[24:25] op_sel_hi:[0,1,1]
	v_pk_fma_f32 v[26:27], v[184:185], v[58:59], v[26:27] op_sel_hi:[0,1,1]
	v_pk_fma_f32 v[28:29], v[184:185], v[60:61], v[28:29] op_sel_hi:[0,1,1]
	v_pk_fma_f32 v[30:31], v[184:185], v[62:63], v[30:31] op_sel_hi:[0,1,1]
	s_waitcnt lgkmcnt(0)
	v_mad_u32_u24 v168, v168, s100, v199
	global_load_dwordx4 v[88:91], v168, s[4:5]
	global_load_dwordx2 v[92:93], v168, s[4:5] offset:16
	s_waitcnt vmcnt(32)
	v_cvt_scalef32_pk32_f32_fp6 v[32:63], v[94:99], 1.0
	v_pk_fma_f32 v[0:1], v[184:185], v[32:33], v[0:1] op_sel:[1,0,0] op_sel_hi:[1,1,1]
	v_pk_fma_f32 v[2:3], v[184:185], v[34:35], v[2:3] op_sel:[1,0,0] op_sel_hi:[1,1,1]
	v_pk_fma_f32 v[4:5], v[184:185], v[36:37], v[4:5] op_sel:[1,0,0] op_sel_hi:[1,1,1]
	v_pk_fma_f32 v[6:7], v[184:185], v[38:39], v[6:7] op_sel:[1,0,0] op_sel_hi:[1,1,1]
	v_pk_fma_f32 v[8:9], v[184:185], v[40:41], v[8:9] op_sel:[1,0,0] op_sel_hi:[1,1,1]
	v_pk_fma_f32 v[10:11], v[184:185], v[42:43], v[10:11] op_sel:[1,0,0] op_sel_hi:[1,1,1]
	v_pk_fma_f32 v[12:13], v[184:185], v[44:45], v[12:13] op_sel:[1,0,0] op_sel_hi:[1,1,1]
	v_pk_fma_f32 v[14:15], v[184:185], v[46:47], v[14:15] op_sel:[1,0,0] op_sel_hi:[1,1,1]
	v_pk_fma_f32 v[16:17], v[184:185], v[48:49], v[16:17] op_sel:[1,0,0] op_sel_hi:[1,1,1]
	v_pk_fma_f32 v[18:19], v[184:185], v[50:51], v[18:19] op_sel:[1,0,0] op_sel_hi:[1,1,1]
	v_pk_fma_f32 v[20:21], v[184:185], v[52:53], v[20:21] op_sel:[1,0,0] op_sel_hi:[1,1,1]
	v_pk_fma_f32 v[22:23], v[184:185], v[54:55], v[22:23] op_sel:[1,0,0] op_sel_hi:[1,1,1]
	v_pk_fma_f32 v[24:25], v[184:185], v[56:57], v[24:25] op_sel:[1,0,0] op_sel_hi:[1,1,1]
	v_pk_fma_f32 v[26:27], v[184:185], v[58:59], v[26:27] op_sel:[1,0,0] op_sel_hi:[1,1,1]
	v_pk_fma_f32 v[28:29], v[184:185], v[60:61], v[28:29] op_sel:[1,0,0] op_sel_hi:[1,1,1]
	v_pk_fma_f32 v[30:31], v[184:185], v[62:63], v[30:31] op_sel:[1,0,0] op_sel_hi:[1,1,1]
	v_mad_u32_u24 v169, v169, s100, v199
	global_load_dwordx4 v[94:97], v169, s[4:5]
	global_load_dwordx2 v[98:99], v169, s[4:5] offset:16
	s_waitcnt vmcnt(32)
	v_cvt_scalef32_pk32_f32_fp6 v[32:63], v[100:105], 1.0
	v_pk_fma_f32 v[0:1], v[186:187], v[32:33], v[0:1] op_sel_hi:[0,1,1]
	v_pk_fma_f32 v[2:3], v[186:187], v[34:35], v[2:3] op_sel_hi:[0,1,1]
	v_pk_fma_f32 v[4:5], v[186:187], v[36:37], v[4:5] op_sel_hi:[0,1,1]
	v_pk_fma_f32 v[6:7], v[186:187], v[38:39], v[6:7] op_sel_hi:[0,1,1]
	v_pk_fma_f32 v[8:9], v[186:187], v[40:41], v[8:9] op_sel_hi:[0,1,1]
	v_pk_fma_f32 v[10:11], v[186:187], v[42:43], v[10:11] op_sel_hi:[0,1,1]
	v_pk_fma_f32 v[12:13], v[186:187], v[44:45], v[12:13] op_sel_hi:[0,1,1]
	v_pk_fma_f32 v[14:15], v[186:187], v[46:47], v[14:15] op_sel_hi:[0,1,1]
	v_pk_fma_f32 v[16:17], v[186:187], v[48:49], v[16:17] op_sel_hi:[0,1,1]
	v_pk_fma_f32 v[18:19], v[186:187], v[50:51], v[18:19] op_sel_hi:[0,1,1]
	v_pk_fma_f32 v[20:21], v[186:187], v[52:53], v[20:21] op_sel_hi:[0,1,1]
	v_pk_fma_f32 v[22:23], v[186:187], v[54:55], v[22:23] op_sel_hi:[0,1,1]
	v_pk_fma_f32 v[24:25], v[186:187], v[56:57], v[24:25] op_sel_hi:[0,1,1]
	v_pk_fma_f32 v[26:27], v[186:187], v[58:59], v[26:27] op_sel_hi:[0,1,1]
	v_pk_fma_f32 v[28:29], v[186:187], v[60:61], v[28:29] op_sel_hi:[0,1,1]
	v_pk_fma_f32 v[30:31], v[186:187], v[62:63], v[30:31] op_sel_hi:[0,1,1]
	v_mad_u32_u24 v170, v170, s100, v199
	global_load_dwordx4 v[100:103], v170, s[4:5]
	global_load_dwordx2 v[104:105], v170, s[4:5] offset:16
	s_waitcnt vmcnt(32)
	v_cvt_scalef32_pk32_f32_fp6 v[32:63], v[106:111], 1.0
	v_pk_fma_f32 v[0:1], v[186:187], v[32:33], v[0:1] op_sel:[1,0,0] op_sel_hi:[1,1,1]
	v_pk_fma_f32 v[2:3], v[186:187], v[34:35], v[2:3] op_sel:[1,0,0] op_sel_hi:[1,1,1]
	v_pk_fma_f32 v[4:5], v[186:187], v[36:37], v[4:5] op_sel:[1,0,0] op_sel_hi:[1,1,1]
	v_pk_fma_f32 v[6:7], v[186:187], v[38:39], v[6:7] op_sel:[1,0,0] op_sel_hi:[1,1,1]
	v_pk_fma_f32 v[8:9], v[186:187], v[40:41], v[8:9] op_sel:[1,0,0] op_sel_hi:[1,1,1]
	v_pk_fma_f32 v[10:11], v[186:187], v[42:43], v[10:11] op_sel:[1,0,0] op_sel_hi:[1,1,1]
	v_pk_fma_f32 v[12:13], v[186:187], v[44:45], v[12:13] op_sel:[1,0,0] op_sel_hi:[1,1,1]
	v_pk_fma_f32 v[14:15], v[186:187], v[46:47], v[14:15] op_sel:[1,0,0] op_sel_hi:[1,1,1]
	v_pk_fma_f32 v[16:17], v[186:187], v[48:49], v[16:17] op_sel:[1,0,0] op_sel_hi:[1,1,1]
	v_pk_fma_f32 v[18:19], v[186:187], v[50:51], v[18:19] op_sel:[1,0,0] op_sel_hi:[1,1,1]
	v_pk_fma_f32 v[20:21], v[186:187], v[52:53], v[20:21] op_sel:[1,0,0] op_sel_hi:[1,1,1]
	v_pk_fma_f32 v[22:23], v[186:187], v[54:55], v[22:23] op_sel:[1,0,0] op_sel_hi:[1,1,1]
	v_pk_fma_f32 v[24:25], v[186:187], v[56:57], v[24:25] op_sel:[1,0,0] op_sel_hi:[1,1,1]
	v_pk_fma_f32 v[26:27], v[186:187], v[58:59], v[26:27] op_sel:[1,0,0] op_sel_hi:[1,1,1]
	v_pk_fma_f32 v[28:29], v[186:187], v[60:61], v[28:29] op_sel:[1,0,0] op_sel_hi:[1,1,1]
	v_pk_fma_f32 v[30:31], v[186:187], v[62:63], v[30:31] op_sel:[1,0,0] op_sel_hi:[1,1,1]
	v_mad_u32_u24 v171, v171, s100, v199
	global_load_dwordx4 v[106:109], v171, s[4:5]
	global_load_dwordx2 v[110:111], v171, s[4:5] offset:16
	ds_read2_b32 v[160:161], v202 offset0:64 offset1:72
	ds_read2_b32 v[162:163], v202 offset0:80 offset1:88
	ds_read2_b32 v[184:185], v203 offset0:96 offset1:104
	ds_read2_b32 v[186:187], v203 offset0:112 offset1:120
	s_waitcnt vmcnt(32)
	v_cvt_scalef32_pk32_f32_fp6 v[32:63], v[112:117], 1.0
	v_pk_fma_f32 v[0:1], v[176:177], v[32:33], v[0:1] op_sel_hi:[0,1,1]
	v_pk_fma_f32 v[2:3], v[176:177], v[34:35], v[2:3] op_sel_hi:[0,1,1]
	v_pk_fma_f32 v[4:5], v[176:177], v[36:37], v[4:5] op_sel_hi:[0,1,1]
	v_pk_fma_f32 v[6:7], v[176:177], v[38:39], v[6:7] op_sel_hi:[0,1,1]
	v_pk_fma_f32 v[8:9], v[176:177], v[40:41], v[8:9] op_sel_hi:[0,1,1]
	v_pk_fma_f32 v[10:11], v[176:177], v[42:43], v[10:11] op_sel_hi:[0,1,1]
	v_pk_fma_f32 v[12:13], v[176:177], v[44:45], v[12:13] op_sel_hi:[0,1,1]
	v_pk_fma_f32 v[14:15], v[176:177], v[46:47], v[14:15] op_sel_hi:[0,1,1]
	v_pk_fma_f32 v[16:17], v[176:177], v[48:49], v[16:17] op_sel_hi:[0,1,1]
	v_pk_fma_f32 v[18:19], v[176:177], v[50:51], v[18:19] op_sel_hi:[0,1,1]
	v_pk_fma_f32 v[20:21], v[176:177], v[52:53], v[20:21] op_sel_hi:[0,1,1]
	v_pk_fma_f32 v[22:23], v[176:177], v[54:55], v[22:23] op_sel_hi:[0,1,1]
	v_pk_fma_f32 v[24:25], v[176:177], v[56:57], v[24:25] op_sel_hi:[0,1,1]
	v_pk_fma_f32 v[26:27], v[176:177], v[58:59], v[26:27] op_sel_hi:[0,1,1]
	v_pk_fma_f32 v[28:29], v[176:177], v[60:61], v[28:29] op_sel_hi:[0,1,1]
	v_pk_fma_f32 v[30:31], v[176:177], v[62:63], v[30:31] op_sel_hi:[0,1,1]
	s_waitcnt lgkmcnt(0)
	v_mad_u32_u24 v160, v160, s100, v199
	global_load_dwordx4 v[112:115], v160, s[4:5]
	global_load_dwordx2 v[116:117], v160, s[4:5] offset:16
	s_waitcnt vmcnt(32)
	v_cvt_scalef32_pk32_f32_fp6 v[32:63], v[118:123], 1.0
	v_pk_fma_f32 v[0:1], v[176:177], v[32:33], v[0:1] op_sel:[1,0,0] op_sel_hi:[1,1,1]
	v_pk_fma_f32 v[2:3], v[176:177], v[34:35], v[2:3] op_sel:[1,0,0] op_sel_hi:[1,1,1]
	v_pk_fma_f32 v[4:5], v[176:177], v[36:37], v[4:5] op_sel:[1,0,0] op_sel_hi:[1,1,1]
	v_pk_fma_f32 v[6:7], v[176:177], v[38:39], v[6:7] op_sel:[1,0,0] op_sel_hi:[1,1,1]
	v_pk_fma_f32 v[8:9], v[176:177], v[40:41], v[8:9] op_sel:[1,0,0] op_sel_hi:[1,1,1]
	v_pk_fma_f32 v[10:11], v[176:177], v[42:43], v[10:11] op_sel:[1,0,0] op_sel_hi:[1,1,1]
	v_pk_fma_f32 v[12:13], v[176:177], v[44:45], v[12:13] op_sel:[1,0,0] op_sel_hi:[1,1,1]
	v_pk_fma_f32 v[14:15], v[176:177], v[46:47], v[14:15] op_sel:[1,0,0] op_sel_hi:[1,1,1]
	v_pk_fma_f32 v[16:17], v[176:177], v[48:49], v[16:17] op_sel:[1,0,0] op_sel_hi:[1,1,1]
	v_pk_fma_f32 v[18:19], v[176:177], v[50:51], v[18:19] op_sel:[1,0,0] op_sel_hi:[1,1,1]
	v_pk_fma_f32 v[20:21], v[176:177], v[52:53], v[20:21] op_sel:[1,0,0] op_sel_hi:[1,1,1]
	v_pk_fma_f32 v[22:23], v[176:177], v[54:55], v[22:23] op_sel:[1,0,0] op_sel_hi:[1,1,1]
	v_pk_fma_f32 v[24:25], v[176:177], v[56:57], v[24:25] op_sel:[1,0,0] op_sel_hi:[1,1,1]
	v_pk_fma_f32 v[26:27], v[176:177], v[58:59], v[26:27] op_sel:[1,0,0] op_sel_hi:[1,1,1]
	v_pk_fma_f32 v[28:29], v[176:177], v[60:61], v[28:29] op_sel:[1,0,0] op_sel_hi:[1,1,1]
	v_pk_fma_f32 v[30:31], v[176:177], v[62:63], v[30:31] op_sel:[1,0,0] op_sel_hi:[1,1,1]
	v_mad_u32_u24 v161, v161, s100, v199
	global_load_dwordx4 v[118:121], v161, s[4:5]
	global_load_dwordx2 v[122:123], v161, s[4:5] offset:16
	s_waitcnt vmcnt(32)
	v_cvt_scalef32_pk32_f32_fp6 v[32:63], v[124:129], 1.0
	v_pk_fma_f32 v[0:1], v[178:179], v[32:33], v[0:1] op_sel_hi:[0,1,1]
	v_pk_fma_f32 v[2:3], v[178:179], v[34:35], v[2:3] op_sel_hi:[0,1,1]
	v_pk_fma_f32 v[4:5], v[178:179], v[36:37], v[4:5] op_sel_hi:[0,1,1]
	v_pk_fma_f32 v[6:7], v[178:179], v[38:39], v[6:7] op_sel_hi:[0,1,1]
	v_pk_fma_f32 v[8:9], v[178:179], v[40:41], v[8:9] op_sel_hi:[0,1,1]
	v_pk_fma_f32 v[10:11], v[178:179], v[42:43], v[10:11] op_sel_hi:[0,1,1]
	v_pk_fma_f32 v[12:13], v[178:179], v[44:45], v[12:13] op_sel_hi:[0,1,1]
	v_pk_fma_f32 v[14:15], v[178:179], v[46:47], v[14:15] op_sel_hi:[0,1,1]
	v_pk_fma_f32 v[16:17], v[178:179], v[48:49], v[16:17] op_sel_hi:[0,1,1]
	v_pk_fma_f32 v[18:19], v[178:179], v[50:51], v[18:19] op_sel_hi:[0,1,1]
	v_pk_fma_f32 v[20:21], v[178:179], v[52:53], v[20:21] op_sel_hi:[0,1,1]
	v_pk_fma_f32 v[22:23], v[178:179], v[54:55], v[22:23] op_sel_hi:[0,1,1]
	v_pk_fma_f32 v[24:25], v[178:179], v[56:57], v[24:25] op_sel_hi:[0,1,1]
	v_pk_fma_f32 v[26:27], v[178:179], v[58:59], v[26:27] op_sel_hi:[0,1,1]
	v_pk_fma_f32 v[28:29], v[178:179], v[60:61], v[28:29] op_sel_hi:[0,1,1]
	v_pk_fma_f32 v[30:31], v[178:179], v[62:63], v[30:31] op_sel_hi:[0,1,1]
	v_mad_u32_u24 v162, v162, s100, v199
	global_load_dwordx4 v[124:127], v162, s[4:5]
	global_load_dwordx2 v[128:129], v162, s[4:5] offset:16
	s_waitcnt vmcnt(32)
	v_cvt_scalef32_pk32_f32_fp6 v[32:63], v[130:135], 1.0
	v_pk_fma_f32 v[0:1], v[178:179], v[32:33], v[0:1] op_sel:[1,0,0] op_sel_hi:[1,1,1]
	v_pk_fma_f32 v[2:3], v[178:179], v[34:35], v[2:3] op_sel:[1,0,0] op_sel_hi:[1,1,1]
	v_pk_fma_f32 v[4:5], v[178:179], v[36:37], v[4:5] op_sel:[1,0,0] op_sel_hi:[1,1,1]
	v_pk_fma_f32 v[6:7], v[178:179], v[38:39], v[6:7] op_sel:[1,0,0] op_sel_hi:[1,1,1]
	v_pk_fma_f32 v[8:9], v[178:179], v[40:41], v[8:9] op_sel:[1,0,0] op_sel_hi:[1,1,1]
	v_pk_fma_f32 v[10:11], v[178:179], v[42:43], v[10:11] op_sel:[1,0,0] op_sel_hi:[1,1,1]
	v_pk_fma_f32 v[12:13], v[178:179], v[44:45], v[12:13] op_sel:[1,0,0] op_sel_hi:[1,1,1]
	v_pk_fma_f32 v[14:15], v[178:179], v[46:47], v[14:15] op_sel:[1,0,0] op_sel_hi:[1,1,1]
	v_pk_fma_f32 v[16:17], v[178:179], v[48:49], v[16:17] op_sel:[1,0,0] op_sel_hi:[1,1,1]
	v_pk_fma_f32 v[18:19], v[178:179], v[50:51], v[18:19] op_sel:[1,0,0] op_sel_hi:[1,1,1]
	v_pk_fma_f32 v[20:21], v[178:179], v[52:53], v[20:21] op_sel:[1,0,0] op_sel_hi:[1,1,1]
	v_pk_fma_f32 v[22:23], v[178:179], v[54:55], v[22:23] op_sel:[1,0,0] op_sel_hi:[1,1,1]
	v_pk_fma_f32 v[24:25], v[178:179], v[56:57], v[24:25] op_sel:[1,0,0] op_sel_hi:[1,1,1]
	v_pk_fma_f32 v[26:27], v[178:179], v[58:59], v[26:27] op_sel:[1,0,0] op_sel_hi:[1,1,1]
	v_pk_fma_f32 v[28:29], v[178:179], v[60:61], v[28:29] op_sel:[1,0,0] op_sel_hi:[1,1,1]
	v_pk_fma_f32 v[30:31], v[178:179], v[62:63], v[30:31] op_sel:[1,0,0] op_sel_hi:[1,1,1]
	v_mad_u32_u24 v163, v163, s100, v199
	global_load_dwordx4 v[130:133], v163, s[4:5]
	global_load_dwordx2 v[134:135], v163, s[4:5] offset:16
	ds_read2_b32 v[168:169], v202 offset0:96 offset1:104
	ds_read2_b32 v[170:171], v202 offset0:112 offset1:120
	ds_read2_b32 v[176:177], v204 offset0:0 offset1:8
	ds_read2_b32 v[178:179], v204 offset0:16 offset1:24
	s_waitcnt vmcnt(32)
	v_cvt_scalef32_pk32_f32_fp6 v[32:63], v[136:141], 1.0
	v_pk_fma_f32 v[0:1], v[184:185], v[32:33], v[0:1] op_sel_hi:[0,1,1]
	v_pk_fma_f32 v[2:3], v[184:185], v[34:35], v[2:3] op_sel_hi:[0,1,1]
	v_pk_fma_f32 v[4:5], v[184:185], v[36:37], v[4:5] op_sel_hi:[0,1,1]
	v_pk_fma_f32 v[6:7], v[184:185], v[38:39], v[6:7] op_sel_hi:[0,1,1]
	v_pk_fma_f32 v[8:9], v[184:185], v[40:41], v[8:9] op_sel_hi:[0,1,1]
	v_pk_fma_f32 v[10:11], v[184:185], v[42:43], v[10:11] op_sel_hi:[0,1,1]
	v_pk_fma_f32 v[12:13], v[184:185], v[44:45], v[12:13] op_sel_hi:[0,1,1]
	v_pk_fma_f32 v[14:15], v[184:185], v[46:47], v[14:15] op_sel_hi:[0,1,1]
	v_pk_fma_f32 v[16:17], v[184:185], v[48:49], v[16:17] op_sel_hi:[0,1,1]
	v_pk_fma_f32 v[18:19], v[184:185], v[50:51], v[18:19] op_sel_hi:[0,1,1]
	v_pk_fma_f32 v[20:21], v[184:185], v[52:53], v[20:21] op_sel_hi:[0,1,1]
	v_pk_fma_f32 v[22:23], v[184:185], v[54:55], v[22:23] op_sel_hi:[0,1,1]
	v_pk_fma_f32 v[24:25], v[184:185], v[56:57], v[24:25] op_sel_hi:[0,1,1]
	v_pk_fma_f32 v[26:27], v[184:185], v[58:59], v[26:27] op_sel_hi:[0,1,1]
	v_pk_fma_f32 v[28:29], v[184:185], v[60:61], v[28:29] op_sel_hi:[0,1,1]
	v_pk_fma_f32 v[30:31], v[184:185], v[62:63], v[30:31] op_sel_hi:[0,1,1]
	s_waitcnt lgkmcnt(0)
	v_mad_u32_u24 v168, v168, s100, v199
	global_load_dwordx4 v[136:139], v168, s[4:5]
	global_load_dwordx2 v[140:141], v168, s[4:5] offset:16
	s_waitcnt vmcnt(32)
	v_cvt_scalef32_pk32_f32_fp6 v[32:63], v[142:147], 1.0
	v_pk_fma_f32 v[0:1], v[184:185], v[32:33], v[0:1] op_sel:[1,0,0] op_sel_hi:[1,1,1]
	v_pk_fma_f32 v[2:3], v[184:185], v[34:35], v[2:3] op_sel:[1,0,0] op_sel_hi:[1,1,1]
	v_pk_fma_f32 v[4:5], v[184:185], v[36:37], v[4:5] op_sel:[1,0,0] op_sel_hi:[1,1,1]
	v_pk_fma_f32 v[6:7], v[184:185], v[38:39], v[6:7] op_sel:[1,0,0] op_sel_hi:[1,1,1]
	v_pk_fma_f32 v[8:9], v[184:185], v[40:41], v[8:9] op_sel:[1,0,0] op_sel_hi:[1,1,1]
	v_pk_fma_f32 v[10:11], v[184:185], v[42:43], v[10:11] op_sel:[1,0,0] op_sel_hi:[1,1,1]
	v_pk_fma_f32 v[12:13], v[184:185], v[44:45], v[12:13] op_sel:[1,0,0] op_sel_hi:[1,1,1]
	v_pk_fma_f32 v[14:15], v[184:185], v[46:47], v[14:15] op_sel:[1,0,0] op_sel_hi:[1,1,1]
	v_pk_fma_f32 v[16:17], v[184:185], v[48:49], v[16:17] op_sel:[1,0,0] op_sel_hi:[1,1,1]
	v_pk_fma_f32 v[18:19], v[184:185], v[50:51], v[18:19] op_sel:[1,0,0] op_sel_hi:[1,1,1]
	v_pk_fma_f32 v[20:21], v[184:185], v[52:53], v[20:21] op_sel:[1,0,0] op_sel_hi:[1,1,1]
	v_pk_fma_f32 v[22:23], v[184:185], v[54:55], v[22:23] op_sel:[1,0,0] op_sel_hi:[1,1,1]
	v_pk_fma_f32 v[24:25], v[184:185], v[56:57], v[24:25] op_sel:[1,0,0] op_sel_hi:[1,1,1]
	v_pk_fma_f32 v[26:27], v[184:185], v[58:59], v[26:27] op_sel:[1,0,0] op_sel_hi:[1,1,1]
	v_pk_fma_f32 v[28:29], v[184:185], v[60:61], v[28:29] op_sel:[1,0,0] op_sel_hi:[1,1,1]
	v_pk_fma_f32 v[30:31], v[184:185], v[62:63], v[30:31] op_sel:[1,0,0] op_sel_hi:[1,1,1]
	v_mad_u32_u24 v169, v169, s100, v199
	global_load_dwordx4 v[142:145], v169, s[4:5]
	global_load_dwordx2 v[146:147], v169, s[4:5] offset:16
	s_waitcnt vmcnt(32)
	v_cvt_scalef32_pk32_f32_fp6 v[32:63], v[148:153], 1.0
	v_pk_fma_f32 v[0:1], v[186:187], v[32:33], v[0:1] op_sel_hi:[0,1,1]
	v_pk_fma_f32 v[2:3], v[186:187], v[34:35], v[2:3] op_sel_hi:[0,1,1]
	v_pk_fma_f32 v[4:5], v[186:187], v[36:37], v[4:5] op_sel_hi:[0,1,1]
	v_pk_fma_f32 v[6:7], v[186:187], v[38:39], v[6:7] op_sel_hi:[0,1,1]
	v_pk_fma_f32 v[8:9], v[186:187], v[40:41], v[8:9] op_sel_hi:[0,1,1]
	v_pk_fma_f32 v[10:11], v[186:187], v[42:43], v[10:11] op_sel_hi:[0,1,1]
	v_pk_fma_f32 v[12:13], v[186:187], v[44:45], v[12:13] op_sel_hi:[0,1,1]
	v_pk_fma_f32 v[14:15], v[186:187], v[46:47], v[14:15] op_sel_hi:[0,1,1]
	v_pk_fma_f32 v[16:17], v[186:187], v[48:49], v[16:17] op_sel_hi:[0,1,1]
	v_pk_fma_f32 v[18:19], v[186:187], v[50:51], v[18:19] op_sel_hi:[0,1,1]
	v_pk_fma_f32 v[20:21], v[186:187], v[52:53], v[20:21] op_sel_hi:[0,1,1]
	v_pk_fma_f32 v[22:23], v[186:187], v[54:55], v[22:23] op_sel_hi:[0,1,1]
	v_pk_fma_f32 v[24:25], v[186:187], v[56:57], v[24:25] op_sel_hi:[0,1,1]
	v_pk_fma_f32 v[26:27], v[186:187], v[58:59], v[26:27] op_sel_hi:[0,1,1]
	v_pk_fma_f32 v[28:29], v[186:187], v[60:61], v[28:29] op_sel_hi:[0,1,1]
	v_pk_fma_f32 v[30:31], v[186:187], v[62:63], v[30:31] op_sel_hi:[0,1,1]
	v_mad_u32_u24 v170, v170, s100, v199
	global_load_dwordx4 v[148:151], v170, s[4:5]
	global_load_dwordx2 v[152:153], v170, s[4:5] offset:16
	s_waitcnt vmcnt(32)
	v_cvt_scalef32_pk32_f32_fp6 v[32:63], v[154:159], 1.0
	v_pk_fma_f32 v[0:1], v[186:187], v[32:33], v[0:1] op_sel:[1,0,0] op_sel_hi:[1,1,1]
	v_pk_fma_f32 v[2:3], v[186:187], v[34:35], v[2:3] op_sel:[1,0,0] op_sel_hi:[1,1,1]
	v_pk_fma_f32 v[4:5], v[186:187], v[36:37], v[4:5] op_sel:[1,0,0] op_sel_hi:[1,1,1]
	v_pk_fma_f32 v[6:7], v[186:187], v[38:39], v[6:7] op_sel:[1,0,0] op_sel_hi:[1,1,1]
	v_pk_fma_f32 v[8:9], v[186:187], v[40:41], v[8:9] op_sel:[1,0,0] op_sel_hi:[1,1,1]
	v_pk_fma_f32 v[10:11], v[186:187], v[42:43], v[10:11] op_sel:[1,0,0] op_sel_hi:[1,1,1]
	v_pk_fma_f32 v[12:13], v[186:187], v[44:45], v[12:13] op_sel:[1,0,0] op_sel_hi:[1,1,1]
	v_pk_fma_f32 v[14:15], v[186:187], v[46:47], v[14:15] op_sel:[1,0,0] op_sel_hi:[1,1,1]
	v_pk_fma_f32 v[16:17], v[186:187], v[48:49], v[16:17] op_sel:[1,0,0] op_sel_hi:[1,1,1]
	v_pk_fma_f32 v[18:19], v[186:187], v[50:51], v[18:19] op_sel:[1,0,0] op_sel_hi:[1,1,1]
	v_pk_fma_f32 v[20:21], v[186:187], v[52:53], v[20:21] op_sel:[1,0,0] op_sel_hi:[1,1,1]
	v_pk_fma_f32 v[22:23], v[186:187], v[54:55], v[22:23] op_sel:[1,0,0] op_sel_hi:[1,1,1]
	v_pk_fma_f32 v[24:25], v[186:187], v[56:57], v[24:25] op_sel:[1,0,0] op_sel_hi:[1,1,1]
	v_pk_fma_f32 v[26:27], v[186:187], v[58:59], v[26:27] op_sel:[1,0,0] op_sel_hi:[1,1,1]
	v_pk_fma_f32 v[28:29], v[186:187], v[60:61], v[28:29] op_sel:[1,0,0] op_sel_hi:[1,1,1]
	v_pk_fma_f32 v[30:31], v[186:187], v[62:63], v[30:31] op_sel:[1,0,0] op_sel_hi:[1,1,1]
	v_mad_u32_u24 v171, v171, s100, v199
	global_load_dwordx4 v[154:157], v171, s[4:5]
	global_load_dwordx2 v[158:159], v171, s[4:5] offset:16
	s_nop 1
	v_permlane32_swap_b32_e32 v0, v16
	v_permlane32_swap_b32_e32 v1, v17
	v_permlane32_swap_b32_e32 v2, v18
	v_permlane32_swap_b32_e32 v3, v19
	v_permlane32_swap_b32_e32 v4, v20
	v_permlane32_swap_b32_e32 v5, v21
	v_permlane32_swap_b32_e32 v6, v22
	v_permlane32_swap_b32_e32 v7, v23
	v_permlane32_swap_b32_e32 v8, v24
	v_permlane32_swap_b32_e32 v9, v25
	v_permlane32_swap_b32_e32 v10, v26
	v_permlane32_swap_b32_e32 v11, v27
	v_permlane32_swap_b32_e32 v12, v28
	v_permlane32_swap_b32_e32 v13, v29
	v_permlane32_swap_b32_e32 v14, v30
	v_permlane32_swap_b32_e32 v15, v31
	v_pk_add_f32 v[0:1], v[0:1], v[16:17]
	v_pk_add_f32 v[2:3], v[2:3], v[18:19]
	v_pk_add_f32 v[4:5], v[4:5], v[20:21]
	v_pk_add_f32 v[6:7], v[6:7], v[22:23]
	v_pk_add_f32 v[8:9], v[8:9], v[24:25]
	v_pk_add_f32 v[10:11], v[10:11], v[26:27]
	v_pk_add_f32 v[12:13], v[12:13], v[28:29]
	v_pk_add_f32 v[14:15], v[14:15], v[30:31]
	s_nop 1
	v_permlane16_swap_b32_e32 v0, v8
	v_permlane16_swap_b32_e32 v1, v9
	v_permlane16_swap_b32_e32 v2, v10
	v_permlane16_swap_b32_e32 v3, v11
	v_permlane16_swap_b32_e32 v4, v12
	v_permlane16_swap_b32_e32 v5, v13
	v_permlane16_swap_b32_e32 v6, v14
	v_permlane16_swap_b32_e32 v7, v15
	v_pk_add_f32 v[0:1], v[0:1], v[8:9]
	v_pk_add_f32 v[2:3], v[2:3], v[10:11]
	v_pk_add_f32 v[4:5], v[4:5], v[12:13]
	v_pk_add_f32 v[6:7], v[6:7], v[14:15]
	s_nop 1
	v_add_f32_dpp v0, v0, v0 row_ror:8 row_mask:0xf bank_mask:0x3
	v_add_f32_dpp v1, v1, v1 row_ror:8 row_mask:0xf bank_mask:0x3
	v_add_f32_dpp v2, v2, v2 row_ror:8 row_mask:0xf bank_mask:0x3
	v_add_f32_dpp v3, v3, v3 row_ror:8 row_mask:0xf bank_mask:0x3
	v_add_f32_dpp v0, v4, v4 row_ror:8 row_mask:0xf bank_mask:0xc
	v_add_f32_dpp v1, v5, v5 row_ror:8 row_mask:0xf bank_mask:0xc
	v_add_f32_dpp v2, v6, v6 row_ror:8 row_mask:0xf bank_mask:0xc
	v_add_f32_dpp v3, v7, v7 row_ror:8 row_mask:0xf bank_mask:0xc
	s_waitcnt vmcnt(32)
	v_pk_add_f32 v[192:193], v[192:193], v[0:1]
	v_pk_add_f32 v[194:195], v[194:195], v[2:3]
	global_store_dwordx4 v200, v[192:195], s[8:9]
	s_add_u32 s14, s14, 1
	s_and_b32 s14, s14, 63
	s_add_u32 s18, s14, 1
	s_and_b32 s98, s18, 63
	s_mov_b32 s100, s98
	s_and_b32 s19, s100, 15
	s_lshr_b32 s98, s100, 4
	s_lshl_b32 s99, s19, 9
	s_mul_i32 s15, s19, s16
	s_lshl_b32 s18, s98, 7
	s_add_u32 s15, s15, s18
	s_lshl_b32 s18, s101, 12
	s_add_u32 s15, s15, s18
	s_add_u32 s8, s24, s15
	s_addc_u32 s9, s25, 0
	s_mul_i32 s15, s98, 0x300000
	s_add_u32 s4, s26, 0x4800000
	s_addc_u32 s5, s27, 0
	s_add_u32 s4, s4, s15
	s_addc_u32 s5, s5, 0
	v_add_u32_e32 v201, s99, v197
	v_add_u32_e32 v203, s99, v198
	s_movk_i32 s100, 0xc0
	ds_read2_b32 v[160:161], v201 offset0:0 offset1:8
	ds_read2_b32 v[162:163], v201 offset0:16 offset1:24
	global_load_dwordx4 v[192:195], v200, s[10:11]
	ds_read2_b32 v[184:185], v204 offset0:32 offset1:40
	ds_read2_b32 v[186:187], v204 offset0:48 offset1:56
	s_waitcnt vmcnt(32)
	v_cvt_scalef32_pk32_f32_fp6 v[32:63], v[64:69], 1.0
	v_pk_mul_f32 v[0:1], v[176:177], v[32:33] op_sel_hi:[0,1]
	v_pk_mul_f32 v[2:3], v[176:177], v[34:35] op_sel_hi:[0,1]
	v_pk_mul_f32 v[4:5], v[176:177], v[36:37] op_sel_hi:[0,1]
	v_pk_mul_f32 v[6:7], v[176:177], v[38:39] op_sel_hi:[0,1]
	v_pk_mul_f32 v[8:9], v[176:177], v[40:41] op_sel_hi:[0,1]
	v_pk_mul_f32 v[10:11], v[176:177], v[42:43] op_sel_hi:[0,1]
	v_pk_mul_f32 v[12:13], v[176:177], v[44:45] op_sel_hi:[0,1]
	v_pk_mul_f32 v[14:15], v[176:177], v[46:47] op_sel_hi:[0,1]
	v_pk_mul_f32 v[16:17], v[176:177], v[48:49] op_sel_hi:[0,1]
	v_pk_mul_f32 v[18:19], v[176:177], v[50:51] op_sel_hi:[0,1]
	v_pk_mul_f32 v[20:21], v[176:177], v[52:53] op_sel_hi:[0,1]
	v_pk_mul_f32 v[22:23], v[176:177], v[54:55] op_sel_hi:[0,1]
	v_pk_mul_f32 v[24:25], v[176:177], v[56:57] op_sel_hi:[0,1]
	v_pk_mul_f32 v[26:27], v[176:177], v[58:59] op_sel_hi:[0,1]
	v_pk_mul_f32 v[28:29], v[176:177], v[60:61] op_sel_hi:[0,1]
	v_pk_mul_f32 v[30:31], v[176:177], v[62:63] op_sel_hi:[0,1]
	s_waitcnt lgkmcnt(0)
	v_mad_u32_u24 v160, v160, s100, v199
	global_load_dwordx4 v[64:67], v160, s[4:5]
	global_load_dwordx2 v[68:69], v160, s[4:5] offset:16
	s_waitcnt vmcnt(32)
	v_cvt_scalef32_pk32_f32_fp6 v[32:63], v[70:75], 1.0
	v_pk_fma_f32 v[0:1], v[176:177], v[32:33], v[0:1] op_sel:[1,0,0] op_sel_hi:[1,1,1]
	v_pk_fma_f32 v[2:3], v[176:177], v[34:35], v[2:3] op_sel:[1,0,0] op_sel_hi:[1,1,1]
	v_pk_fma_f32 v[4:5], v[176:177], v[36:37], v[4:5] op_sel:[1,0,0] op_sel_hi:[1,1,1]
	v_pk_fma_f32 v[6:7], v[176:177], v[38:39], v[6:7] op_sel:[1,0,0] op_sel_hi:[1,1,1]
	v_pk_fma_f32 v[8:9], v[176:177], v[40:41], v[8:9] op_sel:[1,0,0] op_sel_hi:[1,1,1]
	v_pk_fma_f32 v[10:11], v[176:177], v[42:43], v[10:11] op_sel:[1,0,0] op_sel_hi:[1,1,1]
	v_pk_fma_f32 v[12:13], v[176:177], v[44:45], v[12:13] op_sel:[1,0,0] op_sel_hi:[1,1,1]
	v_pk_fma_f32 v[14:15], v[176:177], v[46:47], v[14:15] op_sel:[1,0,0] op_sel_hi:[1,1,1]
	v_pk_fma_f32 v[16:17], v[176:177], v[48:49], v[16:17] op_sel:[1,0,0] op_sel_hi:[1,1,1]
	v_pk_fma_f32 v[18:19], v[176:177], v[50:51], v[18:19] op_sel:[1,0,0] op_sel_hi:[1,1,1]
	v_pk_fma_f32 v[20:21], v[176:177], v[52:53], v[20:21] op_sel:[1,0,0] op_sel_hi:[1,1,1]
	v_pk_fma_f32 v[22:23], v[176:177], v[54:55], v[22:23] op_sel:[1,0,0] op_sel_hi:[1,1,1]
	v_pk_fma_f32 v[24:25], v[176:177], v[56:57], v[24:25] op_sel:[1,0,0] op_sel_hi:[1,1,1]
	v_pk_fma_f32 v[26:27], v[176:177], v[58:59], v[26:27] op_sel:[1,0,0] op_sel_hi:[1,1,1]
	v_pk_fma_f32 v[28:29], v[176:177], v[60:61], v[28:29] op_sel:[1,0,0] op_sel_hi:[1,1,1]
	v_pk_fma_f32 v[30:31], v[176:177], v[62:63], v[30:31] op_sel:[1,0,0] op_sel_hi:[1,1,1]
	v_mad_u32_u24 v161, v161, s100, v199
	global_load_dwordx4 v[70:73], v161, s[4:5]
	global_load_dwordx2 v[74:75], v161, s[4:5] offset:16
	s_waitcnt vmcnt(32)
	v_cvt_scalef32_pk32_f32_fp6 v[32:63], v[76:81], 1.0
	v_pk_fma_f32 v[0:1], v[178:179], v[32:33], v[0:1] op_sel_hi:[0,1,1]
	v_pk_fma_f32 v[2:3], v[178:179], v[34:35], v[2:3] op_sel_hi:[0,1,1]
	v_pk_fma_f32 v[4:5], v[178:179], v[36:37], v[4:5] op_sel_hi:[0,1,1]
	v_pk_fma_f32 v[6:7], v[178:179], v[38:39], v[6:7] op_sel_hi:[0,1,1]
	v_pk_fma_f32 v[8:9], v[178:179], v[40:41], v[8:9] op_sel_hi:[0,1,1]
	v_pk_fma_f32 v[10:11], v[178:179], v[42:43], v[10:11] op_sel_hi:[0,1,1]
	v_pk_fma_f32 v[12:13], v[178:179], v[44:45], v[12:13] op_sel_hi:[0,1,1]
	v_pk_fma_f32 v[14:15], v[178:179], v[46:47], v[14:15] op_sel_hi:[0,1,1]
	v_pk_fma_f32 v[16:17], v[178:179], v[48:49], v[16:17] op_sel_hi:[0,1,1]
	v_pk_fma_f32 v[18:19], v[178:179], v[50:51], v[18:19] op_sel_hi:[0,1,1]
	v_pk_fma_f32 v[20:21], v[178:179], v[52:53], v[20:21] op_sel_hi:[0,1,1]
	v_pk_fma_f32 v[22:23], v[178:179], v[54:55], v[22:23] op_sel_hi:[0,1,1]
	v_pk_fma_f32 v[24:25], v[178:179], v[56:57], v[24:25] op_sel_hi:[0,1,1]
	v_pk_fma_f32 v[26:27], v[178:179], v[58:59], v[26:27] op_sel_hi:[0,1,1]
	v_pk_fma_f32 v[28:29], v[178:179], v[60:61], v[28:29] op_sel_hi:[0,1,1]
	v_pk_fma_f32 v[30:31], v[178:179], v[62:63], v[30:31] op_sel_hi:[0,1,1]
	v_mad_u32_u24 v162, v162, s100, v199
	global_load_dwordx4 v[76:79], v162, s[4:5]
	global_load_dwordx2 v[80:81], v162, s[4:5] offset:16
	s_waitcnt vmcnt(32)
	v_cvt_scalef32_pk32_f32_fp6 v[32:63], v[82:87], 1.0
	v_pk_fma_f32 v[0:1], v[178:179], v[32:33], v[0:1] op_sel:[1,0,0] op_sel_hi:[1,1,1]
	v_pk_fma_f32 v[2:3], v[178:179], v[34:35], v[2:3] op_sel:[1,0,0] op_sel_hi:[1,1,1]
	v_pk_fma_f32 v[4:5], v[178:179], v[36:37], v[4:5] op_sel:[1,0,0] op_sel_hi:[1,1,1]
	v_pk_fma_f32 v[6:7], v[178:179], v[38:39], v[6:7] op_sel:[1,0,0] op_sel_hi:[1,1,1]
	v_pk_fma_f32 v[8:9], v[178:179], v[40:41], v[8:9] op_sel:[1,0,0] op_sel_hi:[1,1,1]
	v_pk_fma_f32 v[10:11], v[178:179], v[42:43], v[10:11] op_sel:[1,0,0] op_sel_hi:[1,1,1]
	v_pk_fma_f32 v[12:13], v[178:179], v[44:45], v[12:13] op_sel:[1,0,0] op_sel_hi:[1,1,1]
	v_pk_fma_f32 v[14:15], v[178:179], v[46:47], v[14:15] op_sel:[1,0,0] op_sel_hi:[1,1,1]
	v_pk_fma_f32 v[16:17], v[178:179], v[48:49], v[16:17] op_sel:[1,0,0] op_sel_hi:[1,1,1]
	v_pk_fma_f32 v[18:19], v[178:179], v[50:51], v[18:19] op_sel:[1,0,0] op_sel_hi:[1,1,1]
	v_pk_fma_f32 v[20:21], v[178:179], v[52:53], v[20:21] op_sel:[1,0,0] op_sel_hi:[1,1,1]
	v_pk_fma_f32 v[22:23], v[178:179], v[54:55], v[22:23] op_sel:[1,0,0] op_sel_hi:[1,1,1]
	v_pk_fma_f32 v[24:25], v[178:179], v[56:57], v[24:25] op_sel:[1,0,0] op_sel_hi:[1,1,1]
	v_pk_fma_f32 v[26:27], v[178:179], v[58:59], v[26:27] op_sel:[1,0,0] op_sel_hi:[1,1,1]
	v_pk_fma_f32 v[28:29], v[178:179], v[60:61], v[28:29] op_sel:[1,0,0] op_sel_hi:[1,1,1]
	v_pk_fma_f32 v[30:31], v[178:179], v[62:63], v[30:31] op_sel:[1,0,0] op_sel_hi:[1,1,1]
	v_mad_u32_u24 v163, v163, s100, v199
	global_load_dwordx4 v[82:85], v163, s[4:5]
	global_load_dwordx2 v[86:87], v163, s[4:5] offset:16
	ds_read2_b32 v[168:169], v201 offset0:32 offset1:40
	ds_read2_b32 v[170:171], v201 offset0:48 offset1:56
	ds_read2_b32 v[176:177], v204 offset0:64 offset1:72
	ds_read2_b32 v[178:179], v204 offset0:80 offset1:88
	s_waitcnt vmcnt(32)
	v_cvt_scalef32_pk32_f32_fp6 v[32:63], v[88:93], 1.0
	v_pk_fma_f32 v[0:1], v[184:185], v[32:33], v[0:1] op_sel_hi:[0,1,1]
	v_pk_fma_f32 v[2:3], v[184:185], v[34:35], v[2:3] op_sel_hi:[0,1,1]
	v_pk_fma_f32 v[4:5], v[184:185], v[36:37], v[4:5] op_sel_hi:[0,1,1]
	v_pk_fma_f32 v[6:7], v[184:185], v[38:39], v[6:7] op_sel_hi:[0,1,1]
	v_pk_fma_f32 v[8:9], v[184:185], v[40:41], v[8:9] op_sel_hi:[0,1,1]
	v_pk_fma_f32 v[10:11], v[184:185], v[42:43], v[10:11] op_sel_hi:[0,1,1]
	v_pk_fma_f32 v[12:13], v[184:185], v[44:45], v[12:13] op_sel_hi:[0,1,1]
	v_pk_fma_f32 v[14:15], v[184:185], v[46:47], v[14:15] op_sel_hi:[0,1,1]
	v_pk_fma_f32 v[16:17], v[184:185], v[48:49], v[16:17] op_sel_hi:[0,1,1]
	v_pk_fma_f32 v[18:19], v[184:185], v[50:51], v[18:19] op_sel_hi:[0,1,1]
	v_pk_fma_f32 v[20:21], v[184:185], v[52:53], v[20:21] op_sel_hi:[0,1,1]
	v_pk_fma_f32 v[22:23], v[184:185], v[54:55], v[22:23] op_sel_hi:[0,1,1]
	v_pk_fma_f32 v[24:25], v[184:185], v[56:57], v[24:25] op_sel_hi:[0,1,1]
	v_pk_fma_f32 v[26:27], v[184:185], v[58:59], v[26:27] op_sel_hi:[0,1,1]
	v_pk_fma_f32 v[28:29], v[184:185], v[60:61], v[28:29] op_sel_hi:[0,1,1]
	v_pk_fma_f32 v[30:31], v[184:185], v[62:63], v[30:31] op_sel_hi:[0,1,1]
	s_waitcnt lgkmcnt(0)
	v_mad_u32_u24 v168, v168, s100, v199
	global_load_dwordx4 v[88:91], v168, s[4:5]
	global_load_dwordx2 v[92:93], v168, s[4:5] offset:16
	s_waitcnt vmcnt(32)
	v_cvt_scalef32_pk32_f32_fp6 v[32:63], v[94:99], 1.0
	v_pk_fma_f32 v[0:1], v[184:185], v[32:33], v[0:1] op_sel:[1,0,0] op_sel_hi:[1,1,1]
	v_pk_fma_f32 v[2:3], v[184:185], v[34:35], v[2:3] op_sel:[1,0,0] op_sel_hi:[1,1,1]
	v_pk_fma_f32 v[4:5], v[184:185], v[36:37], v[4:5] op_sel:[1,0,0] op_sel_hi:[1,1,1]
	v_pk_fma_f32 v[6:7], v[184:185], v[38:39], v[6:7] op_sel:[1,0,0] op_sel_hi:[1,1,1]
	v_pk_fma_f32 v[8:9], v[184:185], v[40:41], v[8:9] op_sel:[1,0,0] op_sel_hi:[1,1,1]
	v_pk_fma_f32 v[10:11], v[184:185], v[42:43], v[10:11] op_sel:[1,0,0] op_sel_hi:[1,1,1]
	v_pk_fma_f32 v[12:13], v[184:185], v[44:45], v[12:13] op_sel:[1,0,0] op_sel_hi:[1,1,1]
	v_pk_fma_f32 v[14:15], v[184:185], v[46:47], v[14:15] op_sel:[1,0,0] op_sel_hi:[1,1,1]
	v_pk_fma_f32 v[16:17], v[184:185], v[48:49], v[16:17] op_sel:[1,0,0] op_sel_hi:[1,1,1]
	v_pk_fma_f32 v[18:19], v[184:185], v[50:51], v[18:19] op_sel:[1,0,0] op_sel_hi:[1,1,1]
	v_pk_fma_f32 v[20:21], v[184:185], v[52:53], v[20:21] op_sel:[1,0,0] op_sel_hi:[1,1,1]
	v_pk_fma_f32 v[22:23], v[184:185], v[54:55], v[22:23] op_sel:[1,0,0] op_sel_hi:[1,1,1]
	v_pk_fma_f32 v[24:25], v[184:185], v[56:57], v[24:25] op_sel:[1,0,0] op_sel_hi:[1,1,1]
	v_pk_fma_f32 v[26:27], v[184:185], v[58:59], v[26:27] op_sel:[1,0,0] op_sel_hi:[1,1,1]
	v_pk_fma_f32 v[28:29], v[184:185], v[60:61], v[28:29] op_sel:[1,0,0] op_sel_hi:[1,1,1]
	v_pk_fma_f32 v[30:31], v[184:185], v[62:63], v[30:31] op_sel:[1,0,0] op_sel_hi:[1,1,1]
	v_mad_u32_u24 v169, v169, s100, v199
	global_load_dwordx4 v[94:97], v169, s[4:5]
	global_load_dwordx2 v[98:99], v169, s[4:5] offset:16
	s_waitcnt vmcnt(32)
	v_cvt_scalef32_pk32_f32_fp6 v[32:63], v[100:105], 1.0
	v_pk_fma_f32 v[0:1], v[186:187], v[32:33], v[0:1] op_sel_hi:[0,1,1]
	v_pk_fma_f32 v[2:3], v[186:187], v[34:35], v[2:3] op_sel_hi:[0,1,1]
	v_pk_fma_f32 v[4:5], v[186:187], v[36:37], v[4:5] op_sel_hi:[0,1,1]
	v_pk_fma_f32 v[6:7], v[186:187], v[38:39], v[6:7] op_sel_hi:[0,1,1]
	v_pk_fma_f32 v[8:9], v[186:187], v[40:41], v[8:9] op_sel_hi:[0,1,1]
	v_pk_fma_f32 v[10:11], v[186:187], v[42:43], v[10:11] op_sel_hi:[0,1,1]
	v_pk_fma_f32 v[12:13], v[186:187], v[44:45], v[12:13] op_sel_hi:[0,1,1]
	v_pk_fma_f32 v[14:15], v[186:187], v[46:47], v[14:15] op_sel_hi:[0,1,1]
	v_pk_fma_f32 v[16:17], v[186:187], v[48:49], v[16:17] op_sel_hi:[0,1,1]
	v_pk_fma_f32 v[18:19], v[186:187], v[50:51], v[18:19] op_sel_hi:[0,1,1]
	v_pk_fma_f32 v[20:21], v[186:187], v[52:53], v[20:21] op_sel_hi:[0,1,1]
	v_pk_fma_f32 v[22:23], v[186:187], v[54:55], v[22:23] op_sel_hi:[0,1,1]
	v_pk_fma_f32 v[24:25], v[186:187], v[56:57], v[24:25] op_sel_hi:[0,1,1]
	v_pk_fma_f32 v[26:27], v[186:187], v[58:59], v[26:27] op_sel_hi:[0,1,1]
	v_pk_fma_f32 v[28:29], v[186:187], v[60:61], v[28:29] op_sel_hi:[0,1,1]
	v_pk_fma_f32 v[30:31], v[186:187], v[62:63], v[30:31] op_sel_hi:[0,1,1]
	v_mad_u32_u24 v170, v170, s100, v199
	global_load_dwordx4 v[100:103], v170, s[4:5]
	global_load_dwordx2 v[104:105], v170, s[4:5] offset:16
	s_waitcnt vmcnt(32)
	v_cvt_scalef32_pk32_f32_fp6 v[32:63], v[106:111], 1.0
	v_pk_fma_f32 v[0:1], v[186:187], v[32:33], v[0:1] op_sel:[1,0,0] op_sel_hi:[1,1,1]
	v_pk_fma_f32 v[2:3], v[186:187], v[34:35], v[2:3] op_sel:[1,0,0] op_sel_hi:[1,1,1]
	v_pk_fma_f32 v[4:5], v[186:187], v[36:37], v[4:5] op_sel:[1,0,0] op_sel_hi:[1,1,1]
	v_pk_fma_f32 v[6:7], v[186:187], v[38:39], v[6:7] op_sel:[1,0,0] op_sel_hi:[1,1,1]
	v_pk_fma_f32 v[8:9], v[186:187], v[40:41], v[8:9] op_sel:[1,0,0] op_sel_hi:[1,1,1]
	v_pk_fma_f32 v[10:11], v[186:187], v[42:43], v[10:11] op_sel:[1,0,0] op_sel_hi:[1,1,1]
	v_pk_fma_f32 v[12:13], v[186:187], v[44:45], v[12:13] op_sel:[1,0,0] op_sel_hi:[1,1,1]
	v_pk_fma_f32 v[14:15], v[186:187], v[46:47], v[14:15] op_sel:[1,0,0] op_sel_hi:[1,1,1]
	v_pk_fma_f32 v[16:17], v[186:187], v[48:49], v[16:17] op_sel:[1,0,0] op_sel_hi:[1,1,1]
	v_pk_fma_f32 v[18:19], v[186:187], v[50:51], v[18:19] op_sel:[1,0,0] op_sel_hi:[1,1,1]
	v_pk_fma_f32 v[20:21], v[186:187], v[52:53], v[20:21] op_sel:[1,0,0] op_sel_hi:[1,1,1]
	v_pk_fma_f32 v[22:23], v[186:187], v[54:55], v[22:23] op_sel:[1,0,0] op_sel_hi:[1,1,1]
	v_pk_fma_f32 v[24:25], v[186:187], v[56:57], v[24:25] op_sel:[1,0,0] op_sel_hi:[1,1,1]
	v_pk_fma_f32 v[26:27], v[186:187], v[58:59], v[26:27] op_sel:[1,0,0] op_sel_hi:[1,1,1]
	v_pk_fma_f32 v[28:29], v[186:187], v[60:61], v[28:29] op_sel:[1,0,0] op_sel_hi:[1,1,1]
	v_pk_fma_f32 v[30:31], v[186:187], v[62:63], v[30:31] op_sel:[1,0,0] op_sel_hi:[1,1,1]
	v_mad_u32_u24 v171, v171, s100, v199
	global_load_dwordx4 v[106:109], v171, s[4:5]
	global_load_dwordx2 v[110:111], v171, s[4:5] offset:16
	ds_read2_b32 v[160:161], v201 offset0:64 offset1:72
	ds_read2_b32 v[162:163], v201 offset0:80 offset1:88
	ds_read2_b32 v[184:185], v204 offset0:96 offset1:104
	ds_read2_b32 v[186:187], v204 offset0:112 offset1:120
	s_waitcnt vmcnt(32)
	v_cvt_scalef32_pk32_f32_fp6 v[32:63], v[112:117], 1.0
	v_pk_fma_f32 v[0:1], v[176:177], v[32:33], v[0:1] op_sel_hi:[0,1,1]
	v_pk_fma_f32 v[2:3], v[176:177], v[34:35], v[2:3] op_sel_hi:[0,1,1]
	v_pk_fma_f32 v[4:5], v[176:177], v[36:37], v[4:5] op_sel_hi:[0,1,1]
	v_pk_fma_f32 v[6:7], v[176:177], v[38:39], v[6:7] op_sel_hi:[0,1,1]
	v_pk_fma_f32 v[8:9], v[176:177], v[40:41], v[8:9] op_sel_hi:[0,1,1]
	v_pk_fma_f32 v[10:11], v[176:177], v[42:43], v[10:11] op_sel_hi:[0,1,1]
	v_pk_fma_f32 v[12:13], v[176:177], v[44:45], v[12:13] op_sel_hi:[0,1,1]
	v_pk_fma_f32 v[14:15], v[176:177], v[46:47], v[14:15] op_sel_hi:[0,1,1]
	v_pk_fma_f32 v[16:17], v[176:177], v[48:49], v[16:17] op_sel_hi:[0,1,1]
	v_pk_fma_f32 v[18:19], v[176:177], v[50:51], v[18:19] op_sel_hi:[0,1,1]
	v_pk_fma_f32 v[20:21], v[176:177], v[52:53], v[20:21] op_sel_hi:[0,1,1]
	v_pk_fma_f32 v[22:23], v[176:177], v[54:55], v[22:23] op_sel_hi:[0,1,1]
	v_pk_fma_f32 v[24:25], v[176:177], v[56:57], v[24:25] op_sel_hi:[0,1,1]
	v_pk_fma_f32 v[26:27], v[176:177], v[58:59], v[26:27] op_sel_hi:[0,1,1]
	v_pk_fma_f32 v[28:29], v[176:177], v[60:61], v[28:29] op_sel_hi:[0,1,1]
	v_pk_fma_f32 v[30:31], v[176:177], v[62:63], v[30:31] op_sel_hi:[0,1,1]
	s_waitcnt lgkmcnt(0)
	v_mad_u32_u24 v160, v160, s100, v199
	global_load_dwordx4 v[112:115], v160, s[4:5]
	global_load_dwordx2 v[116:117], v160, s[4:5] offset:16
	s_waitcnt vmcnt(32)
	v_cvt_scalef32_pk32_f32_fp6 v[32:63], v[118:123], 1.0
	v_pk_fma_f32 v[0:1], v[176:177], v[32:33], v[0:1] op_sel:[1,0,0] op_sel_hi:[1,1,1]
	v_pk_fma_f32 v[2:3], v[176:177], v[34:35], v[2:3] op_sel:[1,0,0] op_sel_hi:[1,1,1]
	v_pk_fma_f32 v[4:5], v[176:177], v[36:37], v[4:5] op_sel:[1,0,0] op_sel_hi:[1,1,1]
	v_pk_fma_f32 v[6:7], v[176:177], v[38:39], v[6:7] op_sel:[1,0,0] op_sel_hi:[1,1,1]
	v_pk_fma_f32 v[8:9], v[176:177], v[40:41], v[8:9] op_sel:[1,0,0] op_sel_hi:[1,1,1]
	v_pk_fma_f32 v[10:11], v[176:177], v[42:43], v[10:11] op_sel:[1,0,0] op_sel_hi:[1,1,1]
	v_pk_fma_f32 v[12:13], v[176:177], v[44:45], v[12:13] op_sel:[1,0,0] op_sel_hi:[1,1,1]
	v_pk_fma_f32 v[14:15], v[176:177], v[46:47], v[14:15] op_sel:[1,0,0] op_sel_hi:[1,1,1]
	v_pk_fma_f32 v[16:17], v[176:177], v[48:49], v[16:17] op_sel:[1,0,0] op_sel_hi:[1,1,1]
	v_pk_fma_f32 v[18:19], v[176:177], v[50:51], v[18:19] op_sel:[1,0,0] op_sel_hi:[1,1,1]
	v_pk_fma_f32 v[20:21], v[176:177], v[52:53], v[20:21] op_sel:[1,0,0] op_sel_hi:[1,1,1]
	v_pk_fma_f32 v[22:23], v[176:177], v[54:55], v[22:23] op_sel:[1,0,0] op_sel_hi:[1,1,1]
	v_pk_fma_f32 v[24:25], v[176:177], v[56:57], v[24:25] op_sel:[1,0,0] op_sel_hi:[1,1,1]
	v_pk_fma_f32 v[26:27], v[176:177], v[58:59], v[26:27] op_sel:[1,0,0] op_sel_hi:[1,1,1]
	v_pk_fma_f32 v[28:29], v[176:177], v[60:61], v[28:29] op_sel:[1,0,0] op_sel_hi:[1,1,1]
	v_pk_fma_f32 v[30:31], v[176:177], v[62:63], v[30:31] op_sel:[1,0,0] op_sel_hi:[1,1,1]
	v_mad_u32_u24 v161, v161, s100, v199
	global_load_dwordx4 v[118:121], v161, s[4:5]
	global_load_dwordx2 v[122:123], v161, s[4:5] offset:16
	s_waitcnt vmcnt(32)
	v_cvt_scalef32_pk32_f32_fp6 v[32:63], v[124:129], 1.0
	v_pk_fma_f32 v[0:1], v[178:179], v[32:33], v[0:1] op_sel_hi:[0,1,1]
	v_pk_fma_f32 v[2:3], v[178:179], v[34:35], v[2:3] op_sel_hi:[0,1,1]
	v_pk_fma_f32 v[4:5], v[178:179], v[36:37], v[4:5] op_sel_hi:[0,1,1]
	v_pk_fma_f32 v[6:7], v[178:179], v[38:39], v[6:7] op_sel_hi:[0,1,1]
	v_pk_fma_f32 v[8:9], v[178:179], v[40:41], v[8:9] op_sel_hi:[0,1,1]
	v_pk_fma_f32 v[10:11], v[178:179], v[42:43], v[10:11] op_sel_hi:[0,1,1]
	v_pk_fma_f32 v[12:13], v[178:179], v[44:45], v[12:13] op_sel_hi:[0,1,1]
	v_pk_fma_f32 v[14:15], v[178:179], v[46:47], v[14:15] op_sel_hi:[0,1,1]
	v_pk_fma_f32 v[16:17], v[178:179], v[48:49], v[16:17] op_sel_hi:[0,1,1]
	v_pk_fma_f32 v[18:19], v[178:179], v[50:51], v[18:19] op_sel_hi:[0,1,1]
	v_pk_fma_f32 v[20:21], v[178:179], v[52:53], v[20:21] op_sel_hi:[0,1,1]
	v_pk_fma_f32 v[22:23], v[178:179], v[54:55], v[22:23] op_sel_hi:[0,1,1]
	v_pk_fma_f32 v[24:25], v[178:179], v[56:57], v[24:25] op_sel_hi:[0,1,1]
	v_pk_fma_f32 v[26:27], v[178:179], v[58:59], v[26:27] op_sel_hi:[0,1,1]
	v_pk_fma_f32 v[28:29], v[178:179], v[60:61], v[28:29] op_sel_hi:[0,1,1]
	v_pk_fma_f32 v[30:31], v[178:179], v[62:63], v[30:31] op_sel_hi:[0,1,1]
	v_mad_u32_u24 v162, v162, s100, v199
	global_load_dwordx4 v[124:127], v162, s[4:5]
	global_load_dwordx2 v[128:129], v162, s[4:5] offset:16
	s_waitcnt vmcnt(32)
	v_cvt_scalef32_pk32_f32_fp6 v[32:63], v[130:135], 1.0
	v_pk_fma_f32 v[0:1], v[178:179], v[32:33], v[0:1] op_sel:[1,0,0] op_sel_hi:[1,1,1]
	v_pk_fma_f32 v[2:3], v[178:179], v[34:35], v[2:3] op_sel:[1,0,0] op_sel_hi:[1,1,1]
	v_pk_fma_f32 v[4:5], v[178:179], v[36:37], v[4:5] op_sel:[1,0,0] op_sel_hi:[1,1,1]
	v_pk_fma_f32 v[6:7], v[178:179], v[38:39], v[6:7] op_sel:[1,0,0] op_sel_hi:[1,1,1]
	v_pk_fma_f32 v[8:9], v[178:179], v[40:41], v[8:9] op_sel:[1,0,0] op_sel_hi:[1,1,1]
	v_pk_fma_f32 v[10:11], v[178:179], v[42:43], v[10:11] op_sel:[1,0,0] op_sel_hi:[1,1,1]
	v_pk_fma_f32 v[12:13], v[178:179], v[44:45], v[12:13] op_sel:[1,0,0] op_sel_hi:[1,1,1]
	v_pk_fma_f32 v[14:15], v[178:179], v[46:47], v[14:15] op_sel:[1,0,0] op_sel_hi:[1,1,1]
	v_pk_fma_f32 v[16:17], v[178:179], v[48:49], v[16:17] op_sel:[1,0,0] op_sel_hi:[1,1,1]
	v_pk_fma_f32 v[18:19], v[178:179], v[50:51], v[18:19] op_sel:[1,0,0] op_sel_hi:[1,1,1]
	v_pk_fma_f32 v[20:21], v[178:179], v[52:53], v[20:21] op_sel:[1,0,0] op_sel_hi:[1,1,1]
	v_pk_fma_f32 v[22:23], v[178:179], v[54:55], v[22:23] op_sel:[1,0,0] op_sel_hi:[1,1,1]
	v_pk_fma_f32 v[24:25], v[178:179], v[56:57], v[24:25] op_sel:[1,0,0] op_sel_hi:[1,1,1]
	v_pk_fma_f32 v[26:27], v[178:179], v[58:59], v[26:27] op_sel:[1,0,0] op_sel_hi:[1,1,1]
	v_pk_fma_f32 v[28:29], v[178:179], v[60:61], v[28:29] op_sel:[1,0,0] op_sel_hi:[1,1,1]
	v_pk_fma_f32 v[30:31], v[178:179], v[62:63], v[30:31] op_sel:[1,0,0] op_sel_hi:[1,1,1]
	v_mad_u32_u24 v163, v163, s100, v199
	global_load_dwordx4 v[130:133], v163, s[4:5]
	global_load_dwordx2 v[134:135], v163, s[4:5] offset:16
	ds_read2_b32 v[168:169], v201 offset0:96 offset1:104
	ds_read2_b32 v[170:171], v201 offset0:112 offset1:120
	ds_read2_b32 v[176:177], v203 offset0:0 offset1:8
	ds_read2_b32 v[178:179], v203 offset0:16 offset1:24
	s_waitcnt vmcnt(32)
	v_cvt_scalef32_pk32_f32_fp6 v[32:63], v[136:141], 1.0
	v_pk_fma_f32 v[0:1], v[184:185], v[32:33], v[0:1] op_sel_hi:[0,1,1]
	v_pk_fma_f32 v[2:3], v[184:185], v[34:35], v[2:3] op_sel_hi:[0,1,1]
	v_pk_fma_f32 v[4:5], v[184:185], v[36:37], v[4:5] op_sel_hi:[0,1,1]
	v_pk_fma_f32 v[6:7], v[184:185], v[38:39], v[6:7] op_sel_hi:[0,1,1]
	v_pk_fma_f32 v[8:9], v[184:185], v[40:41], v[8:9] op_sel_hi:[0,1,1]
	v_pk_fma_f32 v[10:11], v[184:185], v[42:43], v[10:11] op_sel_hi:[0,1,1]
	v_pk_fma_f32 v[12:13], v[184:185], v[44:45], v[12:13] op_sel_hi:[0,1,1]
	v_pk_fma_f32 v[14:15], v[184:185], v[46:47], v[14:15] op_sel_hi:[0,1,1]
	v_pk_fma_f32 v[16:17], v[184:185], v[48:49], v[16:17] op_sel_hi:[0,1,1]
	v_pk_fma_f32 v[18:19], v[184:185], v[50:51], v[18:19] op_sel_hi:[0,1,1]
	v_pk_fma_f32 v[20:21], v[184:185], v[52:53], v[20:21] op_sel_hi:[0,1,1]
	v_pk_fma_f32 v[22:23], v[184:185], v[54:55], v[22:23] op_sel_hi:[0,1,1]
	v_pk_fma_f32 v[24:25], v[184:185], v[56:57], v[24:25] op_sel_hi:[0,1,1]
	v_pk_fma_f32 v[26:27], v[184:185], v[58:59], v[26:27] op_sel_hi:[0,1,1]
	v_pk_fma_f32 v[28:29], v[184:185], v[60:61], v[28:29] op_sel_hi:[0,1,1]
	v_pk_fma_f32 v[30:31], v[184:185], v[62:63], v[30:31] op_sel_hi:[0,1,1]
	s_waitcnt lgkmcnt(0)
	v_mad_u32_u24 v168, v168, s100, v199
	global_load_dwordx4 v[136:139], v168, s[4:5]
	global_load_dwordx2 v[140:141], v168, s[4:5] offset:16
	s_waitcnt vmcnt(32)
	v_cvt_scalef32_pk32_f32_fp6 v[32:63], v[142:147], 1.0
	v_pk_fma_f32 v[0:1], v[184:185], v[32:33], v[0:1] op_sel:[1,0,0] op_sel_hi:[1,1,1]
	v_pk_fma_f32 v[2:3], v[184:185], v[34:35], v[2:3] op_sel:[1,0,0] op_sel_hi:[1,1,1]
	v_pk_fma_f32 v[4:5], v[184:185], v[36:37], v[4:5] op_sel:[1,0,0] op_sel_hi:[1,1,1]
	v_pk_fma_f32 v[6:7], v[184:185], v[38:39], v[6:7] op_sel:[1,0,0] op_sel_hi:[1,1,1]
	v_pk_fma_f32 v[8:9], v[184:185], v[40:41], v[8:9] op_sel:[1,0,0] op_sel_hi:[1,1,1]
	v_pk_fma_f32 v[10:11], v[184:185], v[42:43], v[10:11] op_sel:[1,0,0] op_sel_hi:[1,1,1]
	v_pk_fma_f32 v[12:13], v[184:185], v[44:45], v[12:13] op_sel:[1,0,0] op_sel_hi:[1,1,1]
	v_pk_fma_f32 v[14:15], v[184:185], v[46:47], v[14:15] op_sel:[1,0,0] op_sel_hi:[1,1,1]
	v_pk_fma_f32 v[16:17], v[184:185], v[48:49], v[16:17] op_sel:[1,0,0] op_sel_hi:[1,1,1]
	v_pk_fma_f32 v[18:19], v[184:185], v[50:51], v[18:19] op_sel:[1,0,0] op_sel_hi:[1,1,1]
	v_pk_fma_f32 v[20:21], v[184:185], v[52:53], v[20:21] op_sel:[1,0,0] op_sel_hi:[1,1,1]
	v_pk_fma_f32 v[22:23], v[184:185], v[54:55], v[22:23] op_sel:[1,0,0] op_sel_hi:[1,1,1]
	v_pk_fma_f32 v[24:25], v[184:185], v[56:57], v[24:25] op_sel:[1,0,0] op_sel_hi:[1,1,1]
	v_pk_fma_f32 v[26:27], v[184:185], v[58:59], v[26:27] op_sel:[1,0,0] op_sel_hi:[1,1,1]
	v_pk_fma_f32 v[28:29], v[184:185], v[60:61], v[28:29] op_sel:[1,0,0] op_sel_hi:[1,1,1]
	v_pk_fma_f32 v[30:31], v[184:185], v[62:63], v[30:31] op_sel:[1,0,0] op_sel_hi:[1,1,1]
	v_mad_u32_u24 v169, v169, s100, v199
	global_load_dwordx4 v[142:145], v169, s[4:5]
	global_load_dwordx2 v[146:147], v169, s[4:5] offset:16
	s_waitcnt vmcnt(32)
	v_cvt_scalef32_pk32_f32_fp6 v[32:63], v[148:153], 1.0
	v_pk_fma_f32 v[0:1], v[186:187], v[32:33], v[0:1] op_sel_hi:[0,1,1]
	v_pk_fma_f32 v[2:3], v[186:187], v[34:35], v[2:3] op_sel_hi:[0,1,1]
	v_pk_fma_f32 v[4:5], v[186:187], v[36:37], v[4:5] op_sel_hi:[0,1,1]
	v_pk_fma_f32 v[6:7], v[186:187], v[38:39], v[6:7] op_sel_hi:[0,1,1]
	v_pk_fma_f32 v[8:9], v[186:187], v[40:41], v[8:9] op_sel_hi:[0,1,1]
	v_pk_fma_f32 v[10:11], v[186:187], v[42:43], v[10:11] op_sel_hi:[0,1,1]
	v_pk_fma_f32 v[12:13], v[186:187], v[44:45], v[12:13] op_sel_hi:[0,1,1]
	v_pk_fma_f32 v[14:15], v[186:187], v[46:47], v[14:15] op_sel_hi:[0,1,1]
	v_pk_fma_f32 v[16:17], v[186:187], v[48:49], v[16:17] op_sel_hi:[0,1,1]
	v_pk_fma_f32 v[18:19], v[186:187], v[50:51], v[18:19] op_sel_hi:[0,1,1]
	v_pk_fma_f32 v[20:21], v[186:187], v[52:53], v[20:21] op_sel_hi:[0,1,1]
	v_pk_fma_f32 v[22:23], v[186:187], v[54:55], v[22:23] op_sel_hi:[0,1,1]
	v_pk_fma_f32 v[24:25], v[186:187], v[56:57], v[24:25] op_sel_hi:[0,1,1]
	v_pk_fma_f32 v[26:27], v[186:187], v[58:59], v[26:27] op_sel_hi:[0,1,1]
	v_pk_fma_f32 v[28:29], v[186:187], v[60:61], v[28:29] op_sel_hi:[0,1,1]
	v_pk_fma_f32 v[30:31], v[186:187], v[62:63], v[30:31] op_sel_hi:[0,1,1]
	v_mad_u32_u24 v170, v170, s100, v199
	global_load_dwordx4 v[148:151], v170, s[4:5]
	global_load_dwordx2 v[152:153], v170, s[4:5] offset:16
	s_waitcnt vmcnt(32)
	v_cvt_scalef32_pk32_f32_fp6 v[32:63], v[154:159], 1.0
	v_pk_fma_f32 v[0:1], v[186:187], v[32:33], v[0:1] op_sel:[1,0,0] op_sel_hi:[1,1,1]
	v_pk_fma_f32 v[2:3], v[186:187], v[34:35], v[2:3] op_sel:[1,0,0] op_sel_hi:[1,1,1]
	v_pk_fma_f32 v[4:5], v[186:187], v[36:37], v[4:5] op_sel:[1,0,0] op_sel_hi:[1,1,1]
	v_pk_fma_f32 v[6:7], v[186:187], v[38:39], v[6:7] op_sel:[1,0,0] op_sel_hi:[1,1,1]
	v_pk_fma_f32 v[8:9], v[186:187], v[40:41], v[8:9] op_sel:[1,0,0] op_sel_hi:[1,1,1]
	v_pk_fma_f32 v[10:11], v[186:187], v[42:43], v[10:11] op_sel:[1,0,0] op_sel_hi:[1,1,1]
	v_pk_fma_f32 v[12:13], v[186:187], v[44:45], v[12:13] op_sel:[1,0,0] op_sel_hi:[1,1,1]
	v_pk_fma_f32 v[14:15], v[186:187], v[46:47], v[14:15] op_sel:[1,0,0] op_sel_hi:[1,1,1]
	v_pk_fma_f32 v[16:17], v[186:187], v[48:49], v[16:17] op_sel:[1,0,0] op_sel_hi:[1,1,1]
	v_pk_fma_f32 v[18:19], v[186:187], v[50:51], v[18:19] op_sel:[1,0,0] op_sel_hi:[1,1,1]
	v_pk_fma_f32 v[20:21], v[186:187], v[52:53], v[20:21] op_sel:[1,0,0] op_sel_hi:[1,1,1]
	v_pk_fma_f32 v[22:23], v[186:187], v[54:55], v[22:23] op_sel:[1,0,0] op_sel_hi:[1,1,1]
	v_pk_fma_f32 v[24:25], v[186:187], v[56:57], v[24:25] op_sel:[1,0,0] op_sel_hi:[1,1,1]
	v_pk_fma_f32 v[26:27], v[186:187], v[58:59], v[26:27] op_sel:[1,0,0] op_sel_hi:[1,1,1]
	v_pk_fma_f32 v[28:29], v[186:187], v[60:61], v[28:29] op_sel:[1,0,0] op_sel_hi:[1,1,1]
	v_pk_fma_f32 v[30:31], v[186:187], v[62:63], v[30:31] op_sel:[1,0,0] op_sel_hi:[1,1,1]
	v_mad_u32_u24 v171, v171, s100, v199
	global_load_dwordx4 v[154:157], v171, s[4:5]
	global_load_dwordx2 v[158:159], v171, s[4:5] offset:16
	s_nop 1
	v_permlane32_swap_b32_e32 v0, v16
	v_permlane32_swap_b32_e32 v1, v17
	v_permlane32_swap_b32_e32 v2, v18
	v_permlane32_swap_b32_e32 v3, v19
	v_permlane32_swap_b32_e32 v4, v20
	v_permlane32_swap_b32_e32 v5, v21
	v_permlane32_swap_b32_e32 v6, v22
	v_permlane32_swap_b32_e32 v7, v23
	v_permlane32_swap_b32_e32 v8, v24
	v_permlane32_swap_b32_e32 v9, v25
	v_permlane32_swap_b32_e32 v10, v26
	v_permlane32_swap_b32_e32 v11, v27
	v_permlane32_swap_b32_e32 v12, v28
	v_permlane32_swap_b32_e32 v13, v29
	v_permlane32_swap_b32_e32 v14, v30
	v_permlane32_swap_b32_e32 v15, v31
	v_pk_add_f32 v[0:1], v[0:1], v[16:17]
	v_pk_add_f32 v[2:3], v[2:3], v[18:19]
	v_pk_add_f32 v[4:5], v[4:5], v[20:21]
	v_pk_add_f32 v[6:7], v[6:7], v[22:23]
	v_pk_add_f32 v[8:9], v[8:9], v[24:25]
	v_pk_add_f32 v[10:11], v[10:11], v[26:27]
	v_pk_add_f32 v[12:13], v[12:13], v[28:29]
	v_pk_add_f32 v[14:15], v[14:15], v[30:31]
	s_nop 1
	v_permlane16_swap_b32_e32 v0, v8
	v_permlane16_swap_b32_e32 v1, v9
	v_permlane16_swap_b32_e32 v2, v10
	v_permlane16_swap_b32_e32 v3, v11
	v_permlane16_swap_b32_e32 v4, v12
	v_permlane16_swap_b32_e32 v5, v13
	v_permlane16_swap_b32_e32 v6, v14
	v_permlane16_swap_b32_e32 v7, v15
	v_pk_add_f32 v[0:1], v[0:1], v[8:9]
	v_pk_add_f32 v[2:3], v[2:3], v[10:11]
	v_pk_add_f32 v[4:5], v[4:5], v[12:13]
	v_pk_add_f32 v[6:7], v[6:7], v[14:15]
	s_nop 1
	v_add_f32_dpp v0, v0, v0 row_ror:8 row_mask:0xf bank_mask:0x3
	v_add_f32_dpp v1, v1, v1 row_ror:8 row_mask:0xf bank_mask:0x3
	v_add_f32_dpp v2, v2, v2 row_ror:8 row_mask:0xf bank_mask:0x3
	v_add_f32_dpp v3, v3, v3 row_ror:8 row_mask:0xf bank_mask:0x3
	v_add_f32_dpp v0, v4, v4 row_ror:8 row_mask:0xf bank_mask:0xc
	v_add_f32_dpp v1, v5, v5 row_ror:8 row_mask:0xf bank_mask:0xc
	v_add_f32_dpp v2, v6, v6 row_ror:8 row_mask:0xf bank_mask:0xc
	v_add_f32_dpp v3, v7, v7 row_ror:8 row_mask:0xf bank_mask:0xc
	s_waitcnt vmcnt(32)
	v_pk_add_f32 v[192:193], v[192:193], v[0:1]
	v_pk_add_f32 v[194:195], v[194:195], v[2:3]
	global_store_dwordx4 v200, v[192:195], s[10:11]
	s_add_u32 s14, s14, 1
	s_and_b32 s14, s14, 63
	s_add_u32 s18, s14, 1
	s_and_b32 s98, s18, 63
	s_mov_b32 s100, s98
	s_and_b32 s19, s100, 15
	s_lshr_b32 s98, s100, 4
	s_lshl_b32 s99, s19, 9
	s_mul_i32 s15, s19, s16
	s_lshl_b32 s18, s98, 7
	s_add_u32 s15, s15, s18
	s_lshl_b32 s18, s101, 12
	s_add_u32 s15, s15, s18
	s_add_u32 s10, s24, s15
	s_addc_u32 s11, s25, 0
	s_mul_i32 s15, s98, 0x300000
	s_add_u32 s4, s26, 0x4800000
	s_addc_u32 s5, s27, 0
	s_add_u32 s4, s4, s15
	s_addc_u32 s5, s5, 0
	v_add_u32_e32 v202, s99, v197
	v_add_u32_e32 v204, s99, v198
	s_movk_i32 s100, 0xc0
	ds_read2_b32 v[160:161], v202 offset0:0 offset1:8
	ds_read2_b32 v[162:163], v202 offset0:16 offset1:24
	s_cmp_lg_u32 s14, 0
	s_cbranch_scc1 .Lgv1_loop
	s_waitcnt vmcnt(0) lgkmcnt(0)
	s_lshl_b32 s15, s92, 6
	s_add_u32 s101, s101, s15
	s_cmpk_lt_u32 s101, 0x8000
	s_cbranch_scc1 .Lgv1_chunk
	s_branch .LBB0_1104
